# v31: v30 + residual-epilogue row sum-of-squares reduction via v_permlane16/32_swap instead of ds_bpermute round trips
# baseline (speedup 1.0000x reference)
; DI unsigned cvt_pk(float lo, float hi) { unsigned r; asm("v_cvt_pk_bf16_f32 %0, %1, %2" : "=v"(r) : "v"(lo), "v"(hi)); return r; }
;     __device__ __forceinline__ void operator()(const f32x4 (&acc)[2][2][4][2], const Unit& u, int wr, int wc, int fr, int fq) const {
;     ...
;                 for (int mm = 0; mm < 2; ++mm) {
;                     const int m = mp * 2 + mm;
;                     const int row = row0 + ai * HALF + m * 16;
;                     float s = 0.f;
; #pragma unroll
;                     for (int bj = 0; bj < 2; ++bj) {
;                         u32x4* px = (u32x4*)(X + (size_t)row * DM + col0 + bj * HALF);
;                         float xo[8]; unpack8(xin[mm][bj], xo);
;                         const f32x4 a0 = acc[ai][bj][m][0] + pv[mm][bj][0], a1 = acc[ai][bj][m][1] + pv[mm][bj][1];
;                         u32x4 w;
;                         w.x = cvt_pk(xo[0] + scale * a0[0], xo[1] + scale * a0[1]); w.y = cvt_pk(xo[2] + scale * a0[2], xo[3] + scale * a0[3]);
;                         w.z = cvt_pk(xo[4] + scale * a1[0], xo[5] + scale * a1[1]); w.w = cvt_pk(xo[6] + scale * a1[2], xo[7] + scale * a1[3]);
;                         *px = w;
;                         float xn[8]; unpack8(w, xn);
; #pragma unroll
;                         for (int j = 0; j < 8; ++j) s += xn[j] * xn[j];
;                     }
;                     s += __shfl_xor(s, 16); s += __shfl_xor(s, 32);
;                     if (fq == 0) unsafeAtomicAdd(ssn + row, s);
.LBB0_405:
	s_or_b64 exec, exec, s[12:13]
	s_waitcnt vmcnt(0)
	v_lshlrev_b32_e32 v210, 16, v140
	v_and_b32_e32 v211, 0xffff0000, v140
	v_lshlrev_b32_e32 v214, 16, v141
	v_and_b32_e32 v215, 0xffff0000, v141
	v_and_b32_e32 v238, 0xffff0000, v142
	v_pk_add_f32 v[140:141], v[124:125], v[206:207]
	v_pk_add_f32 v[202:203], v[120:121], v[202:203]
	v_lshlrev_b32_e32 v237, 16, v142
	v_fmac_f32_e32 v210, 0.5, v140
	v_fmac_f32_e32 v211, 0.5, v141
	v_cvt_pk_bf16_f32 v140, v210, v211
	v_fmac_f32_e32 v238, 0.5, v203
	v_and_b32_e32 v203, 0xffff0000, v140
	v_lshlrev_b32_e32 v244, 16, v143
	v_and_b32_e32 v245, 0xffff0000, v143
	v_pk_add_f32 v[142:143], v[126:127], v[208:209]
	v_pk_add_f32 v[204:205], v[122:123], v[204:205]
	v_fmac_f32_e32 v237, 0.5, v202
	v_lshlrev_b32_e32 v202, 16, v140
	v_mul_f32_e32 v203, v203, v203
	v_fmac_f32_e32 v214, 0.5, v142
	v_fmac_f32_e32 v215, 0.5, v143
	v_cvt_pk_bf16_f32 v141, v214, v215
	v_fmac_f32_e32 v244, 0.5, v204
	v_lshlrev_b32_e32 v204, 16, v141
	v_fmac_f32_e32 v203, v202, v202
	v_fmac_f32_e32 v245, 0.5, v205
	v_and_b32_e32 v205, 0xffff0000, v141
	v_fmac_f32_e32 v203, v204, v204
	v_cvt_pk_bf16_f32 v142, v237, v238
	v_fmac_f32_e32 v203, v205, v205
	v_lshlrev_b32_e32 v206, 16, v142
	v_and_b32_e32 v207, 0xffff0000, v142
	v_fmac_f32_e32 v203, v206, v206
	v_cvt_pk_bf16_f32 v143, v244, v245
	v_fmac_f32_e32 v203, v207, v207
	v_lshlrev_b32_e32 v208, 16, v143
	v_and_b32_e32 v209, 0xffff0000, v143
	v_fmac_f32_e32 v203, v208, v208
	v_fmac_f32_e32 v203, v209, v209
	v_lshlrev_b32_e32 v202, 16, v136
	v_and_b32_e32 v204, 0xffff0000, v136
	v_lshlrev_b32_e32 v205, 16, v137
	v_and_b32_e32 v206, 0xffff0000, v137
	v_lshlrev_b32_e32 v207, 16, v138
	v_and_b32_e32 v208, 0xffff0000, v138
	v_lshlrev_b32_e32 v209, 16, v139
	v_and_b32_e32 v210, 0xffff0000, v139
	v_pk_add_f32 v[136:137], v[94:95], v[200:201]
	v_pk_add_f32 v[138:139], v[92:93], v[198:199]
	v_pk_add_f32 v[198:199], v[90:91], v[196:197]
	v_pk_add_f32 v[196:197], v[88:89], v[194:195]
	v_fmac_f32_e32 v202, 0.5, v138
	v_fmac_f32_e32 v204, 0.5, v139
	v_cvt_pk_bf16_f32 v194, v202, v204
	v_fmac_f32_e32 v205, 0.5, v136
	v_lshlrev_b32_e32 v136, 16, v194
	v_fmac_f32_e32 v206, 0.5, v137
	v_and_b32_e32 v137, 0xffff0000, v194
	v_fmac_f32_e32 v203, v136, v136
	v_cvt_pk_bf16_f32 v195, v205, v206
	v_fmac_f32_e32 v203, v137, v137
	v_lshlrev_b32_e32 v138, 16, v195
	v_and_b32_e32 v139, 0xffff0000, v195
	v_fmac_f32_e32 v203, v138, v138
	v_fmac_f32_e32 v207, 0.5, v196
	v_fmac_f32_e32 v208, 0.5, v197
	v_cvt_pk_bf16_f32 v196, v207, v208
	v_fmac_f32_e32 v209, 0.5, v198
	v_lshlrev_b32_e32 v198, 16, v196
	v_fmac_f32_e32 v203, v139, v139
	v_and_b32_e32 v137, 64, v221
	v_fmac_f32_e32 v210, 0.5, v199
	v_and_b32_e32 v199, 0xffff0000, v196
	v_fmac_f32_e32 v203, v198, v198
	v_xor_b32_e32 v136, 16, v221
	v_add_u32_e32 v137, 64, v137
	v_cvt_pk_bf16_f32 v197, v209, v210
	v_fmac_f32_e32 v203, v199, v199
	v_lshlrev_b32_e32 v200, 16, v197
	v_cmp_lt_i32_e64 s[12:13], v136, v137
	v_and_b32_e32 v201, 0xffff0000, v197
	v_fmac_f32_e32 v203, v200, v200
	v_cndmask_b32_e64 v136, v221, v136, s[12:13]
	v_fmac_f32_e32 v203, v201, v201
	v_lshlrev_b32_e32 v237, 2, v136
	v_mov_b32_e32 v136, v203
	s_nop 1
	v_permlane16_swap_b32_e32 v136, v203
	v_xor_b32_e32 v138, 32, v221
	v_cmp_lt_i32_e64 s[12:13], v138, v137
	s_waitcnt lgkmcnt(0)
	v_add_f32_e32 v136, v203, v136
	v_cndmask_b32_e64 v137, v221, v138, s[12:13]
	v_lshlrev_b32_e32 v238, 2, v137
	v_mov_b32_e32 v137, v136
	s_nop 1
	v_permlane32_swap_b32_e32 v137, v136
	v_lshl_add_u64 v[138:139], s[28:29], 0, v[174:175]
	v_lshl_add_u64 v[138:139], v[168:169], 1, v[138:139]
	global_store_dwordx4 v[138:139], v[140:143], off
	global_store_dwordx4 v[138:139], v[194:197], off offset:256
	s_and_saveexec_b64 s[12:13], s[8:9]
	s_cbranch_execz .LBB0_407
	s_waitcnt lgkmcnt(0)
	v_add_f32_e32 v138, v136, v137
	v_lshl_add_u64 v[136:137], v[166:167], 2, s[6:7]
	global_atomic_add_f32 v[136:137], v138, off
; DI unsigned cvt_pk(float lo, float hi) { unsigned r; asm("v_cvt_pk_bf16_f32 %0, %1, %2" : "=v"(r) : "v"(lo), "v"(hi)); return r; }
;     __device__ __forceinline__ void operator()(const f32x4 (&acc)[2][2][4][2], const Unit& u, int wr, int wc, int fr, int fq) const {
;     ...
;                 for (int mm = 0; mm < 2; ++mm) {
;                     const int m = mp * 2 + mm;
;                     const int row = row0 + ai * HALF + m * 16;
;                     float s = 0.f;
; #pragma unroll
;                     for (int bj = 0; bj < 2; ++bj) {
;                         u32x4* px = (u32x4*)(X + (size_t)row * DM + col0 + bj * HALF);
;                         float xo[8]; unpack8(xin[mm][bj], xo);
;                         const f32x4 a0 = acc[ai][bj][m][0] + pv[mm][bj][0], a1 = acc[ai][bj][m][1] + pv[mm][bj][1];
;                         u32x4 w;
;                         w.x = cvt_pk(xo[0] + scale * a0[0], xo[1] + scale * a0[1]); w.y = cvt_pk(xo[2] + scale * a0[2], xo[3] + scale * a0[3]);
;                         w.z = cvt_pk(xo[4] + scale * a1[0], xo[5] + scale * a1[1]); w.w = cvt_pk(xo[6] + scale * a1[2], xo[7] + scale * a1[3]);
;                         *px = w;
;                         float xn[8]; unpack8(w, xn);
; #pragma unroll
;                         for (int j = 0; j < 8; ++j) s += xn[j] * xn[j];
;                     }
;                     s += __shfl_xor(s, 16); s += __shfl_xor(s, 32);
;                     if (fq == 0) unsafeAtomicAdd(ssn + row, s);
.LBB0_407:
	s_or_b64 exec, exec, s[12:13]
	v_lshlrev_b32_e32 v140, 16, v132
	v_and_b32_e32 v141, 0xffff0000, v132
	v_lshlrev_b32_e32 v142, 16, v133
	v_and_b32_e32 v143, 0xffff0000, v133
	v_and_b32_e32 v197, 0xffff0000, v135
	v_pk_add_f32 v[132:133], v[116:117], v[190:191]
	s_waitcnt lgkmcnt(0)
	v_pk_add_f32 v[136:137], v[114:115], v[188:189]
	v_lshlrev_b32_e32 v196, 16, v135
	v_fmac_f32_e32 v140, 0.5, v132
	v_fmac_f32_e32 v141, 0.5, v133
	v_cvt_pk_bf16_f32 v132, v140, v141
	v_fmac_f32_e32 v197, 0.5, v137
	v_and_b32_e32 v137, 0xffff0000, v132
	v_lshlrev_b32_e32 v194, 16, v134
	v_and_b32_e32 v195, 0xffff0000, v134
	v_pk_add_f32 v[134:135], v[118:119], v[192:193]
	v_pk_add_f32 v[138:139], v[112:113], v[186:187]
	v_fmac_f32_e32 v196, 0.5, v136
	v_lshlrev_b32_e32 v136, 16, v132
	v_mul_f32_e32 v186, v137, v137
	v_fmac_f32_e32 v142, 0.5, v134
	v_fmac_f32_e32 v143, 0.5, v135
	v_cvt_pk_bf16_f32 v133, v142, v143
	v_fmac_f32_e32 v194, 0.5, v138
	v_lshlrev_b32_e32 v138, 16, v133
	v_fmac_f32_e32 v186, v136, v136
	v_fmac_f32_e32 v195, 0.5, v139
	v_and_b32_e32 v139, 0xffff0000, v133
	v_fmac_f32_e32 v186, v138, v138
	v_cvt_pk_bf16_f32 v134, v194, v195
	v_fmac_f32_e32 v186, v139, v139
	v_lshlrev_b32_e32 v140, 16, v134
	v_and_b32_e32 v141, 0xffff0000, v134
	v_fmac_f32_e32 v186, v140, v140
	v_cvt_pk_bf16_f32 v135, v196, v197
	v_fmac_f32_e32 v186, v141, v141
	v_lshlrev_b32_e32 v142, 16, v135
	v_and_b32_e32 v143, 0xffff0000, v135
	v_fmac_f32_e32 v186, v142, v142
	v_lshlrev_b32_e32 v136, 16, v128
	v_lshlrev_b32_e32 v187, 16, v130
	v_and_b32_e32 v188, 0xffff0000, v130
	v_lshlrev_b32_e32 v189, 16, v131
	v_and_b32_e32 v190, 0xffff0000, v131
	v_pk_add_f32 v[130:131], v[84:85], v[182:183]
	v_fmac_f32_e32 v186, v143, v143
	v_and_b32_e32 v137, 0xffff0000, v128
	v_lshlrev_b32_e32 v142, 16, v129
	v_and_b32_e32 v143, 0xffff0000, v129
	v_pk_add_f32 v[128:129], v[86:87], v[184:185]
	v_fmac_f32_e32 v136, 0.5, v130
	v_fmac_f32_e32 v137, 0.5, v131
	v_cvt_pk_bf16_f32 v136, v136, v137
	v_fmac_f32_e32 v142, 0.5, v128
	v_lshlrev_b32_e32 v128, 16, v136
	v_fmac_f32_e32 v143, 0.5, v129
	v_and_b32_e32 v129, 0xffff0000, v136
	v_fmac_f32_e32 v186, v128, v128
	v_cvt_pk_bf16_f32 v137, v142, v143
	v_fmac_f32_e32 v186, v129, v129
	v_lshlrev_b32_e32 v130, 16, v137
	v_pk_add_f32 v[140:141], v[82:83], v[180:181]
	v_pk_add_f32 v[138:139], v[80:81], v[178:179]
	v_and_b32_e32 v131, 0xffff0000, v137
	v_fmac_f32_e32 v186, v130, v130
	v_fmac_f32_e32 v187, 0.5, v138
	v_fmac_f32_e32 v188, 0.5, v139
	v_cvt_pk_bf16_f32 v138, v187, v188
	v_fmac_f32_e32 v189, 0.5, v140
	v_lshlrev_b32_e32 v140, 16, v138
	v_fmac_f32_e32 v186, v131, v131
	v_fmac_f32_e32 v190, 0.5, v141
	v_and_b32_e32 v141, 0xffff0000, v138
	v_fmac_f32_e32 v186, v140, v140
	v_cvt_pk_bf16_f32 v139, v189, v190
	v_fmac_f32_e32 v186, v141, v141
	v_lshlrev_b32_e32 v142, 16, v139
	v_and_b32_e32 v143, 0xffff0000, v139
	v_fmac_f32_e32 v186, v142, v142
	v_fmac_f32_e32 v186, v143, v143
	v_mov_b32_e32 v128, v186
	s_nop 1
	v_permlane16_swap_b32_e32 v128, v186
	v_lshl_add_u64 v[130:131], s[28:29], 0, v[176:177]
	v_lshl_add_u64 v[130:131], v[168:169], 1, v[130:131]
	global_store_dwordx4 v[130:131], v[132:135], off
	global_store_dwordx4 v[130:131], v[136:139], off offset:256
	s_waitcnt lgkmcnt(0)
	v_add_f32_e32 v128, v186, v128
	v_mov_b32_e32 v129, v128
	s_nop 1
	v_permlane32_swap_b32_e32 v129, v128
	s_and_saveexec_b64 s[12:13], s[8:9]
	s_cbranch_execz .LBB0_409
	s_waitcnt lgkmcnt(0)
	v_add_f32_e32 v130, v128, v129
	v_lshl_add_u64 v[128:129], v[166:167], 2, s[6:7]
	global_atomic_add_f32 v[128:129], v130, off offset:64

;     __device__ __forceinline__ void operator()(const f32x4 (&acc)[2][2][4][2], const Unit& u, int wr, int wc, int fr, int fq) const {
;     ...
;                 u32x4 xin[2][2];
; #pragma unroll
;                 for (int mm = 0; mm < 2; ++mm)
; #pragma unroll
;                     for (int bj = 0; bj < 2; ++bj) xin[mm][bj] = *(const u32x4*)(X + (size_t)(row0 + ai * HALF + (mp * 2 + mm) * 16) * DM + col0 + bj * HALF);
;                 f32x4 pv[2][2][2];
; #pragma unroll
;                 for (int mm = 0; mm < 2; ++mm)
; #pragma unroll
;                     for (int bj = 0; bj < 2; ++bj)
; #pragma unroll
;                         for (int n = 0; n < 2; ++n) pv[mm][bj][n] = (f32x4){0.f, 0.f, 0.f, 0.f};
;                 if (src) {
;                     u32x4 pc[2][2];
;     ...
;                     asm volatile("global_load_dwordx4 %0, %4, off sc1\n\tglobal_load_dwordx4 %1, %5, off sc1\n\tglobal_load_dwordx4 %2, %6, off sc1\n\tglobal_load_dwordx4 %3, %7, off sc1\n\ts_waitcnt vmcnt(0)"
;                                  : "=&v"(pc[0][0]), "=&v"(pc[0][1]), "=&v"(pc[1][0]), "=&v"(pc[1][1])
;                                  : "v"(src + CI(0, 0)), "v"(src + CI(0, 1)), "v"(src + CI(1, 0)), "v"(src + CI(1, 1))
;                                  : "memory");
;     ...
; #pragma unroll
;                     for (int mm = 0; mm < 2; ++mm)
; #pragma unroll
;                         for (int bj = 0; bj < 2; ++bj) { float f[8]; unpack8(pc[mm][bj], f); pv[mm][bj][0] = (f32x4){f[0], f[1], f[2], f[3]}; pv[mm][bj][1] = (f32x4){f[4], f[5], f[6], f[7]}; }
;                 }
; #pragma unroll
;                 for (int mm = 0; mm < 2; ++mm) {
;                     const int m = mp * 2 + mm;
;                     const int row = row0 + ai * HALF + m * 16;
;                     float s = 0.f;
; #pragma unroll
;                     for (int bj = 0; bj < 2; ++bj) {
;                         u32x4* px = (u32x4*)(X + (size_t)row * DM + col0 + bj * HALF);
;                         float xo[8]; unpack8(xin[mm][bj], xo);
;                         const f32x4 a0 = acc[ai][bj][m][0] + pv[mm][bj][0], a1 = acc[ai][bj][m][1] + pv[mm][bj][1];
;                         u32x4 w;
;                         w.x = cvt_pk(xo[0] + scale * a0[0], xo[1] + scale * a0[1]); w.y = cvt_pk(xo[2] + scale * a0[2], xo[3] + scale * a0[3]);
.LBB0_411:
	s_or_b64 exec, exec, s[12:13]
	s_waitcnt vmcnt(0)
	s_mov_b64 s[30:31], 0x40000
	v_lshl_add_u64 v[250:251], v[174:175], 0, s[30:31]
	v_lshl_add_u64 v[250:251], v[172:173], 0, v[250:251]
	global_load_dwordx4 v[80:83], v[250:251], off
	global_load_dwordx4 v[84:87], v[250:251], off offset:256
	s_mov_b64 s[30:31], 0x48000
	v_lshl_add_u64 v[252:253], v[174:175], 0, s[30:31]
	v_lshl_add_u64 v[252:253], v[172:173], 0, v[252:253]
	global_load_dwordx4 v[88:91], v[252:253], off
	global_load_dwordx4 v[92:95], v[252:253], off offset:256
	s_and_saveexec_b64 s[12:13], vcc
	s_mov_b64 s[30:31], 0x2000
	v_lshl_add_u64 v[250:251], v[170:171], 0, s[30:31]
	global_load_dwordx4 v[112:115], v[250:251], off sc1
	s_mov_b64 s[30:31], 0x3000
	v_lshl_add_u64 v[252:253], v[170:171], 0, s[30:31]
	global_load_dwordx4 v[116:119], v[252:253], off sc1
	s_mov_b64 s[30:31], 0x2400
	v_lshl_add_u64 v[250:251], v[170:171], 0, s[30:31]
	global_load_dwordx4 v[120:123], v[250:251], off sc1
	s_mov_b64 s[30:31], 0x3400
	v_lshl_add_u64 v[252:253], v[170:171], 0, s[30:31]
	global_load_dwordx4 v[124:127], v[252:253], off sc1
	s_or_b64 exec, exec, s[12:13]
	v_lshlrev_b32_e32 v214, 16, v140
	v_and_b32_e32 v215, 0xffff0000, v140
	v_lshlrev_b32_e32 v244, 16, v141
	v_and_b32_e32 v245, 0xffff0000, v141
	v_and_b32_e32 v247, 0xffff0000, v142
	v_pk_add_f32 v[140:141], v[108:109], v[208:209]
	v_pk_add_f32 v[204:205], v[104:105], v[204:205]
	v_lshlrev_b32_e32 v246, 16, v142
	v_fmac_f32_e32 v214, 0.5, v140
	v_fmac_f32_e32 v215, 0.5, v141
	v_cvt_pk_bf16_f32 v140, v214, v215
	v_fmac_f32_e32 v247, 0.5, v205
	v_and_b32_e32 v205, 0xffff0000, v140
	v_lshlrev_b32_e32 v248, 16, v143
	v_and_b32_e32 v249, 0xffff0000, v143
	v_pk_add_f32 v[142:143], v[110:111], v[210:211]
	v_pk_add_f32 v[206:207], v[106:107], v[206:207]
	v_fmac_f32_e32 v246, 0.5, v204
	v_lshlrev_b32_e32 v204, 16, v140
	v_mul_f32_e32 v205, v205, v205
	v_fmac_f32_e32 v244, 0.5, v142
	v_fmac_f32_e32 v245, 0.5, v143
	v_cvt_pk_bf16_f32 v141, v244, v245
	v_fmac_f32_e32 v248, 0.5, v206
	v_lshlrev_b32_e32 v206, 16, v141
	v_fmac_f32_e32 v205, v204, v204
	v_fmac_f32_e32 v249, 0.5, v207
	v_and_b32_e32 v207, 0xffff0000, v141
	v_fmac_f32_e32 v205, v206, v206
	v_cvt_pk_bf16_f32 v142, v246, v247
	v_fmac_f32_e32 v205, v207, v207
	v_lshlrev_b32_e32 v208, 16, v142
	v_and_b32_e32 v209, 0xffff0000, v142
	v_fmac_f32_e32 v205, v208, v208
	v_cvt_pk_bf16_f32 v143, v248, v249
	v_fmac_f32_e32 v205, v209, v209
	v_lshlrev_b32_e32 v210, 16, v143
	v_and_b32_e32 v211, 0xffff0000, v143
	v_fmac_f32_e32 v205, v210, v210
	v_fmac_f32_e32 v205, v211, v211
	v_lshlrev_b32_e32 v204, 16, v136
	v_and_b32_e32 v206, 0xffff0000, v136
	v_lshlrev_b32_e32 v207, 16, v137
	v_and_b32_e32 v208, 0xffff0000, v137
	v_lshlrev_b32_e32 v209, 16, v138
	v_and_b32_e32 v210, 0xffff0000, v138
	v_lshlrev_b32_e32 v211, 16, v139
	v_and_b32_e32 v214, 0xffff0000, v139
	v_pk_add_f32 v[136:137], v[78:79], v[202:203]
	v_pk_add_f32 v[138:139], v[76:77], v[200:201]
	v_pk_add_f32 v[200:201], v[74:75], v[198:199]
	v_pk_add_f32 v[198:199], v[72:73], v[196:197]
	v_fmac_f32_e32 v204, 0.5, v138
	v_fmac_f32_e32 v206, 0.5, v139
	v_cvt_pk_bf16_f32 v196, v204, v206
	v_fmac_f32_e32 v207, 0.5, v136
	v_lshlrev_b32_e32 v136, 16, v196
	v_fmac_f32_e32 v208, 0.5, v137
	v_and_b32_e32 v137, 0xffff0000, v196
	v_fmac_f32_e32 v205, v136, v136
	v_cvt_pk_bf16_f32 v197, v207, v208
	v_fmac_f32_e32 v205, v137, v137
	v_lshlrev_b32_e32 v138, 16, v197
	v_and_b32_e32 v139, 0xffff0000, v197
	v_fmac_f32_e32 v205, v138, v138
	v_fmac_f32_e32 v209, 0.5, v198
	v_fmac_f32_e32 v210, 0.5, v199
	v_cvt_pk_bf16_f32 v198, v209, v210
	v_fmac_f32_e32 v211, 0.5, v200
	v_lshlrev_b32_e32 v200, 16, v198
	v_fmac_f32_e32 v205, v139, v139
	v_fmac_f32_e32 v214, 0.5, v201
	v_and_b32_e32 v201, 0xffff0000, v198
	v_fmac_f32_e32 v205, v200, v200
	v_cvt_pk_bf16_f32 v199, v211, v214
	v_fmac_f32_e32 v205, v201, v201
	v_lshlrev_b32_e32 v202, 16, v199
	v_and_b32_e32 v203, 0xffff0000, v199
	v_fmac_f32_e32 v205, v202, v202
	v_fmac_f32_e32 v205, v203, v203
	v_mov_b32_e32 v136, v205
	s_nop 1
	v_permlane16_swap_b32_e32 v136, v205
	v_lshl_add_u64 v[138:139], s[28:29], 0, v[186:187]
	v_lshl_add_u64 v[138:139], v[168:169], 1, v[138:139]
	global_store_dwordx4 v[138:139], v[140:143], off
	global_store_dwordx4 v[138:139], v[196:199], off offset:256
	s_waitcnt lgkmcnt(0)
	v_add_f32_e32 v136, v205, v136
	v_mov_b32_e32 v137, v136
	s_nop 1
	v_permlane32_swap_b32_e32 v137, v136
	s_and_saveexec_b64 s[12:13], s[8:9]
	s_cbranch_execz .LBB0_413
	s_waitcnt lgkmcnt(0)
	v_add_f32_e32 v138, v136, v137
	v_lshl_add_u64 v[136:137], v[166:167], 2, s[6:7]
	global_atomic_add_f32 v[136:137], v138, off offset:128
; DI unsigned cvt_pk(float lo, float hi) { unsigned r; asm("v_cvt_pk_bf16_f32 %0, %1, %2" : "=v"(r) : "v"(lo), "v"(hi)); return r; }
;     __device__ __forceinline__ void operator()(const f32x4 (&acc)[2][2][4][2], const Unit& u, int wr, int wc, int fr, int fq) const {
;     ...
;                 for (int mm = 0; mm < 2; ++mm) {
;                     const int m = mp * 2 + mm;
;                     const int row = row0 + ai * HALF + m * 16;
;                     float s = 0.f;
; #pragma unroll
;                     for (int bj = 0; bj < 2; ++bj) {
;                         u32x4* px = (u32x4*)(X + (size_t)row * DM + col0 + bj * HALF);
;                         float xo[8]; unpack8(xin[mm][bj], xo);
;                         const f32x4 a0 = acc[ai][bj][m][0] + pv[mm][bj][0], a1 = acc[ai][bj][m][1] + pv[mm][bj][1];
;                         u32x4 w;
;                         w.x = cvt_pk(xo[0] + scale * a0[0], xo[1] + scale * a0[1]); w.y = cvt_pk(xo[2] + scale * a0[2], xo[3] + scale * a0[3]);
;                         w.z = cvt_pk(xo[4] + scale * a1[0], xo[5] + scale * a1[1]); w.w = cvt_pk(xo[6] + scale * a1[2], xo[7] + scale * a1[3]);
;                         *px = w;
;                         float xn[8]; unpack8(w, xn);
; #pragma unroll
;                         for (int j = 0; j < 8; ++j) s += xn[j] * xn[j];
;                     }
;                     s += __shfl_xor(s, 16); s += __shfl_xor(s, 32);
;                     if (fq == 0) unsafeAtomicAdd(ssn + row, s);
.LBB0_413:
	s_or_b64 exec, exec, s[12:13]
	v_lshlrev_b32_e32 v140, 16, v132
	v_and_b32_e32 v141, 0xffff0000, v132
	v_lshlrev_b32_e32 v142, 16, v133
	v_and_b32_e32 v143, 0xffff0000, v133
	v_lshlrev_b32_e32 v186, 16, v134
	v_and_b32_e32 v197, 0xffff0000, v135
	v_pk_add_f32 v[132:133], v[100:101], v[192:193]
	s_waitcnt lgkmcnt(0)
	v_pk_add_f32 v[136:137], v[98:99], v[190:191]
	v_pk_add_f32 v[138:139], v[96:97], v[188:189]
	v_and_b32_e32 v187, 0xffff0000, v134
	v_lshlrev_b32_e32 v196, 16, v135
	v_pk_add_f32 v[134:135], v[102:103], v[194:195]
	v_fmac_f32_e32 v140, 0.5, v132
	v_fmac_f32_e32 v141, 0.5, v133
	v_cvt_pk_bf16_f32 v132, v140, v141
	v_fmac_f32_e32 v186, 0.5, v138
	v_fmac_f32_e32 v197, 0.5, v137
	v_and_b32_e32 v137, 0xffff0000, v132
	v_fmac_f32_e32 v142, 0.5, v134
	v_fmac_f32_e32 v187, 0.5, v139
	v_cvt_pk_bf16_f32 v134, v186, v187
	v_fmac_f32_e32 v196, 0.5, v136
	v_lshlrev_b32_e32 v136, 16, v132
	v_mul_f32_e32 v186, v137, v137
	v_fmac_f32_e32 v143, 0.5, v135
	v_cvt_pk_bf16_f32 v133, v142, v143
	v_fmac_f32_e32 v186, v136, v136
	v_lshlrev_b32_e32 v138, 16, v133
	v_and_b32_e32 v139, 0xffff0000, v133
	v_fmac_f32_e32 v186, v138, v138
	v_lshlrev_b32_e32 v140, 16, v134
	v_fmac_f32_e32 v186, v139, v139
	v_and_b32_e32 v141, 0xffff0000, v134
	v_fmac_f32_e32 v186, v140, v140
	v_cvt_pk_bf16_f32 v135, v196, v197
	v_fmac_f32_e32 v186, v141, v141
	v_lshlrev_b32_e32 v142, 16, v135
	v_and_b32_e32 v143, 0xffff0000, v135
	v_fmac_f32_e32 v186, v142, v142
	v_lshlrev_b32_e32 v136, 16, v128
	v_lshlrev_b32_e32 v187, 16, v130
	v_and_b32_e32 v188, 0xffff0000, v130
	v_lshlrev_b32_e32 v189, 16, v131
	v_and_b32_e32 v190, 0xffff0000, v131
	v_pk_add_f32 v[130:131], v[68:69], v[182:183]
	v_fmac_f32_e32 v186, v143, v143
	v_and_b32_e32 v137, 0xffff0000, v128
	v_lshlrev_b32_e32 v142, 16, v129
	v_and_b32_e32 v143, 0xffff0000, v129
	v_pk_add_f32 v[128:129], v[70:71], v[184:185]
	v_fmac_f32_e32 v136, 0.5, v130
	v_fmac_f32_e32 v137, 0.5, v131
	v_cvt_pk_bf16_f32 v136, v136, v137
	v_fmac_f32_e32 v142, 0.5, v128
	v_lshlrev_b32_e32 v128, 16, v136
	v_fmac_f32_e32 v143, 0.5, v129
	v_and_b32_e32 v129, 0xffff0000, v136
	v_fmac_f32_e32 v186, v128, v128
	v_cvt_pk_bf16_f32 v137, v142, v143
	v_fmac_f32_e32 v186, v129, v129
	v_lshlrev_b32_e32 v130, 16, v137
	v_pk_add_f32 v[140:141], v[66:67], v[180:181]
	v_pk_add_f32 v[138:139], v[64:65], v[178:179]
	v_and_b32_e32 v131, 0xffff0000, v137
	v_fmac_f32_e32 v186, v130, v130
	v_fmac_f32_e32 v187, 0.5, v138
	v_fmac_f32_e32 v188, 0.5, v139
	v_cvt_pk_bf16_f32 v138, v187, v188
	v_fmac_f32_e32 v189, 0.5, v140
	v_lshlrev_b32_e32 v140, 16, v138
	v_fmac_f32_e32 v186, v131, v131
	v_fmac_f32_e32 v190, 0.5, v141
	v_and_b32_e32 v141, 0xffff0000, v138
	v_fmac_f32_e32 v186, v140, v140
	v_cvt_pk_bf16_f32 v139, v189, v190
	v_fmac_f32_e32 v186, v141, v141
	v_lshlrev_b32_e32 v142, 16, v139
	v_and_b32_e32 v143, 0xffff0000, v139
	v_fmac_f32_e32 v186, v142, v142
	v_fmac_f32_e32 v186, v143, v143
	v_mov_b32_e32 v128, v186
	s_nop 1
	v_permlane16_swap_b32_e32 v128, v186
	v_lshl_add_u64 v[130:131], s[28:29], 0, v[176:177]
	v_lshl_add_u64 v[130:131], v[168:169], 1, v[130:131]
	global_store_dwordx4 v[130:131], v[132:135], off
	global_store_dwordx4 v[130:131], v[136:139], off offset:256
	s_waitcnt lgkmcnt(0)
	v_add_f32_e32 v128, v186, v128
	v_mov_b32_e32 v129, v128
	s_nop 1
	v_permlane32_swap_b32_e32 v129, v128
	s_and_saveexec_b64 s[12:13], s[8:9]
	s_cbranch_execz .LBB0_415
	s_waitcnt lgkmcnt(0)
	v_add_f32_e32 v130, v128, v129
	v_lshl_add_u64 v[128:129], v[166:167], 2, s[6:7]
	global_atomic_add_f32 v[128:129], v130, off offset:192

;     __device__ __forceinline__ void operator()(const f32x4 (&acc)[2][2][4][2], const Unit& u, int wr, int wc, int fr, int fq) const {
;     ...
;                 u32x4 xin[2][2];
; #pragma unroll
;                 for (int mm = 0; mm < 2; ++mm)
; #pragma unroll
;                     for (int bj = 0; bj < 2; ++bj) xin[mm][bj] = *(const u32x4*)(X + (size_t)(row0 + ai * HALF + (mp * 2 + mm) * 16) * DM + col0 + bj * HALF);
;                 f32x4 pv[2][2][2];
; #pragma unroll
;                 for (int mm = 0; mm < 2; ++mm)
; #pragma unroll
;                     for (int bj = 0; bj < 2; ++bj)
; #pragma unroll
;                         for (int n = 0; n < 2; ++n) pv[mm][bj][n] = (f32x4){0.f, 0.f, 0.f, 0.f};
;                 if (src) {
;                     u32x4 pc[2][2];
;     ...
;                     asm volatile("global_load_dwordx4 %0, %4, off sc1\n\tglobal_load_dwordx4 %1, %5, off sc1\n\tglobal_load_dwordx4 %2, %6, off sc1\n\tglobal_load_dwordx4 %3, %7, off sc1\n\ts_waitcnt vmcnt(0)"
;                                  : "=&v"(pc[0][0]), "=&v"(pc[0][1]), "=&v"(pc[1][0]), "=&v"(pc[1][1])
;                                  : "v"(src + CI(0, 0)), "v"(src + CI(0, 1)), "v"(src + CI(1, 0)), "v"(src + CI(1, 1))
;                                  : "memory");
;     ...
; #pragma unroll
;                     for (int mm = 0; mm < 2; ++mm)
; #pragma unroll
;                         for (int bj = 0; bj < 2; ++bj) { float f[8]; unpack8(pc[mm][bj], f); pv[mm][bj][0] = (f32x4){f[0], f[1], f[2], f[3]}; pv[mm][bj][1] = (f32x4){f[4], f[5], f[6], f[7]}; }
;                 }
; #pragma unroll
;                 for (int mm = 0; mm < 2; ++mm) {
;                     const int m = mp * 2 + mm;
;                     const int row = row0 + ai * HALF + m * 16;
;                     float s = 0.f;
; #pragma unroll
;                     for (int bj = 0; bj < 2; ++bj) {
;                         u32x4* px = (u32x4*)(X + (size_t)row * DM + col0 + bj * HALF);
;                         float xo[8]; unpack8(xin[mm][bj], xo);
;                         const f32x4 a0 = acc[ai][bj][m][0] + pv[mm][bj][0], a1 = acc[ai][bj][m][1] + pv[mm][bj][1];
;                         u32x4 w;
;                         w.x = cvt_pk(xo[0] + scale * a0[0], xo[1] + scale * a0[1]); w.y = cvt_pk(xo[2] + scale * a0[2], xo[3] + scale * a0[3]);
.LBB0_417:
	s_or_b64 exec, exec, s[12:13]
	s_mov_b64 s[30:31], 0x50000
	v_lshl_add_u64 v[250:251], v[174:175], 0, s[30:31]
	v_lshl_add_u64 v[250:251], v[172:173], 0, v[250:251]
	global_load_dwordx4 v[64:67], v[250:251], off
	global_load_dwordx4 v[68:71], v[250:251], off offset:256
	s_mov_b64 s[30:31], 0x58000
	v_lshl_add_u64 v[252:253], v[174:175], 0, s[30:31]
	v_lshl_add_u64 v[252:253], v[172:173], 0, v[252:253]
	global_load_dwordx4 v[72:75], v[252:253], off
	global_load_dwordx4 v[76:79], v[252:253], off offset:256
	s_and_saveexec_b64 s[12:13], vcc
	s_mov_b64 s[30:31], 0x2800
	v_lshl_add_u64 v[250:251], v[170:171], 0, s[30:31]
	global_load_dwordx4 v[96:99], v[250:251], off sc1
	s_mov_b64 s[30:31], 0x3800
	v_lshl_add_u64 v[252:253], v[170:171], 0, s[30:31]
	global_load_dwordx4 v[100:103], v[252:253], off sc1
	s_mov_b64 s[30:31], 0x2c00
	v_lshl_add_u64 v[250:251], v[170:171], 0, s[30:31]
	global_load_dwordx4 v[104:107], v[250:251], off sc1
	s_mov_b64 s[30:31], 0x3c00
	v_lshl_add_u64 v[252:253], v[170:171], 0, s[30:31]
	global_load_dwordx4 v[108:111], v[252:253], off sc1
	s_or_b64 exec, exec, s[12:13]
	v_lshlrev_b32_e32 v214, 16, v140
	v_and_b32_e32 v215, 0xffff0000, v140
	v_lshlrev_b32_e32 v244, 16, v141
	v_and_b32_e32 v245, 0xffff0000, v141
	v_and_b32_e32 v247, 0xffff0000, v142
	v_pk_add_f32 v[140:141], v[60:61], v[208:209]
	v_pk_add_f32 v[204:205], v[56:57], v[204:205]
	v_lshlrev_b32_e32 v246, 16, v142
	v_fmac_f32_e32 v214, 0.5, v140
	v_fmac_f32_e32 v215, 0.5, v141
	v_cvt_pk_bf16_f32 v140, v214, v215
	v_fmac_f32_e32 v247, 0.5, v205
	v_and_b32_e32 v205, 0xffff0000, v140
	v_lshlrev_b32_e32 v248, 16, v143
	v_and_b32_e32 v249, 0xffff0000, v143
	v_pk_add_f32 v[142:143], v[62:63], v[210:211]
	v_pk_add_f32 v[206:207], v[58:59], v[206:207]
	v_fmac_f32_e32 v246, 0.5, v204
	v_lshlrev_b32_e32 v204, 16, v140
	v_mul_f32_e32 v205, v205, v205
	v_fmac_f32_e32 v244, 0.5, v142
	v_fmac_f32_e32 v245, 0.5, v143
	v_cvt_pk_bf16_f32 v141, v244, v245
	v_fmac_f32_e32 v248, 0.5, v206
	v_lshlrev_b32_e32 v206, 16, v141
	v_fmac_f32_e32 v205, v204, v204
	v_fmac_f32_e32 v249, 0.5, v207
	v_and_b32_e32 v207, 0xffff0000, v141
	v_fmac_f32_e32 v205, v206, v206
	v_cvt_pk_bf16_f32 v142, v246, v247
	v_fmac_f32_e32 v205, v207, v207
	v_lshlrev_b32_e32 v208, 16, v142
	v_and_b32_e32 v209, 0xffff0000, v142
	v_fmac_f32_e32 v205, v208, v208
	v_cvt_pk_bf16_f32 v143, v248, v249
	v_fmac_f32_e32 v205, v209, v209
	v_lshlrev_b32_e32 v210, 16, v143
	v_and_b32_e32 v211, 0xffff0000, v143
	v_fmac_f32_e32 v205, v210, v210
	v_fmac_f32_e32 v205, v211, v211
	v_lshlrev_b32_e32 v204, 16, v136
	v_and_b32_e32 v206, 0xffff0000, v136
	v_lshlrev_b32_e32 v207, 16, v137
	v_and_b32_e32 v208, 0xffff0000, v137
	v_lshlrev_b32_e32 v209, 16, v138
	v_and_b32_e32 v210, 0xffff0000, v138
	v_lshlrev_b32_e32 v211, 16, v139
	v_and_b32_e32 v214, 0xffff0000, v139
	v_pk_add_f32 v[136:137], v[30:31], v[202:203]
	v_pk_add_f32 v[138:139], v[28:29], v[200:201]
	v_pk_add_f32 v[200:201], v[26:27], v[198:199]
	v_pk_add_f32 v[198:199], v[24:25], v[196:197]
	v_fmac_f32_e32 v204, 0.5, v138
	v_fmac_f32_e32 v206, 0.5, v139
	v_cvt_pk_bf16_f32 v196, v204, v206
	v_fmac_f32_e32 v207, 0.5, v136
	v_lshlrev_b32_e32 v136, 16, v196
	v_fmac_f32_e32 v208, 0.5, v137
	v_and_b32_e32 v137, 0xffff0000, v196
	v_fmac_f32_e32 v205, v136, v136
	v_cvt_pk_bf16_f32 v197, v207, v208
	v_fmac_f32_e32 v205, v137, v137
	v_lshlrev_b32_e32 v138, 16, v197
	v_and_b32_e32 v139, 0xffff0000, v197
	v_fmac_f32_e32 v205, v138, v138
	v_fmac_f32_e32 v209, 0.5, v198
	v_fmac_f32_e32 v210, 0.5, v199
	v_cvt_pk_bf16_f32 v198, v209, v210
	v_fmac_f32_e32 v211, 0.5, v200
	v_lshlrev_b32_e32 v200, 16, v198
	v_fmac_f32_e32 v205, v139, v139
	v_fmac_f32_e32 v214, 0.5, v201
	v_and_b32_e32 v201, 0xffff0000, v198
	v_fmac_f32_e32 v205, v200, v200
	v_cvt_pk_bf16_f32 v199, v211, v214
	v_fmac_f32_e32 v205, v201, v201
	v_lshlrev_b32_e32 v202, 16, v199
	v_and_b32_e32 v203, 0xffff0000, v199
	v_fmac_f32_e32 v205, v202, v202
	v_fmac_f32_e32 v205, v203, v203
	v_mov_b32_e32 v136, v205
	s_nop 1
	v_permlane16_swap_b32_e32 v136, v205
	v_lshl_add_u64 v[138:139], s[28:29], 0, v[186:187]
	v_lshl_add_u64 v[138:139], v[168:169], 1, v[138:139]
	global_store_dwordx4 v[138:139], v[140:143], off
	global_store_dwordx4 v[138:139], v[196:199], off offset:256
	s_waitcnt lgkmcnt(0)
	v_add_f32_e32 v136, v205, v136
	v_mov_b32_e32 v137, v136
	s_nop 1
	v_permlane32_swap_b32_e32 v137, v136
	s_and_saveexec_b64 s[12:13], s[8:9]
	s_cbranch_execz .LBB0_419
	s_waitcnt lgkmcnt(0)
	v_add_f32_e32 v138, v136, v137
	v_lshl_add_u64 v[136:137], v[166:167], 2, s[6:7]
	global_atomic_add_f32 v[136:137], v138, off offset:512
; DI unsigned cvt_pk(float lo, float hi) { unsigned r; asm("v_cvt_pk_bf16_f32 %0, %1, %2" : "=v"(r) : "v"(lo), "v"(hi)); return r; }
;     __device__ __forceinline__ void operator()(const f32x4 (&acc)[2][2][4][2], const Unit& u, int wr, int wc, int fr, int fq) const {
;     ...
;                 for (int mm = 0; mm < 2; ++mm) {
;                     const int m = mp * 2 + mm;
;                     const int row = row0 + ai * HALF + m * 16;
;                     float s = 0.f;
; #pragma unroll
;                     for (int bj = 0; bj < 2; ++bj) {
;                         u32x4* px = (u32x4*)(X + (size_t)row * DM + col0 + bj * HALF);
;                         float xo[8]; unpack8(xin[mm][bj], xo);
;                         const f32x4 a0 = acc[ai][bj][m][0] + pv[mm][bj][0], a1 = acc[ai][bj][m][1] + pv[mm][bj][1];
;                         u32x4 w;
;                         w.x = cvt_pk(xo[0] + scale * a0[0], xo[1] + scale * a0[1]); w.y = cvt_pk(xo[2] + scale * a0[2], xo[3] + scale * a0[3]);
;                         w.z = cvt_pk(xo[4] + scale * a1[0], xo[5] + scale * a1[1]); w.w = cvt_pk(xo[6] + scale * a1[2], xo[7] + scale * a1[3]);
;                         *px = w;
;                         float xn[8]; unpack8(w, xn);
; #pragma unroll
;                         for (int j = 0; j < 8; ++j) s += xn[j] * xn[j];
;                     }
;                     s += __shfl_xor(s, 16); s += __shfl_xor(s, 32);
;                     if (fq == 0) unsafeAtomicAdd(ssn + row, s);
.LBB0_419:
	s_or_b64 exec, exec, s[12:13]
	v_lshlrev_b32_e32 v140, 16, v132
	v_and_b32_e32 v141, 0xffff0000, v132
	v_lshlrev_b32_e32 v142, 16, v133
	v_and_b32_e32 v143, 0xffff0000, v133
	v_lshlrev_b32_e32 v186, 16, v134
	v_and_b32_e32 v197, 0xffff0000, v135
	v_pk_add_f32 v[132:133], v[52:53], v[192:193]
	s_waitcnt lgkmcnt(0)
	v_pk_add_f32 v[136:137], v[50:51], v[190:191]
	v_pk_add_f32 v[138:139], v[48:49], v[188:189]
	v_and_b32_e32 v187, 0xffff0000, v134
	v_lshlrev_b32_e32 v196, 16, v135
	v_pk_add_f32 v[134:135], v[54:55], v[194:195]
	v_fmac_f32_e32 v140, 0.5, v132
	v_fmac_f32_e32 v141, 0.5, v133
	v_cvt_pk_bf16_f32 v132, v140, v141
	v_fmac_f32_e32 v186, 0.5, v138
	v_fmac_f32_e32 v197, 0.5, v137
	v_and_b32_e32 v137, 0xffff0000, v132
	v_fmac_f32_e32 v142, 0.5, v134
	v_fmac_f32_e32 v187, 0.5, v139
	v_cvt_pk_bf16_f32 v134, v186, v187
	v_fmac_f32_e32 v196, 0.5, v136
	v_lshlrev_b32_e32 v136, 16, v132
	v_mul_f32_e32 v186, v137, v137
	v_fmac_f32_e32 v143, 0.5, v135
	v_cvt_pk_bf16_f32 v133, v142, v143
	v_fmac_f32_e32 v186, v136, v136
	v_lshlrev_b32_e32 v138, 16, v133
	v_and_b32_e32 v139, 0xffff0000, v133
	v_fmac_f32_e32 v186, v138, v138
	v_lshlrev_b32_e32 v140, 16, v134
	v_fmac_f32_e32 v186, v139, v139
	v_and_b32_e32 v141, 0xffff0000, v134
	v_fmac_f32_e32 v186, v140, v140
	v_cvt_pk_bf16_f32 v135, v196, v197
	v_fmac_f32_e32 v186, v141, v141
	v_lshlrev_b32_e32 v142, 16, v135
	v_and_b32_e32 v143, 0xffff0000, v135
	v_fmac_f32_e32 v186, v142, v142
	v_lshlrev_b32_e32 v136, 16, v128
	v_lshlrev_b32_e32 v187, 16, v130
	v_and_b32_e32 v188, 0xffff0000, v130
	v_lshlrev_b32_e32 v189, 16, v131
	v_and_b32_e32 v190, 0xffff0000, v131
	v_pk_add_f32 v[130:131], v[20:21], v[182:183]
	v_fmac_f32_e32 v186, v143, v143
	v_and_b32_e32 v137, 0xffff0000, v128
	v_lshlrev_b32_e32 v142, 16, v129
	v_and_b32_e32 v143, 0xffff0000, v129
	v_pk_add_f32 v[128:129], v[22:23], v[184:185]
	v_fmac_f32_e32 v136, 0.5, v130
	v_fmac_f32_e32 v137, 0.5, v131
	v_cvt_pk_bf16_f32 v136, v136, v137
	v_fmac_f32_e32 v142, 0.5, v128
	v_lshlrev_b32_e32 v128, 16, v136
	v_fmac_f32_e32 v143, 0.5, v129
	v_and_b32_e32 v129, 0xffff0000, v136
	v_fmac_f32_e32 v186, v128, v128
	v_cvt_pk_bf16_f32 v137, v142, v143
	v_fmac_f32_e32 v186, v129, v129
	v_lshlrev_b32_e32 v130, 16, v137
	v_pk_add_f32 v[140:141], v[18:19], v[180:181]
	v_pk_add_f32 v[138:139], v[16:17], v[178:179]
	v_and_b32_e32 v131, 0xffff0000, v137
	v_fmac_f32_e32 v186, v130, v130
	v_fmac_f32_e32 v187, 0.5, v138
	v_fmac_f32_e32 v188, 0.5, v139
	v_cvt_pk_bf16_f32 v138, v187, v188
	v_fmac_f32_e32 v189, 0.5, v140
	v_lshlrev_b32_e32 v140, 16, v138
	v_fmac_f32_e32 v186, v131, v131
	v_fmac_f32_e32 v190, 0.5, v141
	v_and_b32_e32 v141, 0xffff0000, v138
	v_fmac_f32_e32 v186, v140, v140
	v_cvt_pk_bf16_f32 v139, v189, v190
	v_fmac_f32_e32 v186, v141, v141
	v_lshlrev_b32_e32 v142, 16, v139
	v_and_b32_e32 v143, 0xffff0000, v139
	v_fmac_f32_e32 v186, v142, v142
	v_fmac_f32_e32 v186, v143, v143
	v_mov_b32_e32 v128, v186
	s_nop 1
	v_permlane16_swap_b32_e32 v128, v186
	v_lshl_add_u64 v[130:131], s[28:29], 0, v[176:177]
	v_lshl_add_u64 v[130:131], v[168:169], 1, v[130:131]
	global_store_dwordx4 v[130:131], v[132:135], off
	global_store_dwordx4 v[130:131], v[136:139], off offset:256
	s_waitcnt lgkmcnt(0)
	v_add_f32_e32 v128, v186, v128
	v_mov_b32_e32 v129, v128
	s_nop 1
	v_permlane32_swap_b32_e32 v129, v128
	s_and_saveexec_b64 s[12:13], s[8:9]
	s_cbranch_execz .LBB0_421
	s_waitcnt lgkmcnt(0)
	v_add_f32_e32 v130, v128, v129
	v_lshl_add_u64 v[128:129], v[166:167], 2, s[6:7]
	global_atomic_add_f32 v[128:129], v130, off offset:576

; DI unsigned cvt_pk(float lo, float hi) { unsigned r; asm("v_cvt_pk_bf16_f32 %0, %1, %2" : "=v"(r) : "v"(lo), "v"(hi)); return r; }
;     __device__ __forceinline__ void operator()(const f32x4 (&acc)[2][2][4][2], const Unit& u, int wr, int wc, int fr, int fq) const {
;     ...
;                 for (int mm = 0; mm < 2; ++mm) {
;                     const int m = mp * 2 + mm;
;                     const int row = row0 + ai * HALF + m * 16;
;                     float s = 0.f;
; #pragma unroll
;                     for (int bj = 0; bj < 2; ++bj) {
;                         u32x4* px = (u32x4*)(X + (size_t)row * DM + col0 + bj * HALF);
;                         float xo[8]; unpack8(xin[mm][bj], xo);
;                         const f32x4 a0 = acc[ai][bj][m][0] + pv[mm][bj][0], a1 = acc[ai][bj][m][1] + pv[mm][bj][1];
;                         u32x4 w;
;                         w.x = cvt_pk(xo[0] + scale * a0[0], xo[1] + scale * a0[1]); w.y = cvt_pk(xo[2] + scale * a0[2], xo[3] + scale * a0[3]);
;                         w.z = cvt_pk(xo[4] + scale * a1[0], xo[5] + scale * a1[1]); w.w = cvt_pk(xo[6] + scale * a1[2], xo[7] + scale * a1[3]);
;                         *px = w;
;                         float xn[8]; unpack8(w, xn);
; #pragma unroll
;                         for (int j = 0; j < 8; ++j) s += xn[j] * xn[j];
;                     }
;                     s += __shfl_xor(s, 16); s += __shfl_xor(s, 32);
;                     if (fq == 0) unsafeAtomicAdd(ssn + row, s);
.LBB0_423:
	s_or_b64 exec, exec, s[12:13]
	v_lshlrev_b32_e32 v208, 16, v140
	v_and_b32_e32 v209, 0xffff0000, v140
	v_lshlrev_b32_e32 v210, 16, v141
	v_and_b32_e32 v211, 0xffff0000, v141
	v_and_b32_e32 v245, 0xffff0000, v143
	v_pk_add_f32 v[140:141], v[44:45], v[204:205]
	v_pk_add_f32 v[170:171], v[42:43], v[202:203]
	v_lshlrev_b32_e32 v244, 16, v143
	v_fmac_f32_e32 v208, 0.5, v140
	v_fmac_f32_e32 v209, 0.5, v141
	v_cvt_pk_bf16_f32 v140, v208, v209
	v_fmac_f32_e32 v245, 0.5, v171
	v_and_b32_e32 v171, 0xffff0000, v140
	v_lshlrev_b32_e32 v214, 16, v142
	v_and_b32_e32 v215, 0xffff0000, v142
	v_pk_add_f32 v[142:143], v[46:47], v[206:207]
	v_pk_add_f32 v[200:201], v[40:41], v[200:201]
	v_fmac_f32_e32 v244, 0.5, v170
	v_lshlrev_b32_e32 v170, 16, v140
	v_mul_f32_e32 v206, v171, v171
	v_fmac_f32_e32 v210, 0.5, v142
	v_fmac_f32_e32 v211, 0.5, v143
	v_cvt_pk_bf16_f32 v141, v210, v211
	v_fmac_f32_e32 v214, 0.5, v200
	v_lshlrev_b32_e32 v200, 16, v141
	v_fmac_f32_e32 v206, v170, v170
	v_fmac_f32_e32 v215, 0.5, v201
	v_and_b32_e32 v201, 0xffff0000, v141
	v_fmac_f32_e32 v206, v200, v200
	v_cvt_pk_bf16_f32 v142, v214, v215
	v_fmac_f32_e32 v206, v201, v201
	v_lshlrev_b32_e32 v202, 16, v142
	v_and_b32_e32 v203, 0xffff0000, v142
	v_fmac_f32_e32 v206, v202, v202
	v_cvt_pk_bf16_f32 v143, v244, v245
	v_fmac_f32_e32 v206, v203, v203
	v_lshlrev_b32_e32 v204, 16, v143
	v_and_b32_e32 v205, 0xffff0000, v143
	v_fmac_f32_e32 v206, v204, v204
	v_fmac_f32_e32 v206, v205, v205
	v_lshlrev_b32_e32 v200, 16, v136
	v_and_b32_e32 v201, 0xffff0000, v136
	v_lshlrev_b32_e32 v202, 16, v137
	v_and_b32_e32 v203, 0xffff0000, v137
	v_lshlrev_b32_e32 v204, 16, v138
	v_and_b32_e32 v205, 0xffff0000, v138
	v_lshlrev_b32_e32 v207, 16, v139
	v_and_b32_e32 v208, 0xffff0000, v139
	v_pk_add_f32 v[136:137], v[14:15], v[198:199]
	v_pk_add_f32 v[138:139], v[12:13], v[196:197]
	v_pk_add_f32 v[170:171], v[10:11], v[194:195]
	v_pk_add_f32 v[194:195], v[8:9], v[192:193]
	v_fmac_f32_e32 v200, 0.5, v138
	v_fmac_f32_e32 v201, 0.5, v139
	v_cvt_pk_bf16_f32 v192, v200, v201
	v_fmac_f32_e32 v202, 0.5, v136
	v_lshlrev_b32_e32 v136, 16, v192
	v_fmac_f32_e32 v203, 0.5, v137
	v_and_b32_e32 v137, 0xffff0000, v192
	v_fmac_f32_e32 v206, v136, v136
	v_cvt_pk_bf16_f32 v193, v202, v203
	v_fmac_f32_e32 v206, v137, v137
	v_lshlrev_b32_e32 v138, 16, v193
	v_and_b32_e32 v139, 0xffff0000, v193
	v_fmac_f32_e32 v206, v138, v138
	v_fmac_f32_e32 v204, 0.5, v194
	v_fmac_f32_e32 v205, 0.5, v195
	v_cvt_pk_bf16_f32 v194, v204, v205
	v_fmac_f32_e32 v207, 0.5, v170
	v_lshlrev_b32_e32 v170, 16, v194
	v_fmac_f32_e32 v206, v139, v139
	v_fmac_f32_e32 v208, 0.5, v171
	v_and_b32_e32 v171, 0xffff0000, v194
	v_fmac_f32_e32 v206, v170, v170
	v_cvt_pk_bf16_f32 v195, v207, v208
	v_fmac_f32_e32 v206, v171, v171
	v_lshlrev_b32_e32 v196, 16, v195
	v_and_b32_e32 v197, 0xffff0000, v195
	v_fmac_f32_e32 v206, v196, v196
	v_fmac_f32_e32 v206, v197, v197
	v_mov_b32_e32 v136, v206
	s_nop 1
	v_permlane16_swap_b32_e32 v136, v206
	v_lshl_add_u64 v[138:139], s[28:29], 0, v[182:183]
	v_lshl_add_u64 v[138:139], v[168:169], 1, v[138:139]
	global_store_dwordx4 v[138:139], v[140:143], off
	global_store_dwordx4 v[138:139], v[192:195], off offset:256
	s_waitcnt lgkmcnt(0)
	v_add_f32_e32 v136, v206, v136
	v_mov_b32_e32 v137, v136
	s_nop 1
	v_permlane32_swap_b32_e32 v137, v136
	s_and_saveexec_b64 s[12:13], s[8:9]
	s_cbranch_execz .LBB0_425
	s_waitcnt lgkmcnt(0)
	v_add_f32_e32 v138, v136, v137
	v_lshl_add_u64 v[136:137], v[166:167], 2, s[6:7]
	global_atomic_add_f32 v[136:137], v138, off offset:640
; DI unsigned cvt_pk(float lo, float hi) { unsigned r; asm("v_cvt_pk_bf16_f32 %0, %1, %2" : "=v"(r) : "v"(lo), "v"(hi)); return r; }
;     __device__ __forceinline__ void operator()(const f32x4 (&acc)[2][2][4][2], const Unit& u, int wr, int wc, int fr, int fq) const {
;     ...
;                 for (int mm = 0; mm < 2; ++mm) {
;                     const int m = mp * 2 + mm;
;                     const int row = row0 + ai * HALF + m * 16;
;                     float s = 0.f;
; #pragma unroll
;                     for (int bj = 0; bj < 2; ++bj) {
;                         u32x4* px = (u32x4*)(X + (size_t)row * DM + col0 + bj * HALF);
;                         float xo[8]; unpack8(xin[mm][bj], xo);
;                         const f32x4 a0 = acc[ai][bj][m][0] + pv[mm][bj][0], a1 = acc[ai][bj][m][1] + pv[mm][bj][1];
;                         u32x4 w;
;                         w.x = cvt_pk(xo[0] + scale * a0[0], xo[1] + scale * a0[1]); w.y = cvt_pk(xo[2] + scale * a0[2], xo[3] + scale * a0[3]);
;                         w.z = cvt_pk(xo[4] + scale * a1[0], xo[5] + scale * a1[1]); w.w = cvt_pk(xo[6] + scale * a1[2], xo[7] + scale * a1[3]);
;                         *px = w;
;                         float xn[8]; unpack8(w, xn);
; #pragma unroll
;                         for (int j = 0; j < 8; ++j) s += xn[j] * xn[j];
;                     }
;                     s += __shfl_xor(s, 16); s += __shfl_xor(s, 32);
;                     if (fq == 0) unsafeAtomicAdd(ssn + row, s);
.LBB0_425:
	s_or_b64 exec, exec, s[12:13]
	v_lshlrev_b32_e32 v140, 16, v132
	v_and_b32_e32 v141, 0xffff0000, v132
	v_lshlrev_b32_e32 v142, 16, v133
	v_and_b32_e32 v143, 0xffff0000, v133
	v_lshlrev_b32_e32 v170, 16, v134
	v_and_b32_e32 v183, 0xffff0000, v135
	v_pk_add_f32 v[132:133], v[36:37], v[188:189]
	s_waitcnt lgkmcnt(0)
	v_pk_add_f32 v[136:137], v[34:35], v[186:187]
	v_pk_add_f32 v[138:139], v[32:33], v[184:185]
	v_and_b32_e32 v171, 0xffff0000, v134
	v_lshlrev_b32_e32 v182, 16, v135
	v_pk_add_f32 v[134:135], v[38:39], v[190:191]
	v_fmac_f32_e32 v140, 0.5, v132
	v_fmac_f32_e32 v141, 0.5, v133
	v_cvt_pk_bf16_f32 v132, v140, v141
	v_fmac_f32_e32 v170, 0.5, v138
	v_fmac_f32_e32 v183, 0.5, v137
	v_and_b32_e32 v137, 0xffff0000, v132
	v_fmac_f32_e32 v142, 0.5, v134
	v_fmac_f32_e32 v171, 0.5, v139
	v_cvt_pk_bf16_f32 v134, v170, v171
	v_fmac_f32_e32 v182, 0.5, v136
	v_lshlrev_b32_e32 v136, 16, v132
	v_mul_f32_e32 v170, v137, v137
	v_fmac_f32_e32 v143, 0.5, v135
	v_cvt_pk_bf16_f32 v133, v142, v143
	v_fmac_f32_e32 v170, v136, v136
	v_lshlrev_b32_e32 v138, 16, v133
	v_and_b32_e32 v139, 0xffff0000, v133
	v_fmac_f32_e32 v170, v138, v138
	v_lshlrev_b32_e32 v140, 16, v134
	v_fmac_f32_e32 v170, v139, v139
	v_and_b32_e32 v141, 0xffff0000, v134
	v_fmac_f32_e32 v170, v140, v140
	v_cvt_pk_bf16_f32 v135, v182, v183
	v_fmac_f32_e32 v170, v141, v141
	v_lshlrev_b32_e32 v142, 16, v135
	v_and_b32_e32 v143, 0xffff0000, v135
	v_fmac_f32_e32 v170, v142, v142
	v_lshlrev_b32_e32 v136, 16, v128
	v_lshlrev_b32_e32 v171, 16, v130
	v_and_b32_e32 v182, 0xffff0000, v130
	v_lshlrev_b32_e32 v183, 16, v131
	v_and_b32_e32 v184, 0xffff0000, v131
	v_pk_add_f32 v[130:131], v[4:5], v[178:179]
	v_fmac_f32_e32 v170, v143, v143
	v_and_b32_e32 v137, 0xffff0000, v128
	v_lshlrev_b32_e32 v142, 16, v129
	v_and_b32_e32 v143, 0xffff0000, v129
	v_pk_add_f32 v[128:129], v[6:7], v[180:181]
	v_fmac_f32_e32 v136, 0.5, v130
	v_fmac_f32_e32 v137, 0.5, v131
	v_cvt_pk_bf16_f32 v136, v136, v137
	v_fmac_f32_e32 v142, 0.5, v128
	v_lshlrev_b32_e32 v128, 16, v136
	v_fmac_f32_e32 v143, 0.5, v129
	v_and_b32_e32 v129, 0xffff0000, v136
	v_fmac_f32_e32 v170, v128, v128
	v_cvt_pk_bf16_f32 v137, v142, v143
	v_fmac_f32_e32 v170, v129, v129
	v_lshlrev_b32_e32 v130, 16, v137
	v_pk_add_f32 v[140:141], v[2:3], v[176:177]
	v_pk_add_f32 v[138:139], v[0:1], v[172:173]
	v_and_b32_e32 v131, 0xffff0000, v137
	v_fmac_f32_e32 v170, v130, v130
	v_fmac_f32_e32 v171, 0.5, v138
	v_fmac_f32_e32 v182, 0.5, v139
	v_cvt_pk_bf16_f32 v138, v171, v182
	v_fmac_f32_e32 v183, 0.5, v140
	v_lshlrev_b32_e32 v140, 16, v138
	v_fmac_f32_e32 v170, v131, v131
	v_fmac_f32_e32 v184, 0.5, v141
	v_and_b32_e32 v141, 0xffff0000, v138
	v_fmac_f32_e32 v170, v140, v140
	v_cvt_pk_bf16_f32 v139, v183, v184
	v_fmac_f32_e32 v170, v141, v141
	v_lshlrev_b32_e32 v142, 16, v139
	v_and_b32_e32 v143, 0xffff0000, v139
	v_fmac_f32_e32 v170, v142, v142
	v_fmac_f32_e32 v170, v143, v143
	v_mov_b32_e32 v128, v170
	s_nop 1
	v_permlane16_swap_b32_e32 v128, v170
	v_lshl_add_u64 v[130:131], s[28:29], 0, v[174:175]
	v_lshl_add_u64 v[130:131], v[168:169], 1, v[130:131]
	global_store_dwordx4 v[130:131], v[132:135], off
	global_store_dwordx4 v[130:131], v[136:139], off offset:256
	s_waitcnt lgkmcnt(0)
	v_add_f32_e32 v128, v170, v128
	v_mov_b32_e32 v129, v128
	s_nop 1
	v_permlane32_swap_b32_e32 v129, v128
	s_and_saveexec_b64 s[12:13], s[8:9]
	s_cbranch_execz .LBB0_427
	s_waitcnt lgkmcnt(0)
	v_add_f32_e32 v130, v128, v129
	v_lshl_add_u64 v[128:129], v[166:167], 2, s[6:7]
	global_atomic_add_f32 v[128:129], v130, off offset:704

;     __device__ __forceinline__ void operator()(const f32x4 (&acc)[2][2][4][2], const Unit& u, int wr, int wc, int fr, int fq) const {
;     ...
;         const int row0 = u.pm * BM + wr * 64 + fr, col0 = u.pn * BM + wc * 32 + 8 * fq;
; #pragma unroll
;         for (int ai = 0; ai < 2; ++ai)
; #pragma unroll
;             for (int mp = 0; mp < 2; ++mp) {
;                 u32x4 xin[2][2];
; #pragma unroll
;                 for (int mm = 0; mm < 2; ++mm)
; #pragma unroll
;                     for (int bj = 0; bj < 2; ++bj) xin[mm][bj] = *(const u32x4*)(X + (size_t)(row0 + ai * HALF + (mp * 2 + mm) * 16) * DM + col0 + bj * HALF);
;                 f32x4 pv[2][2][2];
; #pragma unroll
;                 for (int mm = 0; mm < 2; ++mm)
; #pragma unroll
;                     for (int bj = 0; bj < 2; ++bj)
; #pragma unroll
;                         for (int n = 0; n < 2; ++n) pv[mm][bj][n] = (f32x4){0.f, 0.f, 0.f, 0.f};
;                 if (src) {
;                     u32x4 pc[2][2];
;     ...
;                     asm volatile("global_load_dwordx4 %0, %4, off sc1\n\tglobal_load_dwordx4 %1, %5, off sc1\n\tglobal_load_dwordx4 %2, %6, off sc1\n\tglobal_load_dwordx4 %3, %7, off sc1\n\ts_waitcnt vmcnt(0)"
;                                  : "=&v"(pc[0][0]), "=&v"(pc[0][1]), "=&v"(pc[1][0]), "=&v"(pc[1][1])
;                                  : "v"(src + CI(0, 0)), "v"(src + CI(0, 1)), "v"(src + CI(1, 0)), "v"(src + CI(1, 1))
;                                  : "memory");
;     ...
; #pragma unroll
;                     for (int mm = 0; mm < 2; ++mm)
; #pragma unroll
;                         for (int bj = 0; bj < 2; ++bj) { float f[8]; unpack8(pc[mm][bj], f); pv[mm][bj][0] = (f32x4){f[0], f[1], f[2], f[3]}; pv[mm][bj][1] = (f32x4){f[4], f[5], f[6], f[7]}; }
;                 }
; #pragma unroll
;                 for (int mm = 0; mm < 2; ++mm) {
;                     const int m = mp * 2 + mm;
;                     const int row = row0 + ai * HALF + m * 16;
;                     float s = 0.f;
; #pragma unroll
;                     for (int bj = 0; bj < 2; ++bj) {
;                         u32x4* px = (u32x4*)(X + (size_t)row * DM + col0 + bj * HALF);
;                         float xo[8]; unpack8(xin[mm][bj], xo);
;                         const f32x4 a0 = acc[ai][bj][m][0] + pv[mm][bj][0], a1 = acc[ai][bj][m][1] + pv[mm][bj][1];
;                         u32x4 w;
.LBB0_456:
	v_lshl_or_b32 v140, s37, 8, v158
	v_lshl_add_u32 v138, s42, 8, v156
	v_ashrrev_i32_e32 v141, 31, v140
	v_lshlrev_b64 v[168:169], 1, v[140:141]
	v_ashrrev_i32_e32 v139, 31, v138
	v_lshl_add_u64 v[142:143], s[28:29], 0, v[168:169]
	v_lshlrev_b64 v[154:155], 11, v[138:139]
	v_lshl_add_u64 v[164:165], v[142:143], 0, v[154:155]
	global_load_dwordx4 v[160:163], v[164:165], off
	s_nop 0
	global_load_dwordx4 v[164:167], v[164:165], off offset:256
	v_pk_add_f32 v[180:181], v[112:113], 0 op_sel_hi:[1,0]
	v_and_b32_e32 v113, 64, v221
	v_or_b32_e32 v112, 16, v138
	v_pk_add_f32 v[170:171], v[122:123], 0 op_sel_hi:[1,0]
	v_pk_add_f32 v[178:179], v[114:115], 0 op_sel_hi:[1,0]
	v_xor_b32_e32 v114, 16, v221
	v_add_u32_e32 v123, 64, v113
	v_ashrrev_i32_e32 v113, 31, v112
	v_pk_add_f32 v[172:173], v[120:121], 0 op_sel_hi:[1,0]
	v_cmp_lt_i32_e32 vcc, v114, v123
	v_lshlrev_b64 v[120:121], 11, v[112:113]
	v_lshl_add_u64 v[112:113], v[142:143], 0, v[120:121]
	v_cndmask_b32_e32 v114, v221, v114, vcc
	v_pk_add_f32 v[174:175], v[118:119], 0 op_sel_hi:[1,0]
	v_pk_add_f32 v[176:177], v[116:117], 0 op_sel_hi:[1,0]
	v_lshlrev_b32_e32 v122, 2, v114
	global_load_dwordx4 v[116:119], v[112:113], off
	s_nop 0
	global_load_dwordx4 v[112:115], v[112:113], off offset:256
	v_pk_add_f32 v[124:125], v[124:125], 0 op_sel_hi:[1,0]
	v_pk_add_f32 v[126:127], v[126:127], 0 op_sel_hi:[1,0]
	s_waitcnt vmcnt(0)
	v_lshlrev_b32_e32 v182, 16, v160
	v_and_b32_e32 v160, 0xffff0000, v160
	v_fmac_f32_e32 v160, 0.5, v125
	v_lshlrev_b32_e32 v183, 16, v161
	v_and_b32_e32 v161, 0xffff0000, v161
	v_fmac_f32_e32 v182, 0.5, v124
	v_cvt_pk_bf16_f32 v160, v182, v160
	v_fmac_f32_e32 v161, 0.5, v127
	v_and_b32_e32 v125, 0xffff0000, v160
	v_lshlrev_b32_e32 v124, 16, v160
	v_mul_f32_e32 v125, v125, v125
	v_lshlrev_b32_e32 v184, 16, v162
	v_and_b32_e32 v162, 0xffff0000, v162
	v_fmac_f32_e32 v183, 0.5, v126
	v_cvt_pk_bf16_f32 v161, v183, v161
	v_fmac_f32_e32 v125, v124, v124
	v_lshlrev_b32_e32 v126, 16, v161
	v_lshlrev_b32_e32 v185, 16, v163
	v_fmac_f32_e32 v162, 0.5, v173
	v_and_b32_e32 v127, 0xffff0000, v161
	v_fmac_f32_e32 v125, v126, v126
	v_and_b32_e32 v163, 0xffff0000, v163
	v_fmac_f32_e32 v184, 0.5, v172
	v_fmac_f32_e32 v185, 0.5, v170
	v_cvt_pk_bf16_f32 v162, v184, v162
	v_fmac_f32_e32 v125, v127, v127
	v_lshlrev_b32_e32 v170, 16, v162
	v_fmac_f32_e32 v163, 0.5, v171
	v_and_b32_e32 v171, 0xffff0000, v162
	v_fmac_f32_e32 v125, v170, v170
	v_lshlrev_b32_e32 v186, 16, v164
	v_and_b32_e32 v164, 0xffff0000, v164
	v_cvt_pk_bf16_f32 v163, v185, v163
	v_fmac_f32_e32 v125, v171, v171
	v_lshlrev_b32_e32 v172, 16, v163
	v_lshlrev_b32_e32 v187, 16, v165
	v_fmac_f32_e32 v164, 0.5, v177
	v_and_b32_e32 v173, 0xffff0000, v163
	v_fmac_f32_e32 v125, v172, v172
	v_and_b32_e32 v165, 0xffff0000, v165
	v_fmac_f32_e32 v186, 0.5, v176
	v_fmac_f32_e32 v187, 0.5, v174
	v_cvt_pk_bf16_f32 v164, v186, v164
	v_fmac_f32_e32 v125, v173, v173
	v_lshlrev_b32_e32 v174, 16, v164
	v_fmac_f32_e32 v165, 0.5, v175
	v_and_b32_e32 v175, 0xffff0000, v164
	v_fmac_f32_e32 v125, v174, v174
	v_lshlrev_b32_e32 v188, 16, v166
	v_and_b32_e32 v166, 0xffff0000, v166
	v_cvt_pk_bf16_f32 v165, v187, v165
	v_fmac_f32_e32 v125, v175, v175
	v_lshlrev_b32_e32 v176, 16, v165
	v_lshlrev_b32_e32 v189, 16, v167
	v_fmac_f32_e32 v166, 0.5, v181
	v_and_b32_e32 v177, 0xffff0000, v165
	v_fmac_f32_e32 v125, v176, v176
	v_and_b32_e32 v167, 0xffff0000, v167
	v_fmac_f32_e32 v188, 0.5, v180
	v_fmac_f32_e32 v189, 0.5, v178
	v_cvt_pk_bf16_f32 v166, v188, v166
	v_fmac_f32_e32 v125, v177, v177
	v_lshlrev_b32_e32 v178, 16, v166
	v_fmac_f32_e32 v167, 0.5, v179
	v_and_b32_e32 v179, 0xffff0000, v166
	v_fmac_f32_e32 v125, v178, v178
	v_cvt_pk_bf16_f32 v167, v189, v167
	v_fmac_f32_e32 v125, v179, v179
	v_lshlrev_b32_e32 v180, 16, v167
	v_and_b32_e32 v181, 0xffff0000, v167
	v_fmac_f32_e32 v125, v180, v180
	v_fmac_f32_e32 v125, v181, v181
	v_mov_b32_e32 v124, v125
	s_nop 1
	v_permlane16_swap_b32_e32 v124, v125
	v_xor_b32_e32 v126, 32, v221
	v_cmp_lt_i32_e32 vcc, v126, v123
	s_waitcnt lgkmcnt(0)
	v_add_f32_e32 v124, v125, v124
	v_cndmask_b32_e32 v123, v221, v126, vcc
	v_lshlrev_b32_e32 v123, 2, v123
	v_mov_b32_e32 v125, v124
	s_nop 1
	v_permlane32_swap_b32_e32 v125, v124
	v_lshl_add_u64 v[126:127], s[28:29], 0, v[154:155]
	v_lshl_add_u64 v[126:127], v[126:127], 0, v[168:169]
	global_store_dwordx4 v[126:127], v[160:163], off
	global_store_dwordx4 v[126:127], v[164:167], off offset:256
	s_and_saveexec_b64 s[16:17], s[8:9]
	s_cbranch_execz .LBB0_458
	s_waitcnt lgkmcnt(0)
	v_add_f32_e32 v126, v124, v125
	v_lshl_add_u64 v[124:125], v[138:139], 2, s[6:7]
	global_atomic_add_f32 v[124:125], v126, off
;     __device__ __forceinline__ void operator()(const f32x4 (&acc)[2][2][4][2], const Unit& u, int wr, int wc, int fr, int fq) const {
;     ...
;                 u32x4 xin[2][2];
; #pragma unroll
;                 for (int mm = 0; mm < 2; ++mm)
; #pragma unroll
;                     for (int bj = 0; bj < 2; ++bj) xin[mm][bj] = *(const u32x4*)(X + (size_t)(row0 + ai * HALF + (mp * 2 + mm) * 16) * DM + col0 + bj * HALF);
;                 f32x4 pv[2][2][2];
; #pragma unroll
;                 for (int mm = 0; mm < 2; ++mm)
; #pragma unroll
;                     for (int bj = 0; bj < 2; ++bj)
; #pragma unroll
;                         for (int n = 0; n < 2; ++n) pv[mm][bj][n] = (f32x4){0.f, 0.f, 0.f, 0.f};
;                 if (src) {
;                     u32x4 pc[2][2];
;     ...
;                     asm volatile("global_load_dwordx4 %0, %4, off sc1\n\tglobal_load_dwordx4 %1, %5, off sc1\n\tglobal_load_dwordx4 %2, %6, off sc1\n\tglobal_load_dwordx4 %3, %7, off sc1\n\ts_waitcnt vmcnt(0)"
;                                  : "=&v"(pc[0][0]), "=&v"(pc[0][1]), "=&v"(pc[1][0]), "=&v"(pc[1][1])
;                                  : "v"(src + CI(0, 0)), "v"(src + CI(0, 1)), "v"(src + CI(1, 0)), "v"(src + CI(1, 1))
;                                  : "memory");
;     ...
; #pragma unroll
;                     for (int mm = 0; mm < 2; ++mm)
; #pragma unroll
;                         for (int bj = 0; bj < 2; ++bj) { float f[8]; unpack8(pc[mm][bj], f); pv[mm][bj][0] = (f32x4){f[0], f[1], f[2], f[3]}; pv[mm][bj][1] = (f32x4){f[4], f[5], f[6], f[7]}; }
;                 }
; #pragma unroll
;                 for (int mm = 0; mm < 2; ++mm) {
;                     const int m = mp * 2 + mm;
;                     const int row = row0 + ai * HALF + m * 16;
;                     float s = 0.f;
; #pragma unroll
;                     for (int bj = 0; bj < 2; ++bj) {
;                         u32x4* px = (u32x4*)(X + (size_t)row * DM + col0 + bj * HALF);
;                         float xo[8]; unpack8(xin[mm][bj], xo);
;                         const f32x4 a0 = acc[ai][bj][m][0] + pv[mm][bj][0], a1 = acc[ai][bj][m][1] + pv[mm][bj][1];
;                         u32x4 w;
;                         w.x = cvt_pk(xo[0] + scale * a0[0], xo[1] + scale * a0[1]); w.y = cvt_pk(xo[2] + scale * a0[2], xo[3] + scale * a0[3]);
.LBB0_458:
	s_or_b64 exec, exec, s[16:17]
	v_lshlrev_b32_e32 v124, 16, v116
	s_waitcnt lgkmcnt(0)
	v_and_b32_e32 v125, 0xffff0000, v116
	v_pk_add_f32 v[108:109], v[108:109], 0 op_sel_hi:[1,0]
	v_lshlrev_b32_e32 v126, 16, v117
	v_and_b32_e32 v127, 0xffff0000, v117
	v_pk_add_f32 v[116:117], v[106:107], 0 op_sel_hi:[1,0]
	v_pk_add_f32 v[106:107], v[104:105], 0 op_sel_hi:[1,0]
	v_fmac_f32_e32 v124, 0.5, v108
	v_fmac_f32_e32 v125, 0.5, v109
	v_cvt_pk_bf16_f32 v104, v124, v125
	v_pk_add_f32 v[110:111], v[110:111], 0 op_sel_hi:[1,0]
	v_and_b32_e32 v109, 0xffff0000, v104
	v_lshlrev_b32_e32 v108, 16, v104
	v_mul_f32_e32 v124, v109, v109
	v_fmac_f32_e32 v126, 0.5, v110
	v_fmac_f32_e32 v127, 0.5, v111
	v_cvt_pk_bf16_f32 v105, v126, v127
	v_fmac_f32_e32 v124, v108, v108
	v_lshlrev_b32_e32 v110, 16, v105
	v_lshlrev_b32_e32 v160, 16, v118
	v_and_b32_e32 v118, 0xffff0000, v118
	v_lshlrev_b32_e32 v161, 16, v119
	v_and_b32_e32 v111, 0xffff0000, v105
	v_fmac_f32_e32 v124, v110, v110
	v_and_b32_e32 v119, 0xffff0000, v119
	v_fmac_f32_e32 v160, 0.5, v106
	v_fmac_f32_e32 v118, 0.5, v107
	v_cvt_pk_bf16_f32 v106, v160, v118
	v_fmac_f32_e32 v161, 0.5, v116
	v_lshlrev_b32_e32 v116, 16, v106
	v_fmac_f32_e32 v124, v111, v111
	v_fmac_f32_e32 v119, 0.5, v117
	v_and_b32_e32 v117, 0xffff0000, v106
	v_fmac_f32_e32 v124, v116, v116
	v_cvt_pk_bf16_f32 v107, v161, v119
	v_fmac_f32_e32 v124, v117, v117
	v_lshlrev_b32_e32 v118, 16, v107
	v_and_b32_e32 v119, 0xffff0000, v107
	v_fmac_f32_e32 v124, v118, v118
	v_lshlrev_b32_e32 v110, 16, v112
	v_and_b32_e32 v111, 0xffff0000, v112
	v_lshlrev_b32_e32 v116, 16, v114
	v_pk_add_f32 v[100:101], v[100:101], 0 op_sel_hi:[1,0]
	v_pk_add_f32 v[96:97], v[96:97], 0 op_sel_hi:[1,0]
	v_fmac_f32_e32 v124, v119, v119
	v_and_b32_e32 v114, 0xffff0000, v114
	v_pk_add_f32 v[108:109], v[98:99], 0 op_sel_hi:[1,0]
	v_fmac_f32_e32 v110, 0.5, v100
	v_fmac_f32_e32 v111, 0.5, v101
	v_cvt_pk_bf16_f32 v98, v110, v111
	v_fmac_f32_e32 v116, 0.5, v96
	v_lshlrev_b32_e32 v96, 16, v98
	v_lshlrev_b32_e32 v112, 16, v113
	v_and_b32_e32 v113, 0xffff0000, v113
	v_pk_add_f32 v[102:103], v[102:103], 0 op_sel_hi:[1,0]
	v_fmac_f32_e32 v114, 0.5, v97
	v_and_b32_e32 v97, 0xffff0000, v98
	v_fmac_f32_e32 v124, v96, v96
	v_fmac_f32_e32 v112, 0.5, v102
	v_fmac_f32_e32 v113, 0.5, v103
	v_cvt_pk_bf16_f32 v99, v112, v113
	v_fmac_f32_e32 v124, v97, v97
	v_lshlrev_b32_e32 v102, 16, v99
	v_lshlrev_b32_e32 v117, 16, v115
	v_and_b32_e32 v103, 0xffff0000, v99
	v_fmac_f32_e32 v124, v102, v102
	v_and_b32_e32 v115, 0xffff0000, v115
	v_cvt_pk_bf16_f32 v100, v116, v114
	v_fmac_f32_e32 v117, 0.5, v108
	v_lshlrev_b32_e32 v108, 16, v100
	v_fmac_f32_e32 v124, v103, v103
	v_fmac_f32_e32 v115, 0.5, v109
	v_and_b32_e32 v109, 0xffff0000, v100
	v_fmac_f32_e32 v124, v108, v108
	v_cvt_pk_bf16_f32 v101, v117, v115
	v_fmac_f32_e32 v124, v109, v109
	v_lshlrev_b32_e32 v110, 16, v101
	v_and_b32_e32 v111, 0xffff0000, v101
	v_fmac_f32_e32 v124, v110, v110
	v_fmac_f32_e32 v124, v111, v111
	v_mov_b32_e32 v96, v124
	s_nop 1
	v_permlane16_swap_b32_e32 v96, v124
	v_lshl_add_u64 v[102:103], s[28:29], 0, v[120:121]
	v_lshl_add_u64 v[102:103], v[140:141], 1, v[102:103]
	global_store_dwordx4 v[102:103], v[104:107], off
	global_store_dwordx4 v[102:103], v[98:101], off offset:256
	s_waitcnt lgkmcnt(0)
	v_add_f32_e32 v96, v124, v96
	v_mov_b32_e32 v97, v96
	s_nop 1
	v_permlane32_swap_b32_e32 v97, v96
	s_and_saveexec_b64 s[16:17], s[8:9]
	s_cbranch_execz .LBB0_460
	s_waitcnt lgkmcnt(0)
	v_add_f32_e32 v98, v96, v97
	v_lshl_add_u64 v[96:97], v[138:139], 2, s[6:7]
	global_atomic_add_f32 v[96:97], v98, off offset:64
.LBB0_460:
	s_or_b64 exec, exec, s[16:17]
	v_or_b32_e32 v96, 32, v138
	s_waitcnt lgkmcnt(0)
	v_ashrrev_i32_e32 v97, 31, v96
	v_lshlrev_b64 v[106:107], 11, v[96:97]
	v_lshl_add_u64 v[96:97], v[142:143], 0, v[106:107]
	global_load_dwordx4 v[108:111], v[96:97], off
	global_load_dwordx4 v[112:115], v[96:97], off offset:256
	v_or_b32_e32 v96, 48, v138
	v_ashrrev_i32_e32 v97, 31, v96
	v_lshlrev_b64 v[104:105], 11, v[96:97]
	v_lshl_add_u64 v[96:97], v[142:143], 0, v[104:105]
	global_load_dwordx4 v[100:103], v[96:97], off
	s_nop 0
	global_load_dwordx4 v[96:99], v[96:97], off offset:256
	v_lshl_add_u64 v[106:107], s[28:29], 0, v[106:107]
	v_pk_add_f32 v[92:93], v[92:93], 0 op_sel_hi:[1,0]
	v_lshl_add_u64 v[106:107], v[140:141], 1, v[106:107]
	v_pk_add_f32 v[94:95], v[94:95], 0 op_sel_hi:[1,0]
	v_pk_add_f32 v[84:85], v[84:85], 0 op_sel_hi:[1,0]
	v_pk_add_f32 v[86:87], v[86:87], 0 op_sel_hi:[1,0]
	s_waitcnt vmcnt(3)
	v_lshlrev_b32_e32 v116, 16, v108
	v_and_b32_e32 v117, 0xffff0000, v108
	v_lshlrev_b32_e32 v118, 16, v109
	v_and_b32_e32 v119, 0xffff0000, v109
	v_lshlrev_b32_e32 v120, 16, v110
	v_and_b32_e32 v110, 0xffff0000, v110
	v_lshlrev_b32_e32 v121, 16, v111
	v_and_b32_e32 v111, 0xffff0000, v111
	v_pk_add_f32 v[108:109], v[90:91], 0 op_sel_hi:[1,0]
	v_pk_add_f32 v[90:91], v[88:89], 0 op_sel_hi:[1,0]
	v_fmac_f32_e32 v116, 0.5, v92
	v_fmac_f32_e32 v117, 0.5, v93
	v_cvt_pk_bf16_f32 v88, v116, v117
	v_fmac_f32_e32 v118, 0.5, v94
	v_fmac_f32_e32 v119, 0.5, v95
	v_cvt_pk_bf16_f32 v89, v118, v119
	v_fmac_f32_e32 v120, 0.5, v90
	v_fmac_f32_e32 v110, 0.5, v91
	v_cvt_pk_bf16_f32 v90, v120, v110
	v_fmac_f32_e32 v121, 0.5, v108
	v_fmac_f32_e32 v111, 0.5, v109
	v_cvt_pk_bf16_f32 v91, v121, v111
	global_store_dwordx4 v[106:107], v[88:91], off
	v_lshlrev_b32_e32 v92, 16, v88
	v_lshlrev_b32_e32 v93, 16, v89
	v_and_b32_e32 v88, 0xffff0000, v88
	v_mul_f32_e32 v108, v88, v88
	v_fmac_f32_e32 v108, v92, v92
	v_and_b32_e32 v89, 0xffff0000, v89
	v_fmac_f32_e32 v108, v93, v93
	v_lshlrev_b32_e32 v94, 16, v90
	v_fmac_f32_e32 v108, v89, v89
	v_and_b32_e32 v90, 0xffff0000, v90
	v_fmac_f32_e32 v108, v94, v94
	v_lshlrev_b32_e32 v95, 16, v91
	v_fmac_f32_e32 v108, v90, v90
	v_and_b32_e32 v91, 0xffff0000, v91
	v_fmac_f32_e32 v108, v95, v95
	v_fmac_f32_e32 v108, v91, v91
	s_waitcnt vmcnt(3)
; DI unsigned cvt_pk(float lo, float hi) { unsigned r; asm("v_cvt_pk_bf16_f32 %0, %1, %2" : "=v"(r) : "v"(lo), "v"(hi)); return r; }
;     __device__ __forceinline__ void operator()(const f32x4 (&acc)[2][2][4][2], const Unit& u, int wr, int wc, int fr, int fq) const {
;     ...
;                 for (int mm = 0; mm < 2; ++mm) {
;                     const int m = mp * 2 + mm;
;                     const int row = row0 + ai * HALF + m * 16;
;                     float s = 0.f;
; #pragma unroll
;                     for (int bj = 0; bj < 2; ++bj) {
;                         u32x4* px = (u32x4*)(X + (size_t)row * DM + col0 + bj * HALF);
;                         float xo[8]; unpack8(xin[mm][bj], xo);
;                         const f32x4 a0 = acc[ai][bj][m][0] + pv[mm][bj][0], a1 = acc[ai][bj][m][1] + pv[mm][bj][1];
;                         u32x4 w;
;                         w.x = cvt_pk(xo[0] + scale * a0[0], xo[1] + scale * a0[1]); w.y = cvt_pk(xo[2] + scale * a0[2], xo[3] + scale * a0[3]);
;                         w.z = cvt_pk(xo[4] + scale * a1[0], xo[5] + scale * a1[1]); w.w = cvt_pk(xo[6] + scale * a1[2], xo[7] + scale * a1[3]);
;                         *px = w;
;                         float xn[8]; unpack8(w, xn);
; #pragma unroll
;                         for (int j = 0; j < 8; ++j) s += xn[j] * xn[j];
;                     }
;                     s += __shfl_xor(s, 16); s += __shfl_xor(s, 32);
;                     if (fq == 0) unsafeAtomicAdd(ssn + row, s);
	v_lshlrev_b32_e32 v90, 16, v112
	v_and_b32_e32 v91, 0xffff0000, v112
	v_lshlrev_b32_e32 v92, 16, v113
	v_and_b32_e32 v93, 0xffff0000, v113
	v_lshlrev_b32_e32 v94, 16, v114
	v_and_b32_e32 v95, 0xffff0000, v114
	v_lshlrev_b32_e32 v109, 16, v115
	v_and_b32_e32 v110, 0xffff0000, v115
	v_pk_add_f32 v[88:89], v[82:83], 0 op_sel_hi:[1,0]
	v_pk_add_f32 v[82:83], v[80:81], 0 op_sel_hi:[1,0]
	v_fmac_f32_e32 v90, 0.5, v84
	v_fmac_f32_e32 v91, 0.5, v85
	v_cvt_pk_bf16_f32 v80, v90, v91
	v_fmac_f32_e32 v92, 0.5, v86
	v_lshlrev_b32_e32 v84, 16, v80
	v_fmac_f32_e32 v93, 0.5, v87
	v_cvt_pk_bf16_f32 v81, v92, v93
	v_fmac_f32_e32 v94, 0.5, v82
	v_fmac_f32_e32 v95, 0.5, v83
	v_cvt_pk_bf16_f32 v82, v94, v95
	v_fmac_f32_e32 v109, 0.5, v88
	v_fmac_f32_e32 v110, 0.5, v89
	v_cvt_pk_bf16_f32 v83, v109, v110
	global_store_dwordx4 v[106:107], v[80:83], off offset:256
	v_fmac_f32_e32 v108, v84, v84
	v_lshlrev_b32_e32 v85, 16, v81
	v_and_b32_e32 v80, 0xffff0000, v80
	v_fmac_f32_e32 v108, v80, v80
	v_and_b32_e32 v81, 0xffff0000, v81
	v_fmac_f32_e32 v108, v85, v85
	v_lshlrev_b32_e32 v86, 16, v82
	v_fmac_f32_e32 v108, v81, v81
	v_and_b32_e32 v82, 0xffff0000, v82
	v_fmac_f32_e32 v108, v86, v86
	v_lshlrev_b32_e32 v87, 16, v83
	v_fmac_f32_e32 v108, v82, v82
	v_and_b32_e32 v83, 0xffff0000, v83
	v_fmac_f32_e32 v108, v87, v87
	v_fmac_f32_e32 v108, v83, v83
	v_mov_b32_e32 v80, v108
	s_nop 1
	v_permlane16_swap_b32_e32 v80, v108
	s_waitcnt lgkmcnt(0)
	v_add_f32_e32 v80, v108, v80
	v_mov_b32_e32 v81, v80
	s_nop 1
	v_permlane32_swap_b32_e32 v81, v80
	s_and_saveexec_b64 s[16:17], s[8:9]
	s_cbranch_execz .LBB0_462
	s_waitcnt lgkmcnt(0)
	v_add_f32_e32 v82, v80, v81
	v_lshl_add_u64 v[80:81], v[138:139], 2, s[6:7]
	global_atomic_add_f32 v[80:81], v82, off offset:128
.LBB0_462:
	s_or_b64 exec, exec, s[16:17]
	s_waitcnt vmcnt(3)
	v_lshlrev_b32_e32 v82, 16, v100
	v_and_b32_e32 v83, 0xffff0000, v100
	v_lshlrev_b32_e32 v84, 16, v101
	v_pk_add_f32 v[78:79], v[78:79], 0 op_sel_hi:[1,0]
	v_pk_add_f32 v[76:77], v[76:77], 0 op_sel_hi:[1,0]
	v_and_b32_e32 v85, 0xffff0000, v101
	s_waitcnt lgkmcnt(0)
	v_pk_add_f32 v[80:81], v[74:75], 0 op_sel_hi:[1,0]
	v_pk_add_f32 v[74:75], v[72:73], 0 op_sel_hi:[1,0]
	v_fmac_f32_e32 v82, 0.5, v76
	v_fmac_f32_e32 v83, 0.5, v77
	v_cvt_pk_bf16_f32 v72, v82, v83
	v_fmac_f32_e32 v84, 0.5, v78
	v_and_b32_e32 v77, 0xffff0000, v72
	v_fmac_f32_e32 v85, 0.5, v79
	v_cvt_pk_bf16_f32 v73, v84, v85
	v_lshlrev_b32_e32 v76, 16, v72
	v_mul_f32_e32 v84, v77, v77
	v_lshlrev_b32_e32 v78, 16, v73
	v_fmac_f32_e32 v84, v76, v76
	v_lshlrev_b32_e32 v86, 16, v102
	v_and_b32_e32 v87, 0xffff0000, v102
	v_lshlrev_b32_e32 v88, 16, v103
	v_and_b32_e32 v79, 0xffff0000, v73
	v_fmac_f32_e32 v84, v78, v78
	v_and_b32_e32 v89, 0xffff0000, v103
	v_fmac_f32_e32 v86, 0.5, v74
	v_fmac_f32_e32 v87, 0.5, v75
	v_cvt_pk_bf16_f32 v74, v86, v87
	v_fmac_f32_e32 v88, 0.5, v80
	v_lshlrev_b32_e32 v80, 16, v74
	v_fmac_f32_e32 v84, v79, v79
	v_fmac_f32_e32 v89, 0.5, v81
	v_and_b32_e32 v81, 0xffff0000, v74
	v_fmac_f32_e32 v84, v80, v80
	v_cvt_pk_bf16_f32 v75, v88, v89
	v_fmac_f32_e32 v84, v81, v81
	v_lshlrev_b32_e32 v82, 16, v75
	v_and_b32_e32 v83, 0xffff0000, v75
	v_fmac_f32_e32 v84, v82, v82
	s_waitcnt vmcnt(2)
	v_lshlrev_b32_e32 v78, 16, v96
	v_and_b32_e32 v79, 0xffff0000, v96
	v_lshlrev_b32_e32 v82, 16, v98
	v_pk_add_f32 v[68:69], v[68:69], 0 op_sel_hi:[1,0]
	v_pk_add_f32 v[64:65], v[64:65], 0 op_sel_hi:[1,0]
	v_fmac_f32_e32 v84, v83, v83
	v_and_b32_e32 v83, 0xffff0000, v98
	v_pk_add_f32 v[76:77], v[66:67], 0 op_sel_hi:[1,0]
	v_fmac_f32_e32 v78, 0.5, v68
	v_fmac_f32_e32 v79, 0.5, v69
	v_cvt_pk_bf16_f32 v66, v78, v79
	v_fmac_f32_e32 v82, 0.5, v64
	v_lshlrev_b32_e32 v64, 16, v66
	v_lshlrev_b32_e32 v80, 16, v97
	v_and_b32_e32 v81, 0xffff0000, v97
	v_pk_add_f32 v[70:71], v[70:71], 0 op_sel_hi:[1,0]
	v_fmac_f32_e32 v83, 0.5, v65
	v_and_b32_e32 v65, 0xffff0000, v66
	v_fmac_f32_e32 v84, v64, v64
	v_fmac_f32_e32 v80, 0.5, v70
	v_fmac_f32_e32 v81, 0.5, v71
	v_cvt_pk_bf16_f32 v67, v80, v81
	v_fmac_f32_e32 v84, v65, v65
	v_lshlrev_b32_e32 v70, 16, v67
	v_lshlrev_b32_e32 v85, 16, v99
	v_and_b32_e32 v71, 0xffff0000, v67
	v_fmac_f32_e32 v84, v70, v70
	v_and_b32_e32 v86, 0xffff0000, v99
	v_cvt_pk_bf16_f32 v68, v82, v83
	v_fmac_f32_e32 v85, 0.5, v76
	v_lshlrev_b32_e32 v76, 16, v68
	v_fmac_f32_e32 v84, v71, v71
	v_fmac_f32_e32 v86, 0.5, v77
	v_and_b32_e32 v77, 0xffff0000, v68
	v_fmac_f32_e32 v84, v76, v76
	v_cvt_pk_bf16_f32 v69, v85, v86
	v_fmac_f32_e32 v84, v77, v77
	v_lshlrev_b32_e32 v78, 16, v69
	v_and_b32_e32 v79, 0xffff0000, v69
	v_fmac_f32_e32 v84, v78, v78
	v_fmac_f32_e32 v84, v79, v79
	v_mov_b32_e32 v64, v84
	s_nop 1
	v_permlane16_swap_b32_e32 v64, v84
	v_lshl_add_u64 v[70:71], s[28:29], 0, v[104:105]
	v_lshl_add_u64 v[70:71], v[140:141], 1, v[70:71]
	global_store_dwordx4 v[70:71], v[72:75], off
	global_store_dwordx4 v[70:71], v[66:69], off offset:256
	s_waitcnt lgkmcnt(0)
	v_add_f32_e32 v64, v84, v64
	v_mov_b32_e32 v65, v64
	s_nop 1
	v_permlane32_swap_b32_e32 v65, v64
	s_and_saveexec_b64 s[16:17], s[8:9]
	s_cbranch_execz .LBB0_464
	s_waitcnt lgkmcnt(0)
	v_add_f32_e32 v66, v64, v65
	v_lshl_add_u64 v[64:65], v[138:139], 2, s[6:7]
	global_atomic_add_f32 v[64:65], v66, off offset:192
;     __device__ __forceinline__ void operator()(const f32x4 (&acc)[2][2][4][2], const Unit& u, int wr, int wc, int fr, int fq) const {
;     ...
;                 u32x4 xin[2][2];
; #pragma unroll
;                 for (int mm = 0; mm < 2; ++mm)
; #pragma unroll
;                     for (int bj = 0; bj < 2; ++bj) xin[mm][bj] = *(const u32x4*)(X + (size_t)(row0 + ai * HALF + (mp * 2 + mm) * 16) * DM + col0 + bj * HALF);
;                 f32x4 pv[2][2][2];
; #pragma unroll
;                 for (int mm = 0; mm < 2; ++mm)
; #pragma unroll
;                     for (int bj = 0; bj < 2; ++bj)
; #pragma unroll
;                         for (int n = 0; n < 2; ++n) pv[mm][bj][n] = (f32x4){0.f, 0.f, 0.f, 0.f};
;                 if (src) {
;                     u32x4 pc[2][2];
;     ...
;                     asm volatile("global_load_dwordx4 %0, %4, off sc1\n\tglobal_load_dwordx4 %1, %5, off sc1\n\tglobal_load_dwordx4 %2, %6, off sc1\n\tglobal_load_dwordx4 %3, %7, off sc1\n\ts_waitcnt vmcnt(0)"
;                                  : "=&v"(pc[0][0]), "=&v"(pc[0][1]), "=&v"(pc[1][0]), "=&v"(pc[1][1])
;                                  : "v"(src + CI(0, 0)), "v"(src + CI(0, 1)), "v"(src + CI(1, 0)), "v"(src + CI(1, 1))
;                                  : "memory");
;     ...
; #pragma unroll
;                     for (int mm = 0; mm < 2; ++mm)
; #pragma unroll
;                         for (int bj = 0; bj < 2; ++bj) { float f[8]; unpack8(pc[mm][bj], f); pv[mm][bj][0] = (f32x4){f[0], f[1], f[2], f[3]}; pv[mm][bj][1] = (f32x4){f[4], f[5], f[6], f[7]}; }
;                 }
; #pragma unroll
;                 for (int mm = 0; mm < 2; ++mm) {
;                     const int m = mp * 2 + mm;
;                     const int row = row0 + ai * HALF + m * 16;
;                     float s = 0.f;
; #pragma unroll
;                     for (int bj = 0; bj < 2; ++bj) {
;                         u32x4* px = (u32x4*)(X + (size_t)row * DM + col0 + bj * HALF);
;                         float xo[8]; unpack8(xin[mm][bj], xo);
;                         const f32x4 a0 = acc[ai][bj][m][0] + pv[mm][bj][0], a1 = acc[ai][bj][m][1] + pv[mm][bj][1];
;                         u32x4 w;
;                         w.x = cvt_pk(xo[0] + scale * a0[0], xo[1] + scale * a0[1]); w.y = cvt_pk(xo[2] + scale * a0[2], xo[3] + scale * a0[3]);
.LBB0_464:
	s_or_b64 exec, exec, s[16:17]
	s_mov_b64 s[16:17], 0x40000
	v_lshl_add_u64 v[74:75], v[154:155], 0, s[16:17]
	s_waitcnt lgkmcnt(0)
	v_lshl_add_u64 v[64:65], v[142:143], 0, v[74:75]
	global_load_dwordx4 v[76:79], v[64:65], off
	global_load_dwordx4 v[80:83], v[64:65], off offset:256
	s_mov_b64 s[16:17], 0x48000
	v_lshl_add_u64 v[72:73], v[154:155], 0, s[16:17]
	v_lshl_add_u64 v[64:65], v[142:143], 0, v[72:73]
	global_load_dwordx4 v[68:71], v[64:65], off
	s_nop 0
	global_load_dwordx4 v[64:67], v[64:65], off offset:256
	v_lshl_add_u64 v[74:75], s[28:29], 0, v[74:75]
	v_pk_add_f32 v[60:61], v[60:61], 0 op_sel_hi:[1,0]
	v_lshl_add_u64 v[74:75], v[140:141], 1, v[74:75]
	v_pk_add_f32 v[62:63], v[62:63], 0 op_sel_hi:[1,0]
	v_pk_add_f32 v[52:53], v[52:53], 0 op_sel_hi:[1,0]
	v_pk_add_f32 v[54:55], v[54:55], 0 op_sel_hi:[1,0]
	s_waitcnt vmcnt(3)
	v_lshlrev_b32_e32 v84, 16, v76
	v_and_b32_e32 v85, 0xffff0000, v76
	v_lshlrev_b32_e32 v86, 16, v77
	v_and_b32_e32 v87, 0xffff0000, v77
	v_lshlrev_b32_e32 v88, 16, v78
	v_and_b32_e32 v78, 0xffff0000, v78
	v_lshlrev_b32_e32 v89, 16, v79
	v_and_b32_e32 v79, 0xffff0000, v79
	v_pk_add_f32 v[76:77], v[58:59], 0 op_sel_hi:[1,0]
	v_pk_add_f32 v[58:59], v[56:57], 0 op_sel_hi:[1,0]
	v_fmac_f32_e32 v84, 0.5, v60
	v_fmac_f32_e32 v85, 0.5, v61
	v_cvt_pk_bf16_f32 v56, v84, v85
	v_fmac_f32_e32 v86, 0.5, v62
	v_fmac_f32_e32 v87, 0.5, v63
	v_cvt_pk_bf16_f32 v57, v86, v87
	v_fmac_f32_e32 v88, 0.5, v58
	v_fmac_f32_e32 v78, 0.5, v59
	v_cvt_pk_bf16_f32 v58, v88, v78
	v_fmac_f32_e32 v89, 0.5, v76
	v_fmac_f32_e32 v79, 0.5, v77
	v_cvt_pk_bf16_f32 v59, v89, v79
	global_store_dwordx4 v[74:75], v[56:59], off
	v_lshlrev_b32_e32 v60, 16, v56
	v_lshlrev_b32_e32 v61, 16, v57
	v_and_b32_e32 v56, 0xffff0000, v56
	v_mul_f32_e32 v76, v56, v56
	v_fmac_f32_e32 v76, v60, v60
	v_and_b32_e32 v57, 0xffff0000, v57
	v_fmac_f32_e32 v76, v61, v61
	v_lshlrev_b32_e32 v62, 16, v58
	v_fmac_f32_e32 v76, v57, v57
	v_and_b32_e32 v58, 0xffff0000, v58
	v_fmac_f32_e32 v76, v62, v62
	v_lshlrev_b32_e32 v63, 16, v59
	v_fmac_f32_e32 v76, v58, v58
	v_and_b32_e32 v59, 0xffff0000, v59
	v_fmac_f32_e32 v76, v63, v63
	v_fmac_f32_e32 v76, v59, v59
	s_waitcnt vmcnt(3)
	v_lshlrev_b32_e32 v58, 16, v80
	v_and_b32_e32 v59, 0xffff0000, v80
	v_lshlrev_b32_e32 v60, 16, v81
	v_and_b32_e32 v61, 0xffff0000, v81
	v_lshlrev_b32_e32 v62, 16, v82
	v_and_b32_e32 v63, 0xffff0000, v82
	v_lshlrev_b32_e32 v77, 16, v83
	v_and_b32_e32 v78, 0xffff0000, v83
	v_pk_add_f32 v[56:57], v[50:51], 0 op_sel_hi:[1,0]
	v_pk_add_f32 v[50:51], v[48:49], 0 op_sel_hi:[1,0]
	v_fmac_f32_e32 v58, 0.5, v52
	v_fmac_f32_e32 v59, 0.5, v53
	v_cvt_pk_bf16_f32 v48, v58, v59
	v_fmac_f32_e32 v60, 0.5, v54
	v_lshlrev_b32_e32 v52, 16, v48
	v_fmac_f32_e32 v61, 0.5, v55
	v_cvt_pk_bf16_f32 v49, v60, v61
	v_fmac_f32_e32 v62, 0.5, v50
	v_fmac_f32_e32 v63, 0.5, v51
	v_cvt_pk_bf16_f32 v50, v62, v63
	v_fmac_f32_e32 v77, 0.5, v56
	v_fmac_f32_e32 v78, 0.5, v57
	v_cvt_pk_bf16_f32 v51, v77, v78
	global_store_dwordx4 v[74:75], v[48:51], off offset:256
	v_fmac_f32_e32 v76, v52, v52
	v_lshlrev_b32_e32 v53, 16, v49
	v_and_b32_e32 v48, 0xffff0000, v48
	v_fmac_f32_e32 v76, v48, v48
	v_and_b32_e32 v49, 0xffff0000, v49
	v_fmac_f32_e32 v76, v53, v53
	v_lshlrev_b32_e32 v54, 16, v50
	v_fmac_f32_e32 v76, v49, v49
	v_and_b32_e32 v50, 0xffff0000, v50
	v_fmac_f32_e32 v76, v54, v54
	v_lshlrev_b32_e32 v55, 16, v51
	v_fmac_f32_e32 v76, v50, v50
	v_and_b32_e32 v51, 0xffff0000, v51
	v_fmac_f32_e32 v76, v55, v55
	v_fmac_f32_e32 v76, v51, v51
	v_mov_b32_e32 v48, v76
	s_nop 1
	v_permlane16_swap_b32_e32 v48, v76
	s_waitcnt lgkmcnt(0)
	v_add_f32_e32 v48, v76, v48
	v_mov_b32_e32 v49, v48
	s_nop 1
	v_permlane32_swap_b32_e32 v49, v48
	s_and_saveexec_b64 s[16:17], s[8:9]
	s_cbranch_execz .LBB0_466
	s_waitcnt lgkmcnt(0)
	v_add_f32_e32 v50, v48, v49
	v_lshl_add_u64 v[48:49], v[138:139], 2, s[6:7]
	global_atomic_add_f32 v[48:49], v50, off offset:512
.LBB0_466:
	s_or_b64 exec, exec, s[16:17]
	s_waitcnt vmcnt(3)
	v_lshlrev_b32_e32 v50, 16, v68
	v_and_b32_e32 v51, 0xffff0000, v68
	v_lshlrev_b32_e32 v52, 16, v69
	v_pk_add_f32 v[46:47], v[46:47], 0 op_sel_hi:[1,0]
	v_pk_add_f32 v[44:45], v[44:45], 0 op_sel_hi:[1,0]
	v_and_b32_e32 v53, 0xffff0000, v69
	s_waitcnt lgkmcnt(0)
	v_pk_add_f32 v[48:49], v[42:43], 0 op_sel_hi:[1,0]
	v_pk_add_f32 v[42:43], v[40:41], 0 op_sel_hi:[1,0]
	v_fmac_f32_e32 v50, 0.5, v44
	v_fmac_f32_e32 v51, 0.5, v45
	v_cvt_pk_bf16_f32 v40, v50, v51
	v_fmac_f32_e32 v52, 0.5, v46
	v_and_b32_e32 v45, 0xffff0000, v40
	v_fmac_f32_e32 v53, 0.5, v47
	v_cvt_pk_bf16_f32 v41, v52, v53
	v_lshlrev_b32_e32 v44, 16, v40
	v_mul_f32_e32 v52, v45, v45
	v_lshlrev_b32_e32 v46, 16, v41
	v_fmac_f32_e32 v52, v44, v44
	v_lshlrev_b32_e32 v54, 16, v70
	v_and_b32_e32 v55, 0xffff0000, v70
	v_lshlrev_b32_e32 v56, 16, v71
	v_and_b32_e32 v47, 0xffff0000, v41
	v_fmac_f32_e32 v52, v46, v46
	v_and_b32_e32 v57, 0xffff0000, v71
	v_fmac_f32_e32 v54, 0.5, v42
	v_fmac_f32_e32 v55, 0.5, v43
	v_cvt_pk_bf16_f32 v42, v54, v55
	v_fmac_f32_e32 v56, 0.5, v48
	v_lshlrev_b32_e32 v48, 16, v42
	v_fmac_f32_e32 v52, v47, v47
	v_fmac_f32_e32 v57, 0.5, v49
	v_and_b32_e32 v49, 0xffff0000, v42
	v_fmac_f32_e32 v52, v48, v48
	v_cvt_pk_bf16_f32 v43, v56, v57
	v_fmac_f32_e32 v52, v49, v49
	v_lshlrev_b32_e32 v50, 16, v43
	v_and_b32_e32 v51, 0xffff0000, v43
	v_fmac_f32_e32 v52, v50, v50
	s_waitcnt vmcnt(2)
;     __device__ __forceinline__ void operator()(const f32x4 (&acc)[2][2][4][2], const Unit& u, int wr, int wc, int fr, int fq) const {
;     ...
;                 u32x4 xin[2][2];
; #pragma unroll
;                 for (int mm = 0; mm < 2; ++mm)
; #pragma unroll
;                     for (int bj = 0; bj < 2; ++bj) xin[mm][bj] = *(const u32x4*)(X + (size_t)(row0 + ai * HALF + (mp * 2 + mm) * 16) * DM + col0 + bj * HALF);
;                 f32x4 pv[2][2][2];
; #pragma unroll
;                 for (int mm = 0; mm < 2; ++mm)
; #pragma unroll
;                     for (int bj = 0; bj < 2; ++bj)
; #pragma unroll
;                         for (int n = 0; n < 2; ++n) pv[mm][bj][n] = (f32x4){0.f, 0.f, 0.f, 0.f};
;                 if (src) {
;                     u32x4 pc[2][2];
;     ...
;                     asm volatile("global_load_dwordx4 %0, %4, off sc1\n\tglobal_load_dwordx4 %1, %5, off sc1\n\tglobal_load_dwordx4 %2, %6, off sc1\n\tglobal_load_dwordx4 %3, %7, off sc1\n\ts_waitcnt vmcnt(0)"
;                                  : "=&v"(pc[0][0]), "=&v"(pc[0][1]), "=&v"(pc[1][0]), "=&v"(pc[1][1])
;                                  : "v"(src + CI(0, 0)), "v"(src + CI(0, 1)), "v"(src + CI(1, 0)), "v"(src + CI(1, 1))
;                                  : "memory");
;     ...
; #pragma unroll
;                     for (int mm = 0; mm < 2; ++mm)
; #pragma unroll
;                         for (int bj = 0; bj < 2; ++bj) { float f[8]; unpack8(pc[mm][bj], f); pv[mm][bj][0] = (f32x4){f[0], f[1], f[2], f[3]}; pv[mm][bj][1] = (f32x4){f[4], f[5], f[6], f[7]}; }
;                 }
; #pragma unroll
;                 for (int mm = 0; mm < 2; ++mm) {
;                     const int m = mp * 2 + mm;
;                     const int row = row0 + ai * HALF + m * 16;
;                     float s = 0.f;
; #pragma unroll
;                     for (int bj = 0; bj < 2; ++bj) {
;                         u32x4* px = (u32x4*)(X + (size_t)row * DM + col0 + bj * HALF);
;                         float xo[8]; unpack8(xin[mm][bj], xo);
;                         const f32x4 a0 = acc[ai][bj][m][0] + pv[mm][bj][0], a1 = acc[ai][bj][m][1] + pv[mm][bj][1];
;                         u32x4 w;
;                         w.x = cvt_pk(xo[0] + scale * a0[0], xo[1] + scale * a0[1]); w.y = cvt_pk(xo[2] + scale * a0[2], xo[3] + scale * a0[3]);
	v_lshlrev_b32_e32 v46, 16, v64
	v_and_b32_e32 v47, 0xffff0000, v64
	v_lshlrev_b32_e32 v50, 16, v66
	v_pk_add_f32 v[36:37], v[36:37], 0 op_sel_hi:[1,0]
	v_pk_add_f32 v[32:33], v[32:33], 0 op_sel_hi:[1,0]
	v_fmac_f32_e32 v52, v51, v51
	v_and_b32_e32 v51, 0xffff0000, v66
	v_pk_add_f32 v[44:45], v[34:35], 0 op_sel_hi:[1,0]
	v_fmac_f32_e32 v46, 0.5, v36
	v_fmac_f32_e32 v47, 0.5, v37
	v_cvt_pk_bf16_f32 v34, v46, v47
	v_fmac_f32_e32 v50, 0.5, v32
	v_lshlrev_b32_e32 v32, 16, v34
	v_lshlrev_b32_e32 v48, 16, v65
	v_and_b32_e32 v49, 0xffff0000, v65
	v_pk_add_f32 v[38:39], v[38:39], 0 op_sel_hi:[1,0]
	v_fmac_f32_e32 v51, 0.5, v33
	v_and_b32_e32 v33, 0xffff0000, v34
	v_fmac_f32_e32 v52, v32, v32
	v_fmac_f32_e32 v48, 0.5, v38
	v_fmac_f32_e32 v49, 0.5, v39
	v_cvt_pk_bf16_f32 v35, v48, v49
	v_fmac_f32_e32 v52, v33, v33
	v_lshlrev_b32_e32 v38, 16, v35
	v_lshlrev_b32_e32 v53, 16, v67
	v_and_b32_e32 v39, 0xffff0000, v35
	v_fmac_f32_e32 v52, v38, v38
	v_and_b32_e32 v54, 0xffff0000, v67
	v_cvt_pk_bf16_f32 v36, v50, v51
	v_fmac_f32_e32 v53, 0.5, v44
	v_lshlrev_b32_e32 v44, 16, v36
	v_fmac_f32_e32 v52, v39, v39
	v_fmac_f32_e32 v54, 0.5, v45
	v_and_b32_e32 v45, 0xffff0000, v36
	v_fmac_f32_e32 v52, v44, v44
	v_cvt_pk_bf16_f32 v37, v53, v54
	v_fmac_f32_e32 v52, v45, v45
	v_lshlrev_b32_e32 v46, 16, v37
	v_and_b32_e32 v47, 0xffff0000, v37
	v_fmac_f32_e32 v52, v46, v46
	v_fmac_f32_e32 v52, v47, v47
	v_mov_b32_e32 v32, v52
	s_nop 1
	v_permlane16_swap_b32_e32 v32, v52
	v_lshl_add_u64 v[38:39], s[28:29], 0, v[72:73]
	v_lshl_add_u64 v[38:39], v[140:141], 1, v[38:39]
	global_store_dwordx4 v[38:39], v[40:43], off
	global_store_dwordx4 v[38:39], v[34:37], off offset:256
	s_waitcnt lgkmcnt(0)
	v_add_f32_e32 v32, v52, v32
	v_mov_b32_e32 v33, v32
	s_nop 1
	v_permlane32_swap_b32_e32 v33, v32
	s_and_saveexec_b64 s[16:17], s[8:9]
	s_cbranch_execz .LBB0_468
	s_waitcnt lgkmcnt(0)
	v_add_f32_e32 v34, v32, v33
	v_lshl_add_u64 v[32:33], v[138:139], 2, s[6:7]
	global_atomic_add_f32 v[32:33], v34, off offset:576
.LBB0_468:
	s_or_b64 exec, exec, s[16:17]
	s_mov_b64 s[16:17], 0x50000
	v_lshl_add_u64 v[42:43], v[154:155], 0, s[16:17]
	s_waitcnt lgkmcnt(0)
	v_lshl_add_u64 v[32:33], v[142:143], 0, v[42:43]
	global_load_dwordx4 v[44:47], v[32:33], off
	global_load_dwordx4 v[48:51], v[32:33], off offset:256
	s_mov_b64 s[16:17], 0x58000
	v_lshl_add_u64 v[40:41], v[154:155], 0, s[16:17]
	v_lshl_add_u64 v[32:33], v[142:143], 0, v[40:41]
	global_load_dwordx4 v[36:39], v[32:33], off
	s_nop 0
	global_load_dwordx4 v[32:35], v[32:33], off offset:256
	v_lshl_add_u64 v[42:43], s[28:29], 0, v[42:43]
	v_pk_add_f32 v[28:29], v[28:29], 0 op_sel_hi:[1,0]
	v_lshl_add_u64 v[42:43], v[140:141], 1, v[42:43]
	v_pk_add_f32 v[30:31], v[30:31], 0 op_sel_hi:[1,0]
	v_pk_add_f32 v[20:21], v[20:21], 0 op_sel_hi:[1,0]
	v_pk_add_f32 v[22:23], v[22:23], 0 op_sel_hi:[1,0]
	s_waitcnt vmcnt(3)
	v_lshlrev_b32_e32 v52, 16, v44
	v_and_b32_e32 v53, 0xffff0000, v44
	v_lshlrev_b32_e32 v54, 16, v45
	v_and_b32_e32 v55, 0xffff0000, v45
	v_lshlrev_b32_e32 v56, 16, v46
	v_and_b32_e32 v46, 0xffff0000, v46
	v_lshlrev_b32_e32 v57, 16, v47
	v_and_b32_e32 v47, 0xffff0000, v47
	v_pk_add_f32 v[44:45], v[26:27], 0 op_sel_hi:[1,0]
	v_pk_add_f32 v[26:27], v[24:25], 0 op_sel_hi:[1,0]
	v_fmac_f32_e32 v52, 0.5, v28
	v_fmac_f32_e32 v53, 0.5, v29
	v_cvt_pk_bf16_f32 v24, v52, v53
	v_fmac_f32_e32 v54, 0.5, v30
	v_fmac_f32_e32 v55, 0.5, v31
	v_cvt_pk_bf16_f32 v25, v54, v55
	v_fmac_f32_e32 v56, 0.5, v26
	v_fmac_f32_e32 v46, 0.5, v27
	v_cvt_pk_bf16_f32 v26, v56, v46
	v_fmac_f32_e32 v57, 0.5, v44
	v_fmac_f32_e32 v47, 0.5, v45
	v_cvt_pk_bf16_f32 v27, v57, v47
	global_store_dwordx4 v[42:43], v[24:27], off
	v_lshlrev_b32_e32 v28, 16, v24
	v_lshlrev_b32_e32 v29, 16, v25
	v_and_b32_e32 v24, 0xffff0000, v24
	v_mul_f32_e32 v44, v24, v24
	v_fmac_f32_e32 v44, v28, v28
	v_and_b32_e32 v25, 0xffff0000, v25
	v_fmac_f32_e32 v44, v29, v29
	v_lshlrev_b32_e32 v30, 16, v26
	v_fmac_f32_e32 v44, v25, v25
	v_and_b32_e32 v26, 0xffff0000, v26
	v_fmac_f32_e32 v44, v30, v30
	v_lshlrev_b32_e32 v31, 16, v27
	v_fmac_f32_e32 v44, v26, v26
	v_and_b32_e32 v27, 0xffff0000, v27
	v_fmac_f32_e32 v44, v31, v31
	v_fmac_f32_e32 v44, v27, v27
	s_waitcnt vmcnt(3)
	v_lshlrev_b32_e32 v26, 16, v48
	v_and_b32_e32 v27, 0xffff0000, v48
	v_lshlrev_b32_e32 v28, 16, v49
	v_and_b32_e32 v29, 0xffff0000, v49
	v_lshlrev_b32_e32 v30, 16, v50
	v_and_b32_e32 v31, 0xffff0000, v50
	v_lshlrev_b32_e32 v45, 16, v51
	v_and_b32_e32 v46, 0xffff0000, v51
	v_pk_add_f32 v[24:25], v[18:19], 0 op_sel_hi:[1,0]
	v_pk_add_f32 v[18:19], v[16:17], 0 op_sel_hi:[1,0]
	v_fmac_f32_e32 v26, 0.5, v20
	v_fmac_f32_e32 v27, 0.5, v21
	v_cvt_pk_bf16_f32 v16, v26, v27
	v_fmac_f32_e32 v28, 0.5, v22
	v_lshlrev_b32_e32 v20, 16, v16
	v_fmac_f32_e32 v29, 0.5, v23
	v_cvt_pk_bf16_f32 v17, v28, v29
	v_fmac_f32_e32 v30, 0.5, v18
	v_fmac_f32_e32 v31, 0.5, v19
	v_cvt_pk_bf16_f32 v18, v30, v31
	v_fmac_f32_e32 v45, 0.5, v24
	v_fmac_f32_e32 v46, 0.5, v25
	v_cvt_pk_bf16_f32 v19, v45, v46
	global_store_dwordx4 v[42:43], v[16:19], off offset:256
	v_fmac_f32_e32 v44, v20, v20
	v_lshlrev_b32_e32 v21, 16, v17
	v_and_b32_e32 v16, 0xffff0000, v16
	v_fmac_f32_e32 v44, v16, v16
	v_and_b32_e32 v17, 0xffff0000, v17
	v_fmac_f32_e32 v44, v21, v21
	v_lshlrev_b32_e32 v22, 16, v18
	v_fmac_f32_e32 v44, v17, v17
	v_and_b32_e32 v18, 0xffff0000, v18
	v_fmac_f32_e32 v44, v22, v22
	v_lshlrev_b32_e32 v23, 16, v19
	v_fmac_f32_e32 v44, v18, v18
	v_and_b32_e32 v19, 0xffff0000, v19
	v_fmac_f32_e32 v44, v23, v23
	v_fmac_f32_e32 v44, v19, v19
	v_mov_b32_e32 v16, v44
	s_nop 1
	v_permlane16_swap_b32_e32 v16, v44
	s_waitcnt lgkmcnt(0)
	v_add_f32_e32 v16, v44, v16
	v_mov_b32_e32 v17, v16
	s_nop 1
	v_permlane32_swap_b32_e32 v17, v16
	s_and_saveexec_b64 s[16:17], s[8:9]
	s_cbranch_execz .LBB0_470
	s_waitcnt lgkmcnt(0)
	v_add_f32_e32 v18, v16, v17
	v_lshl_add_u64 v[16:17], v[138:139], 2, s[6:7]
	global_atomic_add_f32 v[16:17], v18, off offset:640
; DI unsigned cvt_pk(float lo, float hi) { unsigned r; asm("v_cvt_pk_bf16_f32 %0, %1, %2" : "=v"(r) : "v"(lo), "v"(hi)); return r; }
;     __device__ __forceinline__ void operator()(const f32x4 (&acc)[2][2][4][2], const Unit& u, int wr, int wc, int fr, int fq) const {
;     ...
;                 for (int mm = 0; mm < 2; ++mm) {
;                     const int m = mp * 2 + mm;
;                     const int row = row0 + ai * HALF + m * 16;
;                     float s = 0.f;
; #pragma unroll
;                     for (int bj = 0; bj < 2; ++bj) {
;                         u32x4* px = (u32x4*)(X + (size_t)row * DM + col0 + bj * HALF);
;                         float xo[8]; unpack8(xin[mm][bj], xo);
;                         const f32x4 a0 = acc[ai][bj][m][0] + pv[mm][bj][0], a1 = acc[ai][bj][m][1] + pv[mm][bj][1];
;                         u32x4 w;
;                         w.x = cvt_pk(xo[0] + scale * a0[0], xo[1] + scale * a0[1]); w.y = cvt_pk(xo[2] + scale * a0[2], xo[3] + scale * a0[3]);
;                         w.z = cvt_pk(xo[4] + scale * a1[0], xo[5] + scale * a1[1]); w.w = cvt_pk(xo[6] + scale * a1[2], xo[7] + scale * a1[3]);
;                         *px = w;
;                         float xn[8]; unpack8(w, xn);
; #pragma unroll
;                         for (int j = 0; j < 8; ++j) s += xn[j] * xn[j];
;                     }
;                     s += __shfl_xor(s, 16); s += __shfl_xor(s, 32);
;                     if (fq == 0) unsafeAtomicAdd(ssn + row, s);
.LBB0_470:
	s_or_b64 exec, exec, s[16:17]
	s_waitcnt vmcnt(3)
	v_lshlrev_b32_e32 v18, 16, v36
	v_and_b32_e32 v19, 0xffff0000, v36
	v_lshlrev_b32_e32 v20, 16, v37
	v_pk_add_f32 v[14:15], v[14:15], 0 op_sel_hi:[1,0]
	v_pk_add_f32 v[12:13], v[12:13], 0 op_sel_hi:[1,0]
	v_and_b32_e32 v21, 0xffff0000, v37
	s_waitcnt lgkmcnt(0)
	v_pk_add_f32 v[16:17], v[10:11], 0 op_sel_hi:[1,0]
	v_pk_add_f32 v[10:11], v[8:9], 0 op_sel_hi:[1,0]
	v_fmac_f32_e32 v18, 0.5, v12
	v_fmac_f32_e32 v19, 0.5, v13
	v_cvt_pk_bf16_f32 v8, v18, v19
	v_fmac_f32_e32 v20, 0.5, v14
	v_and_b32_e32 v13, 0xffff0000, v8
	v_fmac_f32_e32 v21, 0.5, v15
	v_cvt_pk_bf16_f32 v9, v20, v21
	v_lshlrev_b32_e32 v12, 16, v8
	v_mul_f32_e32 v20, v13, v13
	v_lshlrev_b32_e32 v14, 16, v9
	v_fmac_f32_e32 v20, v12, v12
	v_lshlrev_b32_e32 v22, 16, v38
	v_and_b32_e32 v23, 0xffff0000, v38
	v_lshlrev_b32_e32 v24, 16, v39
	v_and_b32_e32 v15, 0xffff0000, v9
	v_fmac_f32_e32 v20, v14, v14
	v_and_b32_e32 v25, 0xffff0000, v39
	v_fmac_f32_e32 v22, 0.5, v10
	v_fmac_f32_e32 v23, 0.5, v11
	v_cvt_pk_bf16_f32 v10, v22, v23
	v_fmac_f32_e32 v24, 0.5, v16
	v_lshlrev_b32_e32 v16, 16, v10
	v_fmac_f32_e32 v20, v15, v15
	v_fmac_f32_e32 v25, 0.5, v17
	v_and_b32_e32 v17, 0xffff0000, v10
	v_fmac_f32_e32 v20, v16, v16
	v_cvt_pk_bf16_f32 v11, v24, v25
	v_fmac_f32_e32 v20, v17, v17
	v_lshlrev_b32_e32 v18, 16, v11
	v_and_b32_e32 v19, 0xffff0000, v11
	v_fmac_f32_e32 v20, v18, v18
	s_waitcnt vmcnt(2)
	v_lshlrev_b32_e32 v14, 16, v32
	v_and_b32_e32 v15, 0xffff0000, v32
	v_lshlrev_b32_e32 v18, 16, v34
	v_pk_add_f32 v[4:5], v[4:5], 0 op_sel_hi:[1,0]
	v_pk_add_f32 v[0:1], v[0:1], 0 op_sel_hi:[1,0]
	v_fmac_f32_e32 v20, v19, v19
	v_and_b32_e32 v19, 0xffff0000, v34
	v_pk_add_f32 v[12:13], v[2:3], 0 op_sel_hi:[1,0]
	v_fmac_f32_e32 v14, 0.5, v4
	v_fmac_f32_e32 v15, 0.5, v5
	v_cvt_pk_bf16_f32 v2, v14, v15
	v_fmac_f32_e32 v18, 0.5, v0
	v_lshlrev_b32_e32 v0, 16, v2
	v_lshlrev_b32_e32 v16, 16, v33
	v_and_b32_e32 v17, 0xffff0000, v33
	v_pk_add_f32 v[6:7], v[6:7], 0 op_sel_hi:[1,0]
	v_fmac_f32_e32 v19, 0.5, v1
	v_and_b32_e32 v1, 0xffff0000, v2
	v_fmac_f32_e32 v20, v0, v0
	v_fmac_f32_e32 v16, 0.5, v6
	v_fmac_f32_e32 v17, 0.5, v7
	v_cvt_pk_bf16_f32 v3, v16, v17
	v_fmac_f32_e32 v20, v1, v1
	v_lshlrev_b32_e32 v6, 16, v3
	v_lshlrev_b32_e32 v21, 16, v35
	v_and_b32_e32 v7, 0xffff0000, v3
	v_fmac_f32_e32 v20, v6, v6
	v_and_b32_e32 v22, 0xffff0000, v35
	v_cvt_pk_bf16_f32 v4, v18, v19
	v_fmac_f32_e32 v21, 0.5, v12
	v_lshlrev_b32_e32 v12, 16, v4
	v_fmac_f32_e32 v20, v7, v7
	v_fmac_f32_e32 v22, 0.5, v13
	v_and_b32_e32 v13, 0xffff0000, v4
	v_fmac_f32_e32 v20, v12, v12
	v_cvt_pk_bf16_f32 v5, v21, v22
	v_fmac_f32_e32 v20, v13, v13
	v_lshlrev_b32_e32 v14, 16, v5
	v_and_b32_e32 v15, 0xffff0000, v5
	v_fmac_f32_e32 v20, v14, v14
	v_fmac_f32_e32 v20, v15, v15
	v_mov_b32_e32 v0, v20
	s_nop 1
	v_permlane16_swap_b32_e32 v0, v20
	v_lshl_add_u64 v[6:7], s[28:29], 0, v[40:41]
	v_lshl_add_u64 v[6:7], v[140:141], 1, v[6:7]
	global_store_dwordx4 v[6:7], v[8:11], off
	global_store_dwordx4 v[6:7], v[2:5], off offset:256
	s_waitcnt lgkmcnt(0)
	v_add_f32_e32 v0, v20, v0
	v_mov_b32_e32 v1, v0
	s_nop 1
	v_permlane32_swap_b32_e32 v1, v0
	s_and_saveexec_b64 s[16:17], s[8:9]
	s_cbranch_execz .LBB0_472
	s_waitcnt lgkmcnt(0)
	v_add_f32_e32 v2, v0, v1
	v_lshl_add_u64 v[0:1], v[138:139], 2, s[6:7]
	global_atomic_add_f32 v[0:1], v2, off offset:704

; DI unsigned cvt_pk(float lo, float hi) { unsigned r; asm("v_cvt_pk_bf16_f32 %0, %1, %2" : "=v"(r) : "v"(lo), "v"(hi)); return r; }
;     __device__ __forceinline__ void operator()(const f32x4 (&acc)[2][2][4][2], const Unit& u, int wr, int wc, int fr, int fq) const {
;     ...
;                 for (int mm = 0; mm < 2; ++mm) {
;                     const int m = mp * 2 + mm;
;                     const int row = row0 + ai * HALF + m * 16;
;                     float s = 0.f;
; #pragma unroll
;                     for (int bj = 0; bj < 2; ++bj) {
;                         u32x4* px = (u32x4*)(X + (size_t)row * DM + col0 + bj * HALF);
;                         float xo[8]; unpack8(xin[mm][bj], xo);
;                         const f32x4 a0 = acc[ai][bj][m][0] + pv[mm][bj][0], a1 = acc[ai][bj][m][1] + pv[mm][bj][1];
;                         u32x4 w;
;                         w.x = cvt_pk(xo[0] + scale * a0[0], xo[1] + scale * a0[1]); w.y = cvt_pk(xo[2] + scale * a0[2], xo[3] + scale * a0[3]);
;                         w.z = cvt_pk(xo[4] + scale * a1[0], xo[5] + scale * a1[1]); w.w = cvt_pk(xo[6] + scale * a1[2], xo[7] + scale * a1[3]);
;                         *px = w;
;                         float xn[8]; unpack8(w, xn);
; #pragma unroll
;                         for (int j = 0; j < 8; ++j) s += xn[j] * xn[j];
;                     }
;                     s += __shfl_xor(s, 16); s += __shfl_xor(s, 32);
;                     if (fq == 0) unsafeAtomicAdd(ssn + row, s);
.LBB0_1161:
	s_or_b64 exec, exec, s[16:17]
	s_waitcnt vmcnt(0)
	v_lshlrev_b32_e32 v210, 16, v140
	v_and_b32_e32 v211, 0xffff0000, v140
	v_lshlrev_b32_e32 v214, 16, v141
	v_and_b32_e32 v215, 0xffff0000, v141
	v_pk_add_f32 v[140:141], v[124:125], v[206:207]
	v_lshlrev_b32_e32 v237, 16, v142
	v_and_b32_e32 v238, 0xffff0000, v142
	v_lshlrev_b32_e32 v244, 16, v143
	v_and_b32_e32 v245, 0xffff0000, v143
	v_pk_add_f32 v[142:143], v[126:127], v[208:209]
	v_add_f32_e32 v140, v140, v210
	v_add_f32_e32 v141, v141, v211
	v_pk_add_f32 v[202:203], v[120:121], v[202:203]
	v_cvt_pk_bf16_f32 v140, v140, v141
	v_add_f32_e32 v141, v142, v214
	v_add_f32_e32 v142, v143, v215
	v_pk_add_f32 v[204:205], v[122:123], v[204:205]
	v_cvt_pk_bf16_f32 v141, v141, v142
	v_add_f32_e32 v142, v202, v237
	v_add_f32_e32 v143, v203, v238
	v_cvt_pk_bf16_f32 v142, v142, v143
	v_add_f32_e32 v143, v204, v244
	v_add_f32_e32 v202, v205, v245
	v_and_b32_e32 v203, 0xffff0000, v140
	v_cvt_pk_bf16_f32 v143, v143, v202
	v_lshlrev_b32_e32 v202, 16, v140
	v_mul_f32_e32 v203, v203, v203
	v_lshlrev_b32_e32 v204, 16, v141
	v_fmac_f32_e32 v203, v202, v202
	v_and_b32_e32 v205, 0xffff0000, v141
	v_fmac_f32_e32 v203, v204, v204
	v_lshlrev_b32_e32 v206, 16, v142
	v_fmac_f32_e32 v203, v205, v205
	v_and_b32_e32 v207, 0xffff0000, v142
	v_fmac_f32_e32 v203, v206, v206
	v_lshlrev_b32_e32 v208, 16, v143
	v_fmac_f32_e32 v203, v207, v207
	v_and_b32_e32 v209, 0xffff0000, v143
	v_fmac_f32_e32 v203, v208, v208
	v_lshlrev_b32_e32 v202, 16, v136
	v_and_b32_e32 v204, 0xffff0000, v136
	v_lshlrev_b32_e32 v205, 16, v137
	v_and_b32_e32 v206, 0xffff0000, v137
	v_pk_add_f32 v[136:137], v[94:95], v[200:201]
	v_fmac_f32_e32 v203, v209, v209
	v_lshlrev_b32_e32 v207, 16, v138
	v_and_b32_e32 v208, 0xffff0000, v138
	v_lshlrev_b32_e32 v209, 16, v139
	v_and_b32_e32 v210, 0xffff0000, v139
	v_pk_add_f32 v[138:139], v[92:93], v[198:199]
	v_pk_add_f32 v[198:199], v[90:91], v[196:197]
	v_pk_add_f32 v[196:197], v[88:89], v[194:195]
	v_add_f32_e32 v136, v136, v205
	v_add_f32_e32 v137, v137, v206
	v_cvt_pk_bf16_f32 v195, v136, v137
	v_add_f32_e32 v136, v196, v207
	v_add_f32_e32 v137, v197, v208
	v_cvt_pk_bf16_f32 v196, v136, v137
	v_add_f32_e32 v136, v198, v209
	v_add_f32_e32 v138, v138, v202
	v_add_f32_e32 v139, v139, v204
	v_cvt_pk_bf16_f32 v194, v138, v139
	v_add_f32_e32 v137, v199, v210
	v_cvt_pk_bf16_f32 v197, v136, v137
	v_lshlrev_b32_e32 v136, 16, v194
	v_and_b32_e32 v137, 0xffff0000, v194
	v_fmac_f32_e32 v203, v136, v136
	v_lshlrev_b32_e32 v138, 16, v195
	v_fmac_f32_e32 v203, v137, v137
	v_and_b32_e32 v139, 0xffff0000, v195
	v_fmac_f32_e32 v203, v138, v138
	v_lshlrev_b32_e32 v198, 16, v196
	v_fmac_f32_e32 v203, v139, v139
	v_and_b32_e32 v137, 64, v221
	v_and_b32_e32 v199, 0xffff0000, v196
	v_fmac_f32_e32 v203, v198, v198
	v_xor_b32_e32 v136, 16, v221
	v_add_u32_e32 v137, 64, v137
	v_lshlrev_b32_e32 v200, 16, v197
	v_fmac_f32_e32 v203, v199, v199
	v_cmp_lt_i32_e64 s[16:17], v136, v137
	v_and_b32_e32 v201, 0xffff0000, v197
	v_fmac_f32_e32 v203, v200, v200
	v_cndmask_b32_e64 v136, v221, v136, s[16:17]
	v_fmac_f32_e32 v203, v201, v201
	v_lshlrev_b32_e32 v237, 2, v136
	v_mov_b32_e32 v136, v203
	s_nop 1
	v_permlane16_swap_b32_e32 v136, v203
	v_xor_b32_e32 v138, 32, v221
	v_cmp_lt_i32_e64 s[16:17], v138, v137
	s_waitcnt lgkmcnt(0)
	v_add_f32_e32 v136, v203, v136
	v_cndmask_b32_e64 v137, v221, v138, s[16:17]
	v_lshlrev_b32_e32 v238, 2, v137
	v_mov_b32_e32 v137, v136
	s_nop 1
	v_permlane32_swap_b32_e32 v137, v136
	v_lshl_add_u64 v[138:139], s[36:37], 0, v[174:175]
	v_lshl_add_u64 v[138:139], v[168:169], 1, v[138:139]
	global_store_dwordx4 v[138:139], v[140:143], off
	global_store_dwordx4 v[138:139], v[194:197], off offset:256
	s_and_saveexec_b64 s[16:17], s[12:13]
	s_cbranch_execz .LBB0_1163
	s_waitcnt lgkmcnt(0)
	v_add_f32_e32 v138, v136, v137
	v_lshl_add_u64 v[136:137], v[166:167], 2, s[4:5]
	global_atomic_add_f32 v[136:137], v138, off
; DI unsigned cvt_pk(float lo, float hi) { unsigned r; asm("v_cvt_pk_bf16_f32 %0, %1, %2" : "=v"(r) : "v"(lo), "v"(hi)); return r; }
;     __device__ __forceinline__ void operator()(const f32x4 (&acc)[2][2][4][2], const Unit& u, int wr, int wc, int fr, int fq) const {
;     ...
;                 for (int mm = 0; mm < 2; ++mm) {
;                     const int m = mp * 2 + mm;
;                     const int row = row0 + ai * HALF + m * 16;
;                     float s = 0.f;
; #pragma unroll
;                     for (int bj = 0; bj < 2; ++bj) {
;                         u32x4* px = (u32x4*)(X + (size_t)row * DM + col0 + bj * HALF);
;                         float xo[8]; unpack8(xin[mm][bj], xo);
;                         const f32x4 a0 = acc[ai][bj][m][0] + pv[mm][bj][0], a1 = acc[ai][bj][m][1] + pv[mm][bj][1];
;                         u32x4 w;
;                         w.x = cvt_pk(xo[0] + scale * a0[0], xo[1] + scale * a0[1]); w.y = cvt_pk(xo[2] + scale * a0[2], xo[3] + scale * a0[3]);
;                         w.z = cvt_pk(xo[4] + scale * a1[0], xo[5] + scale * a1[1]); w.w = cvt_pk(xo[6] + scale * a1[2], xo[7] + scale * a1[3]);
;                         *px = w;
;                         float xn[8]; unpack8(w, xn);
; #pragma unroll
;                         for (int j = 0; j < 8; ++j) s += xn[j] * xn[j];
;                     }
;                     s += __shfl_xor(s, 16); s += __shfl_xor(s, 32);
;                     if (fq == 0) unsafeAtomicAdd(ssn + row, s);
.LBB0_1163:
	s_or_b64 exec, exec, s[16:17]
	v_lshlrev_b32_e32 v140, 16, v132
	v_and_b32_e32 v141, 0xffff0000, v132
	v_lshlrev_b32_e32 v142, 16, v133
	v_and_b32_e32 v143, 0xffff0000, v133
	v_pk_add_f32 v[132:133], v[116:117], v[190:191]
	v_lshlrev_b32_e32 v194, 16, v134
	v_and_b32_e32 v195, 0xffff0000, v134
	v_lshlrev_b32_e32 v196, 16, v135
	v_and_b32_e32 v197, 0xffff0000, v135
	v_pk_add_f32 v[134:135], v[118:119], v[192:193]
	v_add_f32_e32 v132, v132, v140
	v_add_f32_e32 v133, v133, v141
	v_pk_add_f32 v[138:139], v[112:113], v[186:187]
	v_cvt_pk_bf16_f32 v132, v132, v133
	v_add_f32_e32 v133, v134, v142
	v_add_f32_e32 v134, v135, v143
	s_waitcnt lgkmcnt(0)
	v_pk_add_f32 v[136:137], v[114:115], v[188:189]
	v_cvt_pk_bf16_f32 v133, v133, v134
	v_add_f32_e32 v134, v138, v194
	v_add_f32_e32 v135, v139, v195
	v_cvt_pk_bf16_f32 v134, v134, v135
	v_add_f32_e32 v135, v136, v196
	v_add_f32_e32 v136, v137, v197
	v_and_b32_e32 v137, 0xffff0000, v132
	v_cvt_pk_bf16_f32 v135, v135, v136
	v_lshlrev_b32_e32 v136, 16, v132
	v_mul_f32_e32 v186, v137, v137
	v_lshlrev_b32_e32 v138, 16, v133
	v_fmac_f32_e32 v186, v136, v136
	v_and_b32_e32 v139, 0xffff0000, v133
	v_fmac_f32_e32 v186, v138, v138
	v_lshlrev_b32_e32 v140, 16, v134
	v_fmac_f32_e32 v186, v139, v139
	v_and_b32_e32 v141, 0xffff0000, v134
	v_fmac_f32_e32 v186, v140, v140
	v_lshlrev_b32_e32 v142, 16, v135
	v_fmac_f32_e32 v186, v141, v141
	v_and_b32_e32 v143, 0xffff0000, v135
	v_fmac_f32_e32 v186, v142, v142
	v_fmac_f32_e32 v186, v143, v143
	v_lshlrev_b32_e32 v136, 16, v128
	v_and_b32_e32 v137, 0xffff0000, v128
	v_lshlrev_b32_e32 v142, 16, v129
	v_and_b32_e32 v143, 0xffff0000, v129
	v_pk_add_f32 v[128:129], v[86:87], v[184:185]
	v_lshlrev_b32_e32 v187, 16, v130
	v_and_b32_e32 v188, 0xffff0000, v130
	v_lshlrev_b32_e32 v189, 16, v131
	v_and_b32_e32 v190, 0xffff0000, v131
	v_pk_add_f32 v[130:131], v[84:85], v[182:183]
	v_pk_add_f32 v[138:139], v[80:81], v[178:179]
	v_add_f32_e32 v128, v128, v142
	v_pk_add_f32 v[140:141], v[82:83], v[180:181]
	v_add_f32_e32 v131, v131, v137
	v_add_f32_e32 v129, v129, v143
	v_cvt_pk_bf16_f32 v137, v128, v129
	v_add_f32_e32 v128, v138, v187
	v_add_f32_e32 v129, v139, v188
	v_cvt_pk_bf16_f32 v138, v128, v129
	v_add_f32_e32 v128, v140, v189
	v_add_f32_e32 v130, v130, v136
	v_cvt_pk_bf16_f32 v136, v130, v131
	v_add_f32_e32 v129, v141, v190
	v_cvt_pk_bf16_f32 v139, v128, v129
	v_lshlrev_b32_e32 v128, 16, v136
	v_and_b32_e32 v129, 0xffff0000, v136
	v_fmac_f32_e32 v186, v128, v128
	v_lshlrev_b32_e32 v130, 16, v137
	v_fmac_f32_e32 v186, v129, v129
	v_and_b32_e32 v131, 0xffff0000, v137
	v_fmac_f32_e32 v186, v130, v130
	v_lshlrev_b32_e32 v140, 16, v138
	v_fmac_f32_e32 v186, v131, v131
	v_and_b32_e32 v141, 0xffff0000, v138
	v_fmac_f32_e32 v186, v140, v140
	v_lshlrev_b32_e32 v142, 16, v139
	v_fmac_f32_e32 v186, v141, v141
	v_and_b32_e32 v143, 0xffff0000, v139
	v_fmac_f32_e32 v186, v142, v142
	v_fmac_f32_e32 v186, v143, v143
	v_mov_b32_e32 v128, v186
	s_nop 1
	v_permlane16_swap_b32_e32 v128, v186
	v_lshl_add_u64 v[130:131], s[36:37], 0, v[176:177]
	v_lshl_add_u64 v[130:131], v[168:169], 1, v[130:131]
	global_store_dwordx4 v[130:131], v[132:135], off
	global_store_dwordx4 v[130:131], v[136:139], off offset:256
	s_waitcnt lgkmcnt(0)
	v_add_f32_e32 v128, v186, v128
	v_mov_b32_e32 v129, v128
	s_nop 1
	v_permlane32_swap_b32_e32 v129, v128
	s_and_saveexec_b64 s[16:17], s[12:13]
	s_cbranch_execz .LBB0_1165
	s_waitcnt lgkmcnt(0)
	v_add_f32_e32 v130, v128, v129
	v_lshl_add_u64 v[128:129], v[166:167], 2, s[4:5]
	global_atomic_add_f32 v[128:129], v130, off offset:64

;     __device__ __forceinline__ void operator()(const f32x4 (&acc)[2][2][4][2], const Unit& u, int wr, int wc, int fr, int fq) const {
;     ...
;                 u32x4 xin[2][2];
; #pragma unroll
;                 for (int mm = 0; mm < 2; ++mm)
; #pragma unroll
;                     for (int bj = 0; bj < 2; ++bj) xin[mm][bj] = *(const u32x4*)(X + (size_t)(row0 + ai * HALF + (mp * 2 + mm) * 16) * DM + col0 + bj * HALF);
;                 f32x4 pv[2][2][2];
; #pragma unroll
;                 for (int mm = 0; mm < 2; ++mm)
; #pragma unroll
;                     for (int bj = 0; bj < 2; ++bj)
; #pragma unroll
;                         for (int n = 0; n < 2; ++n) pv[mm][bj][n] = (f32x4){0.f, 0.f, 0.f, 0.f};
;                 if (src) {
;                     u32x4 pc[2][2];
;     ...
;                     asm volatile("global_load_dwordx4 %0, %4, off sc1\n\tglobal_load_dwordx4 %1, %5, off sc1\n\tglobal_load_dwordx4 %2, %6, off sc1\n\tglobal_load_dwordx4 %3, %7, off sc1\n\ts_waitcnt vmcnt(0)"
;                                  : "=&v"(pc[0][0]), "=&v"(pc[0][1]), "=&v"(pc[1][0]), "=&v"(pc[1][1])
;                                  : "v"(src + CI(0, 0)), "v"(src + CI(0, 1)), "v"(src + CI(1, 0)), "v"(src + CI(1, 1))
;                                  : "memory");
;     ...
; #pragma unroll
;                     for (int mm = 0; mm < 2; ++mm)
; #pragma unroll
;                         for (int bj = 0; bj < 2; ++bj) { float f[8]; unpack8(pc[mm][bj], f); pv[mm][bj][0] = (f32x4){f[0], f[1], f[2], f[3]}; pv[mm][bj][1] = (f32x4){f[4], f[5], f[6], f[7]}; }
;                 }
; #pragma unroll
;                 for (int mm = 0; mm < 2; ++mm) {
;                     const int m = mp * 2 + mm;
;                     const int row = row0 + ai * HALF + m * 16;
;                     float s = 0.f;
; #pragma unroll
;                     for (int bj = 0; bj < 2; ++bj) {
;                         u32x4* px = (u32x4*)(X + (size_t)row * DM + col0 + bj * HALF);
;                         float xo[8]; unpack8(xin[mm][bj], xo);
;                         const f32x4 a0 = acc[ai][bj][m][0] + pv[mm][bj][0], a1 = acc[ai][bj][m][1] + pv[mm][bj][1];
;                         u32x4 w;
;                         w.x = cvt_pk(xo[0] + scale * a0[0], xo[1] + scale * a0[1]); w.y = cvt_pk(xo[2] + scale * a0[2], xo[3] + scale * a0[3]);
.LBB0_1167:
	s_or_b64 exec, exec, s[16:17]
	s_waitcnt vmcnt(0)
	s_mov_b64 s[38:39], 0x40000
	v_lshl_add_u64 v[250:251], v[174:175], 0, s[38:39]
	v_lshl_add_u64 v[250:251], v[172:173], 0, v[250:251]
	global_load_dwordx4 v[80:83], v[250:251], off
	global_load_dwordx4 v[84:87], v[250:251], off offset:256
	s_mov_b64 s[38:39], 0x48000
	v_lshl_add_u64 v[252:253], v[174:175], 0, s[38:39]
	v_lshl_add_u64 v[252:253], v[172:173], 0, v[252:253]
	global_load_dwordx4 v[88:91], v[252:253], off
	global_load_dwordx4 v[92:95], v[252:253], off offset:256
	s_and_saveexec_b64 s[16:17], vcc
	s_mov_b64 s[38:39], 0x2000
	v_lshl_add_u64 v[250:251], v[170:171], 0, s[38:39]
	global_load_dwordx4 v[112:115], v[250:251], off sc1
	s_mov_b64 s[38:39], 0x3000
	v_lshl_add_u64 v[252:253], v[170:171], 0, s[38:39]
	global_load_dwordx4 v[116:119], v[252:253], off sc1
	s_mov_b64 s[38:39], 0x2400
	v_lshl_add_u64 v[250:251], v[170:171], 0, s[38:39]
	global_load_dwordx4 v[120:123], v[250:251], off sc1
	s_mov_b64 s[38:39], 0x3400
	v_lshl_add_u64 v[252:253], v[170:171], 0, s[38:39]
	global_load_dwordx4 v[124:127], v[252:253], off sc1
	s_or_b64 exec, exec, s[16:17]
	v_lshlrev_b32_e32 v214, 16, v140
	v_and_b32_e32 v215, 0xffff0000, v140
	v_lshlrev_b32_e32 v244, 16, v141
	v_and_b32_e32 v245, 0xffff0000, v141
	v_pk_add_f32 v[140:141], v[108:109], v[208:209]
	v_lshlrev_b32_e32 v246, 16, v142
	v_and_b32_e32 v247, 0xffff0000, v142
	v_lshlrev_b32_e32 v248, 16, v143
	v_and_b32_e32 v249, 0xffff0000, v143
	v_pk_add_f32 v[142:143], v[110:111], v[210:211]
	v_add_f32_e32 v140, v140, v214
	v_add_f32_e32 v141, v141, v215
	v_pk_add_f32 v[204:205], v[104:105], v[204:205]
	v_cvt_pk_bf16_f32 v140, v140, v141
	v_add_f32_e32 v141, v142, v244
	v_add_f32_e32 v142, v143, v245
	v_pk_add_f32 v[206:207], v[106:107], v[206:207]
	v_cvt_pk_bf16_f32 v141, v141, v142
	v_add_f32_e32 v142, v204, v246
	v_add_f32_e32 v143, v205, v247
	v_cvt_pk_bf16_f32 v142, v142, v143
	v_add_f32_e32 v143, v206, v248
	v_add_f32_e32 v204, v207, v249
	v_and_b32_e32 v205, 0xffff0000, v140
	v_cvt_pk_bf16_f32 v143, v143, v204
	v_lshlrev_b32_e32 v204, 16, v140
	v_mul_f32_e32 v205, v205, v205
	v_lshlrev_b32_e32 v206, 16, v141
	v_fmac_f32_e32 v205, v204, v204
	v_and_b32_e32 v207, 0xffff0000, v141
	v_fmac_f32_e32 v205, v206, v206
	v_lshlrev_b32_e32 v208, 16, v142
	v_fmac_f32_e32 v205, v207, v207
	v_and_b32_e32 v209, 0xffff0000, v142
	v_fmac_f32_e32 v205, v208, v208
	v_lshlrev_b32_e32 v210, 16, v143
	v_fmac_f32_e32 v205, v209, v209
	v_and_b32_e32 v211, 0xffff0000, v143
	v_fmac_f32_e32 v205, v210, v210
	v_lshlrev_b32_e32 v204, 16, v136
	v_and_b32_e32 v206, 0xffff0000, v136
	v_lshlrev_b32_e32 v207, 16, v137
	v_and_b32_e32 v208, 0xffff0000, v137
	v_pk_add_f32 v[136:137], v[78:79], v[202:203]
	v_fmac_f32_e32 v205, v211, v211
	v_lshlrev_b32_e32 v209, 16, v138
	v_and_b32_e32 v210, 0xffff0000, v138
	v_lshlrev_b32_e32 v211, 16, v139
	v_and_b32_e32 v214, 0xffff0000, v139
	v_pk_add_f32 v[138:139], v[76:77], v[200:201]
	v_pk_add_f32 v[200:201], v[74:75], v[198:199]
	v_pk_add_f32 v[198:199], v[72:73], v[196:197]
	v_add_f32_e32 v136, v136, v207
	v_add_f32_e32 v137, v137, v208
	v_cvt_pk_bf16_f32 v197, v136, v137
	v_add_f32_e32 v136, v198, v209
	v_add_f32_e32 v137, v199, v210
	v_cvt_pk_bf16_f32 v198, v136, v137
	v_add_f32_e32 v136, v200, v211
	v_add_f32_e32 v138, v138, v204
	v_add_f32_e32 v139, v139, v206
	v_cvt_pk_bf16_f32 v196, v138, v139
	v_add_f32_e32 v137, v201, v214
	v_cvt_pk_bf16_f32 v199, v136, v137
	v_lshlrev_b32_e32 v136, 16, v196
	v_and_b32_e32 v137, 0xffff0000, v196
	v_fmac_f32_e32 v205, v136, v136
	v_lshlrev_b32_e32 v138, 16, v197
	v_fmac_f32_e32 v205, v137, v137
	v_and_b32_e32 v139, 0xffff0000, v197
	v_fmac_f32_e32 v205, v138, v138
	v_lshlrev_b32_e32 v200, 16, v198
	v_fmac_f32_e32 v205, v139, v139
	v_and_b32_e32 v201, 0xffff0000, v198
	v_fmac_f32_e32 v205, v200, v200
	v_lshlrev_b32_e32 v202, 16, v199
	v_fmac_f32_e32 v205, v201, v201
	v_and_b32_e32 v203, 0xffff0000, v199
	v_fmac_f32_e32 v205, v202, v202
	v_fmac_f32_e32 v205, v203, v203
	v_mov_b32_e32 v136, v205
	s_nop 1
	v_permlane16_swap_b32_e32 v136, v205
	v_lshl_add_u64 v[138:139], s[36:37], 0, v[186:187]
	v_lshl_add_u64 v[138:139], v[168:169], 1, v[138:139]
	global_store_dwordx4 v[138:139], v[140:143], off
	global_store_dwordx4 v[138:139], v[196:199], off offset:256
	s_waitcnt lgkmcnt(0)
	v_add_f32_e32 v136, v205, v136
	v_mov_b32_e32 v137, v136
	s_nop 1
	v_permlane32_swap_b32_e32 v137, v136
	s_and_saveexec_b64 s[16:17], s[12:13]
	s_cbranch_execz .LBB0_1169
	s_waitcnt lgkmcnt(0)
	v_add_f32_e32 v138, v136, v137
	v_lshl_add_u64 v[136:137], v[166:167], 2, s[4:5]
	global_atomic_add_f32 v[136:137], v138, off offset:128
; DI unsigned cvt_pk(float lo, float hi) { unsigned r; asm("v_cvt_pk_bf16_f32 %0, %1, %2" : "=v"(r) : "v"(lo), "v"(hi)); return r; }
;     __device__ __forceinline__ void operator()(const f32x4 (&acc)[2][2][4][2], const Unit& u, int wr, int wc, int fr, int fq) const {
;     ...
;                 for (int mm = 0; mm < 2; ++mm) {
;                     const int m = mp * 2 + mm;
;                     const int row = row0 + ai * HALF + m * 16;
;                     float s = 0.f;
; #pragma unroll
;                     for (int bj = 0; bj < 2; ++bj) {
;                         u32x4* px = (u32x4*)(X + (size_t)row * DM + col0 + bj * HALF);
;                         float xo[8]; unpack8(xin[mm][bj], xo);
;                         const f32x4 a0 = acc[ai][bj][m][0] + pv[mm][bj][0], a1 = acc[ai][bj][m][1] + pv[mm][bj][1];
;                         u32x4 w;
;                         w.x = cvt_pk(xo[0] + scale * a0[0], xo[1] + scale * a0[1]); w.y = cvt_pk(xo[2] + scale * a0[2], xo[3] + scale * a0[3]);
;                         w.z = cvt_pk(xo[4] + scale * a1[0], xo[5] + scale * a1[1]); w.w = cvt_pk(xo[6] + scale * a1[2], xo[7] + scale * a1[3]);
;                         *px = w;
;                         float xn[8]; unpack8(w, xn);
; #pragma unroll
;                         for (int j = 0; j < 8; ++j) s += xn[j] * xn[j];
;                     }
;                     s += __shfl_xor(s, 16); s += __shfl_xor(s, 32);
;                     if (fq == 0) unsafeAtomicAdd(ssn + row, s);
.LBB0_1169:
	s_or_b64 exec, exec, s[16:17]
	v_lshlrev_b32_e32 v140, 16, v132
	v_and_b32_e32 v141, 0xffff0000, v132
	v_lshlrev_b32_e32 v142, 16, v133
	v_and_b32_e32 v143, 0xffff0000, v133
	v_pk_add_f32 v[132:133], v[100:101], v[192:193]
	v_lshlrev_b32_e32 v186, 16, v134
	v_and_b32_e32 v187, 0xffff0000, v134
	v_lshlrev_b32_e32 v196, 16, v135
	v_and_b32_e32 v197, 0xffff0000, v135
	v_pk_add_f32 v[134:135], v[102:103], v[194:195]
	v_add_f32_e32 v132, v132, v140
	v_add_f32_e32 v133, v133, v141
	v_pk_add_f32 v[138:139], v[96:97], v[188:189]
	v_cvt_pk_bf16_f32 v132, v132, v133
	v_add_f32_e32 v133, v134, v142
	v_add_f32_e32 v134, v135, v143
	s_waitcnt lgkmcnt(0)
	v_pk_add_f32 v[136:137], v[98:99], v[190:191]
	v_cvt_pk_bf16_f32 v133, v133, v134
	v_add_f32_e32 v134, v138, v186
	v_add_f32_e32 v135, v139, v187
	v_cvt_pk_bf16_f32 v134, v134, v135
	v_add_f32_e32 v135, v136, v196
	v_add_f32_e32 v136, v137, v197
	v_and_b32_e32 v137, 0xffff0000, v132
	v_cvt_pk_bf16_f32 v135, v135, v136
	v_lshlrev_b32_e32 v136, 16, v132
	v_mul_f32_e32 v186, v137, v137
	v_lshlrev_b32_e32 v138, 16, v133
	v_fmac_f32_e32 v186, v136, v136
	v_and_b32_e32 v139, 0xffff0000, v133
	v_fmac_f32_e32 v186, v138, v138
	v_lshlrev_b32_e32 v140, 16, v134
	v_fmac_f32_e32 v186, v139, v139
	v_and_b32_e32 v141, 0xffff0000, v134
	v_fmac_f32_e32 v186, v140, v140
	v_lshlrev_b32_e32 v142, 16, v135
	v_fmac_f32_e32 v186, v141, v141
	v_and_b32_e32 v143, 0xffff0000, v135
	v_fmac_f32_e32 v186, v142, v142
	v_fmac_f32_e32 v186, v143, v143
	v_lshlrev_b32_e32 v136, 16, v128
	v_and_b32_e32 v137, 0xffff0000, v128
	v_lshlrev_b32_e32 v142, 16, v129
	v_and_b32_e32 v143, 0xffff0000, v129
	v_pk_add_f32 v[128:129], v[70:71], v[184:185]
	v_lshlrev_b32_e32 v187, 16, v130
	v_and_b32_e32 v188, 0xffff0000, v130
	v_lshlrev_b32_e32 v189, 16, v131
	v_and_b32_e32 v190, 0xffff0000, v131
	v_pk_add_f32 v[130:131], v[68:69], v[182:183]
	v_pk_add_f32 v[138:139], v[64:65], v[178:179]
	v_add_f32_e32 v128, v128, v142
	v_pk_add_f32 v[140:141], v[66:67], v[180:181]
	v_add_f32_e32 v131, v131, v137
	v_add_f32_e32 v129, v129, v143
	v_cvt_pk_bf16_f32 v137, v128, v129
	v_add_f32_e32 v128, v138, v187
	v_add_f32_e32 v129, v139, v188
	v_cvt_pk_bf16_f32 v138, v128, v129
	v_add_f32_e32 v128, v140, v189
	v_add_f32_e32 v130, v130, v136
	v_cvt_pk_bf16_f32 v136, v130, v131
	v_add_f32_e32 v129, v141, v190
	v_cvt_pk_bf16_f32 v139, v128, v129
	v_lshlrev_b32_e32 v128, 16, v136
	v_and_b32_e32 v129, 0xffff0000, v136
	v_fmac_f32_e32 v186, v128, v128
	v_lshlrev_b32_e32 v130, 16, v137
	v_fmac_f32_e32 v186, v129, v129
	v_and_b32_e32 v131, 0xffff0000, v137
	v_fmac_f32_e32 v186, v130, v130
	v_lshlrev_b32_e32 v140, 16, v138
	v_fmac_f32_e32 v186, v131, v131
	v_and_b32_e32 v141, 0xffff0000, v138
	v_fmac_f32_e32 v186, v140, v140
	v_lshlrev_b32_e32 v142, 16, v139
	v_fmac_f32_e32 v186, v141, v141
	v_and_b32_e32 v143, 0xffff0000, v139
	v_fmac_f32_e32 v186, v142, v142
	v_fmac_f32_e32 v186, v143, v143
	v_mov_b32_e32 v128, v186
	s_nop 1
	v_permlane16_swap_b32_e32 v128, v186
	v_lshl_add_u64 v[130:131], s[36:37], 0, v[176:177]
	v_lshl_add_u64 v[130:131], v[168:169], 1, v[130:131]
	global_store_dwordx4 v[130:131], v[132:135], off
	global_store_dwordx4 v[130:131], v[136:139], off offset:256
	s_waitcnt lgkmcnt(0)
	v_add_f32_e32 v128, v186, v128
	v_mov_b32_e32 v129, v128
	s_nop 1
	v_permlane32_swap_b32_e32 v129, v128
	s_and_saveexec_b64 s[16:17], s[12:13]
	s_cbranch_execz .LBB0_1171
	s_waitcnt lgkmcnt(0)
	v_add_f32_e32 v130, v128, v129
	v_lshl_add_u64 v[128:129], v[166:167], 2, s[4:5]
	global_atomic_add_f32 v[128:129], v130, off offset:192

;     __device__ __forceinline__ void operator()(const f32x4 (&acc)[2][2][4][2], const Unit& u, int wr, int wc, int fr, int fq) const {
;     ...
;                 u32x4 xin[2][2];
; #pragma unroll
;                 for (int mm = 0; mm < 2; ++mm)
; #pragma unroll
;                     for (int bj = 0; bj < 2; ++bj) xin[mm][bj] = *(const u32x4*)(X + (size_t)(row0 + ai * HALF + (mp * 2 + mm) * 16) * DM + col0 + bj * HALF);
;                 f32x4 pv[2][2][2];
; #pragma unroll
;                 for (int mm = 0; mm < 2; ++mm)
; #pragma unroll
;                     for (int bj = 0; bj < 2; ++bj)
; #pragma unroll
;                         for (int n = 0; n < 2; ++n) pv[mm][bj][n] = (f32x4){0.f, 0.f, 0.f, 0.f};
;                 if (src) {
;                     u32x4 pc[2][2];
;     ...
;                     asm volatile("global_load_dwordx4 %0, %4, off sc1\n\tglobal_load_dwordx4 %1, %5, off sc1\n\tglobal_load_dwordx4 %2, %6, off sc1\n\tglobal_load_dwordx4 %3, %7, off sc1\n\ts_waitcnt vmcnt(0)"
;                                  : "=&v"(pc[0][0]), "=&v"(pc[0][1]), "=&v"(pc[1][0]), "=&v"(pc[1][1])
;                                  : "v"(src + CI(0, 0)), "v"(src + CI(0, 1)), "v"(src + CI(1, 0)), "v"(src + CI(1, 1))
;                                  : "memory");
;     ...
; #pragma unroll
;                     for (int mm = 0; mm < 2; ++mm)
; #pragma unroll
;                         for (int bj = 0; bj < 2; ++bj) { float f[8]; unpack8(pc[mm][bj], f); pv[mm][bj][0] = (f32x4){f[0], f[1], f[2], f[3]}; pv[mm][bj][1] = (f32x4){f[4], f[5], f[6], f[7]}; }
;                 }
; #pragma unroll
;                 for (int mm = 0; mm < 2; ++mm) {
;                     const int m = mp * 2 + mm;
;                     const int row = row0 + ai * HALF + m * 16;
;                     float s = 0.f;
; #pragma unroll
;                     for (int bj = 0; bj < 2; ++bj) {
;                         u32x4* px = (u32x4*)(X + (size_t)row * DM + col0 + bj * HALF);
;                         float xo[8]; unpack8(xin[mm][bj], xo);
;                         const f32x4 a0 = acc[ai][bj][m][0] + pv[mm][bj][0], a1 = acc[ai][bj][m][1] + pv[mm][bj][1];
;                         u32x4 w;
;                         w.x = cvt_pk(xo[0] + scale * a0[0], xo[1] + scale * a0[1]); w.y = cvt_pk(xo[2] + scale * a0[2], xo[3] + scale * a0[3]);
.LBB0_1173:
	s_or_b64 exec, exec, s[16:17]
	s_mov_b64 s[38:39], 0x50000
	v_lshl_add_u64 v[250:251], v[174:175], 0, s[38:39]
	v_lshl_add_u64 v[250:251], v[172:173], 0, v[250:251]
	global_load_dwordx4 v[64:67], v[250:251], off
	global_load_dwordx4 v[68:71], v[250:251], off offset:256
	s_mov_b64 s[38:39], 0x58000
	v_lshl_add_u64 v[252:253], v[174:175], 0, s[38:39]
	v_lshl_add_u64 v[252:253], v[172:173], 0, v[252:253]
	global_load_dwordx4 v[72:75], v[252:253], off
	global_load_dwordx4 v[76:79], v[252:253], off offset:256
	s_and_saveexec_b64 s[16:17], vcc
	s_mov_b64 s[38:39], 0x2800
	v_lshl_add_u64 v[250:251], v[170:171], 0, s[38:39]
	global_load_dwordx4 v[96:99], v[250:251], off sc1
	s_mov_b64 s[38:39], 0x3800
	v_lshl_add_u64 v[252:253], v[170:171], 0, s[38:39]
	global_load_dwordx4 v[100:103], v[252:253], off sc1
	s_mov_b64 s[38:39], 0x2c00
	v_lshl_add_u64 v[250:251], v[170:171], 0, s[38:39]
	global_load_dwordx4 v[104:107], v[250:251], off sc1
	s_mov_b64 s[38:39], 0x3c00
	v_lshl_add_u64 v[252:253], v[170:171], 0, s[38:39]
	global_load_dwordx4 v[108:111], v[252:253], off sc1
	s_or_b64 exec, exec, s[16:17]
	v_lshlrev_b32_e32 v214, 16, v140
	v_and_b32_e32 v215, 0xffff0000, v140
	v_lshlrev_b32_e32 v244, 16, v141
	v_and_b32_e32 v245, 0xffff0000, v141
	v_pk_add_f32 v[140:141], v[60:61], v[208:209]
	v_lshlrev_b32_e32 v246, 16, v142
	v_and_b32_e32 v247, 0xffff0000, v142
	v_lshlrev_b32_e32 v248, 16, v143
	v_and_b32_e32 v249, 0xffff0000, v143
	v_pk_add_f32 v[142:143], v[62:63], v[210:211]
	v_add_f32_e32 v140, v140, v214
	v_add_f32_e32 v141, v141, v215
	v_pk_add_f32 v[204:205], v[56:57], v[204:205]
	v_cvt_pk_bf16_f32 v140, v140, v141
	v_add_f32_e32 v141, v142, v244
	v_add_f32_e32 v142, v143, v245
	v_pk_add_f32 v[206:207], v[58:59], v[206:207]
	v_cvt_pk_bf16_f32 v141, v141, v142
	v_add_f32_e32 v142, v204, v246
	v_add_f32_e32 v143, v205, v247
	v_cvt_pk_bf16_f32 v142, v142, v143
	v_add_f32_e32 v143, v206, v248
	v_add_f32_e32 v204, v207, v249
	v_and_b32_e32 v205, 0xffff0000, v140
	v_cvt_pk_bf16_f32 v143, v143, v204
	v_lshlrev_b32_e32 v204, 16, v140
	v_mul_f32_e32 v205, v205, v205
	v_lshlrev_b32_e32 v206, 16, v141
	v_fmac_f32_e32 v205, v204, v204
	v_and_b32_e32 v207, 0xffff0000, v141
	v_fmac_f32_e32 v205, v206, v206
	v_lshlrev_b32_e32 v208, 16, v142
	v_fmac_f32_e32 v205, v207, v207
	v_and_b32_e32 v209, 0xffff0000, v142
	v_fmac_f32_e32 v205, v208, v208
	v_lshlrev_b32_e32 v210, 16, v143
	v_fmac_f32_e32 v205, v209, v209
	v_and_b32_e32 v211, 0xffff0000, v143
	v_fmac_f32_e32 v205, v210, v210
	v_lshlrev_b32_e32 v204, 16, v136
	v_and_b32_e32 v206, 0xffff0000, v136
	v_lshlrev_b32_e32 v207, 16, v137
	v_and_b32_e32 v208, 0xffff0000, v137
	v_pk_add_f32 v[136:137], v[30:31], v[202:203]
	v_fmac_f32_e32 v205, v211, v211
	v_lshlrev_b32_e32 v209, 16, v138
	v_and_b32_e32 v210, 0xffff0000, v138
	v_lshlrev_b32_e32 v211, 16, v139
	v_and_b32_e32 v214, 0xffff0000, v139
	v_pk_add_f32 v[138:139], v[28:29], v[200:201]
	v_pk_add_f32 v[200:201], v[26:27], v[198:199]
	v_pk_add_f32 v[198:199], v[24:25], v[196:197]
	v_add_f32_e32 v136, v136, v207
	v_add_f32_e32 v137, v137, v208
	v_cvt_pk_bf16_f32 v197, v136, v137
	v_add_f32_e32 v136, v198, v209
	v_add_f32_e32 v137, v199, v210
	v_cvt_pk_bf16_f32 v198, v136, v137
	v_add_f32_e32 v136, v200, v211
	v_add_f32_e32 v138, v138, v204
	v_add_f32_e32 v139, v139, v206
	v_cvt_pk_bf16_f32 v196, v138, v139
	v_add_f32_e32 v137, v201, v214
	v_cvt_pk_bf16_f32 v199, v136, v137
	v_lshlrev_b32_e32 v136, 16, v196
	v_and_b32_e32 v137, 0xffff0000, v196
	v_fmac_f32_e32 v205, v136, v136
	v_lshlrev_b32_e32 v138, 16, v197
	v_fmac_f32_e32 v205, v137, v137
	v_and_b32_e32 v139, 0xffff0000, v197
	v_fmac_f32_e32 v205, v138, v138
	v_lshlrev_b32_e32 v200, 16, v198
	v_fmac_f32_e32 v205, v139, v139
	v_and_b32_e32 v201, 0xffff0000, v198
	v_fmac_f32_e32 v205, v200, v200
	v_lshlrev_b32_e32 v202, 16, v199
	v_fmac_f32_e32 v205, v201, v201
	v_and_b32_e32 v203, 0xffff0000, v199
	v_fmac_f32_e32 v205, v202, v202
	v_fmac_f32_e32 v205, v203, v203
	v_mov_b32_e32 v136, v205
	s_nop 1
	v_permlane16_swap_b32_e32 v136, v205
	v_lshl_add_u64 v[138:139], s[36:37], 0, v[186:187]
	v_lshl_add_u64 v[138:139], v[168:169], 1, v[138:139]
	global_store_dwordx4 v[138:139], v[140:143], off
	global_store_dwordx4 v[138:139], v[196:199], off offset:256
	s_waitcnt lgkmcnt(0)
	v_add_f32_e32 v136, v205, v136
	v_mov_b32_e32 v137, v136
	s_nop 1
	v_permlane32_swap_b32_e32 v137, v136
	s_and_saveexec_b64 s[16:17], s[12:13]
	s_cbranch_execz .LBB0_1175
	s_waitcnt lgkmcnt(0)
	v_add_f32_e32 v138, v136, v137
	v_lshl_add_u64 v[136:137], v[166:167], 2, s[4:5]
	global_atomic_add_f32 v[136:137], v138, off offset:512
; DI unsigned cvt_pk(float lo, float hi) { unsigned r; asm("v_cvt_pk_bf16_f32 %0, %1, %2" : "=v"(r) : "v"(lo), "v"(hi)); return r; }
;     __device__ __forceinline__ void operator()(const f32x4 (&acc)[2][2][4][2], const Unit& u, int wr, int wc, int fr, int fq) const {
;     ...
;                 for (int mm = 0; mm < 2; ++mm) {
;                     const int m = mp * 2 + mm;
;                     const int row = row0 + ai * HALF + m * 16;
;                     float s = 0.f;
; #pragma unroll
;                     for (int bj = 0; bj < 2; ++bj) {
;                         u32x4* px = (u32x4*)(X + (size_t)row * DM + col0 + bj * HALF);
;                         float xo[8]; unpack8(xin[mm][bj], xo);
;                         const f32x4 a0 = acc[ai][bj][m][0] + pv[mm][bj][0], a1 = acc[ai][bj][m][1] + pv[mm][bj][1];
;                         u32x4 w;
;                         w.x = cvt_pk(xo[0] + scale * a0[0], xo[1] + scale * a0[1]); w.y = cvt_pk(xo[2] + scale * a0[2], xo[3] + scale * a0[3]);
;                         w.z = cvt_pk(xo[4] + scale * a1[0], xo[5] + scale * a1[1]); w.w = cvt_pk(xo[6] + scale * a1[2], xo[7] + scale * a1[3]);
;                         *px = w;
;                         float xn[8]; unpack8(w, xn);
; #pragma unroll
;                         for (int j = 0; j < 8; ++j) s += xn[j] * xn[j];
;                     }
;                     s += __shfl_xor(s, 16); s += __shfl_xor(s, 32);
;                     if (fq == 0) unsafeAtomicAdd(ssn + row, s);
.LBB0_1175:
	s_or_b64 exec, exec, s[16:17]
	v_lshlrev_b32_e32 v140, 16, v132
	v_and_b32_e32 v141, 0xffff0000, v132
	v_lshlrev_b32_e32 v142, 16, v133
	v_and_b32_e32 v143, 0xffff0000, v133
	v_pk_add_f32 v[132:133], v[52:53], v[192:193]
	v_lshlrev_b32_e32 v186, 16, v134
	v_and_b32_e32 v187, 0xffff0000, v134
	v_lshlrev_b32_e32 v196, 16, v135
	v_and_b32_e32 v197, 0xffff0000, v135
	v_pk_add_f32 v[134:135], v[54:55], v[194:195]
	v_add_f32_e32 v132, v132, v140
	v_add_f32_e32 v133, v133, v141
	v_pk_add_f32 v[138:139], v[48:49], v[188:189]
	v_cvt_pk_bf16_f32 v132, v132, v133
	v_add_f32_e32 v133, v134, v142
	v_add_f32_e32 v134, v135, v143
	s_waitcnt lgkmcnt(0)
	v_pk_add_f32 v[136:137], v[50:51], v[190:191]
	v_cvt_pk_bf16_f32 v133, v133, v134
	v_add_f32_e32 v134, v138, v186
	v_add_f32_e32 v135, v139, v187
	v_cvt_pk_bf16_f32 v134, v134, v135
	v_add_f32_e32 v135, v136, v196
	v_add_f32_e32 v136, v137, v197
	v_and_b32_e32 v137, 0xffff0000, v132
	v_cvt_pk_bf16_f32 v135, v135, v136
	v_lshlrev_b32_e32 v136, 16, v132
	v_mul_f32_e32 v186, v137, v137
	v_lshlrev_b32_e32 v138, 16, v133
	v_fmac_f32_e32 v186, v136, v136
	v_and_b32_e32 v139, 0xffff0000, v133
	v_fmac_f32_e32 v186, v138, v138
	v_lshlrev_b32_e32 v140, 16, v134
	v_fmac_f32_e32 v186, v139, v139
	v_and_b32_e32 v141, 0xffff0000, v134
	v_fmac_f32_e32 v186, v140, v140
	v_lshlrev_b32_e32 v142, 16, v135
	v_fmac_f32_e32 v186, v141, v141
	v_and_b32_e32 v143, 0xffff0000, v135
	v_fmac_f32_e32 v186, v142, v142
	v_fmac_f32_e32 v186, v143, v143
	v_lshlrev_b32_e32 v136, 16, v128
	v_and_b32_e32 v137, 0xffff0000, v128
	v_lshlrev_b32_e32 v142, 16, v129
	v_and_b32_e32 v143, 0xffff0000, v129
	v_pk_add_f32 v[128:129], v[22:23], v[184:185]
	v_lshlrev_b32_e32 v187, 16, v130
	v_and_b32_e32 v188, 0xffff0000, v130
	v_lshlrev_b32_e32 v189, 16, v131
	v_and_b32_e32 v190, 0xffff0000, v131
	v_pk_add_f32 v[130:131], v[20:21], v[182:183]
	v_pk_add_f32 v[138:139], v[16:17], v[178:179]
	v_add_f32_e32 v128, v128, v142
	v_pk_add_f32 v[140:141], v[18:19], v[180:181]
	v_add_f32_e32 v131, v131, v137
	v_add_f32_e32 v129, v129, v143
	v_cvt_pk_bf16_f32 v137, v128, v129
	v_add_f32_e32 v128, v138, v187
	v_add_f32_e32 v129, v139, v188
	v_cvt_pk_bf16_f32 v138, v128, v129
	v_add_f32_e32 v128, v140, v189
	v_add_f32_e32 v130, v130, v136
	v_cvt_pk_bf16_f32 v136, v130, v131
	v_add_f32_e32 v129, v141, v190
	v_cvt_pk_bf16_f32 v139, v128, v129
	v_lshlrev_b32_e32 v128, 16, v136
	v_and_b32_e32 v129, 0xffff0000, v136
	v_fmac_f32_e32 v186, v128, v128
	v_lshlrev_b32_e32 v130, 16, v137
	v_fmac_f32_e32 v186, v129, v129
	v_and_b32_e32 v131, 0xffff0000, v137
	v_fmac_f32_e32 v186, v130, v130
	v_lshlrev_b32_e32 v140, 16, v138
	v_fmac_f32_e32 v186, v131, v131
	v_and_b32_e32 v141, 0xffff0000, v138
	v_fmac_f32_e32 v186, v140, v140
	v_lshlrev_b32_e32 v142, 16, v139
	v_fmac_f32_e32 v186, v141, v141
	v_and_b32_e32 v143, 0xffff0000, v139
	v_fmac_f32_e32 v186, v142, v142
	v_fmac_f32_e32 v186, v143, v143
	v_mov_b32_e32 v128, v186
	s_nop 1
	v_permlane16_swap_b32_e32 v128, v186
	v_lshl_add_u64 v[130:131], s[36:37], 0, v[176:177]
	v_lshl_add_u64 v[130:131], v[168:169], 1, v[130:131]
	global_store_dwordx4 v[130:131], v[132:135], off
	global_store_dwordx4 v[130:131], v[136:139], off offset:256
	s_waitcnt lgkmcnt(0)
	v_add_f32_e32 v128, v186, v128
	v_mov_b32_e32 v129, v128
	s_nop 1
	v_permlane32_swap_b32_e32 v129, v128
	s_and_saveexec_b64 s[16:17], s[12:13]
	s_cbranch_execz .LBB0_1177
	s_waitcnt lgkmcnt(0)
	v_add_f32_e32 v130, v128, v129
	v_lshl_add_u64 v[128:129], v[166:167], 2, s[4:5]
	global_atomic_add_f32 v[128:129], v130, off offset:576

; DI unsigned cvt_pk(float lo, float hi) { unsigned r; asm("v_cvt_pk_bf16_f32 %0, %1, %2" : "=v"(r) : "v"(lo), "v"(hi)); return r; }
;     __device__ __forceinline__ void operator()(const f32x4 (&acc)[2][2][4][2], const Unit& u, int wr, int wc, int fr, int fq) const {
;     ...
;                 for (int mm = 0; mm < 2; ++mm) {
;                     const int m = mp * 2 + mm;
;                     const int row = row0 + ai * HALF + m * 16;
;                     float s = 0.f;
; #pragma unroll
;                     for (int bj = 0; bj < 2; ++bj) {
;                         u32x4* px = (u32x4*)(X + (size_t)row * DM + col0 + bj * HALF);
;                         float xo[8]; unpack8(xin[mm][bj], xo);
;                         const f32x4 a0 = acc[ai][bj][m][0] + pv[mm][bj][0], a1 = acc[ai][bj][m][1] + pv[mm][bj][1];
;                         u32x4 w;
;                         w.x = cvt_pk(xo[0] + scale * a0[0], xo[1] + scale * a0[1]); w.y = cvt_pk(xo[2] + scale * a0[2], xo[3] + scale * a0[3]);
;                         w.z = cvt_pk(xo[4] + scale * a1[0], xo[5] + scale * a1[1]); w.w = cvt_pk(xo[6] + scale * a1[2], xo[7] + scale * a1[3]);
;                         *px = w;
;                         float xn[8]; unpack8(w, xn);
; #pragma unroll
;                         for (int j = 0; j < 8; ++j) s += xn[j] * xn[j];
;                     }
;                     s += __shfl_xor(s, 16); s += __shfl_xor(s, 32);
;                     if (fq == 0) unsafeAtomicAdd(ssn + row, s);
.LBB0_1179:
	s_or_b64 exec, exec, s[16:17]
	v_lshlrev_b32_e32 v208, 16, v140
	v_and_b32_e32 v209, 0xffff0000, v140
	v_lshlrev_b32_e32 v210, 16, v141
	v_and_b32_e32 v211, 0xffff0000, v141
	v_pk_add_f32 v[140:141], v[44:45], v[204:205]
	v_lshlrev_b32_e32 v214, 16, v142
	v_and_b32_e32 v215, 0xffff0000, v142
	v_lshlrev_b32_e32 v244, 16, v143
	v_and_b32_e32 v245, 0xffff0000, v143
	v_pk_add_f32 v[142:143], v[46:47], v[206:207]
	v_add_f32_e32 v140, v140, v208
	v_add_f32_e32 v141, v141, v209
	v_pk_add_f32 v[200:201], v[40:41], v[200:201]
	v_cvt_pk_bf16_f32 v140, v140, v141
	v_add_f32_e32 v141, v142, v210
	v_add_f32_e32 v142, v143, v211
	v_pk_add_f32 v[170:171], v[42:43], v[202:203]
	v_cvt_pk_bf16_f32 v141, v141, v142
	v_add_f32_e32 v142, v200, v214
	v_add_f32_e32 v143, v201, v215
	v_cvt_pk_bf16_f32 v142, v142, v143
	v_add_f32_e32 v143, v170, v244
	v_add_f32_e32 v170, v171, v245
	v_and_b32_e32 v171, 0xffff0000, v140
	v_cvt_pk_bf16_f32 v143, v143, v170
	v_lshlrev_b32_e32 v170, 16, v140
	v_mul_f32_e32 v206, v171, v171
	v_lshlrev_b32_e32 v200, 16, v141
	v_fmac_f32_e32 v206, v170, v170
	v_and_b32_e32 v201, 0xffff0000, v141
	v_fmac_f32_e32 v206, v200, v200
	v_lshlrev_b32_e32 v202, 16, v142
	v_fmac_f32_e32 v206, v201, v201
	v_and_b32_e32 v203, 0xffff0000, v142
	v_fmac_f32_e32 v206, v202, v202
	v_lshlrev_b32_e32 v204, 16, v143
	v_fmac_f32_e32 v206, v203, v203
	v_lshlrev_b32_e32 v200, 16, v136
	v_and_b32_e32 v201, 0xffff0000, v136
	v_lshlrev_b32_e32 v202, 16, v137
	v_and_b32_e32 v203, 0xffff0000, v137
	v_pk_add_f32 v[136:137], v[14:15], v[198:199]
	v_and_b32_e32 v205, 0xffff0000, v143
	v_fmac_f32_e32 v206, v204, v204
	v_lshlrev_b32_e32 v204, 16, v138
	v_pk_add_f32 v[170:171], v[10:11], v[194:195]
	v_pk_add_f32 v[194:195], v[8:9], v[192:193]
	v_add_f32_e32 v136, v136, v202
	v_fmac_f32_e32 v206, v205, v205
	v_and_b32_e32 v205, 0xffff0000, v138
	v_lshlrev_b32_e32 v207, 16, v139
	v_add_f32_e32 v137, v137, v203
	v_cvt_pk_bf16_f32 v193, v136, v137
	v_add_f32_e32 v136, v194, v204
	v_and_b32_e32 v208, 0xffff0000, v139
	v_pk_add_f32 v[138:139], v[12:13], v[196:197]
	v_add_f32_e32 v137, v195, v205
	v_cvt_pk_bf16_f32 v194, v136, v137
	v_add_f32_e32 v136, v170, v207
	v_add_f32_e32 v138, v138, v200
	v_add_f32_e32 v139, v139, v201
	v_cvt_pk_bf16_f32 v192, v138, v139
	v_add_f32_e32 v137, v171, v208
	v_cvt_pk_bf16_f32 v195, v136, v137
	v_lshlrev_b32_e32 v136, 16, v192
	v_and_b32_e32 v137, 0xffff0000, v192
	v_fmac_f32_e32 v206, v136, v136
	v_lshlrev_b32_e32 v138, 16, v193
	v_fmac_f32_e32 v206, v137, v137
	v_and_b32_e32 v139, 0xffff0000, v193
	v_fmac_f32_e32 v206, v138, v138
	v_lshlrev_b32_e32 v170, 16, v194
	v_fmac_f32_e32 v206, v139, v139
	v_and_b32_e32 v171, 0xffff0000, v194
	v_fmac_f32_e32 v206, v170, v170
	v_lshlrev_b32_e32 v196, 16, v195
	v_fmac_f32_e32 v206, v171, v171
	v_and_b32_e32 v197, 0xffff0000, v195
	v_fmac_f32_e32 v206, v196, v196
	v_fmac_f32_e32 v206, v197, v197
	v_mov_b32_e32 v136, v206
	s_nop 1
	v_permlane16_swap_b32_e32 v136, v206
	v_lshl_add_u64 v[138:139], s[36:37], 0, v[182:183]
	v_lshl_add_u64 v[138:139], v[168:169], 1, v[138:139]
	global_store_dwordx4 v[138:139], v[140:143], off
	global_store_dwordx4 v[138:139], v[192:195], off offset:256
	s_waitcnt lgkmcnt(0)
	v_add_f32_e32 v136, v206, v136
	v_mov_b32_e32 v137, v136
	s_nop 1
	v_permlane32_swap_b32_e32 v137, v136
	s_and_saveexec_b64 s[16:17], s[12:13]
	s_cbranch_execz .LBB0_1181
	s_waitcnt lgkmcnt(0)
	v_add_f32_e32 v138, v136, v137
	v_lshl_add_u64 v[136:137], v[166:167], 2, s[4:5]
	global_atomic_add_f32 v[136:137], v138, off offset:640
; DI unsigned cvt_pk(float lo, float hi) { unsigned r; asm("v_cvt_pk_bf16_f32 %0, %1, %2" : "=v"(r) : "v"(lo), "v"(hi)); return r; }
;     __device__ __forceinline__ void operator()(const f32x4 (&acc)[2][2][4][2], const Unit& u, int wr, int wc, int fr, int fq) const {
;     ...
;                 for (int mm = 0; mm < 2; ++mm) {
;                     const int m = mp * 2 + mm;
;                     const int row = row0 + ai * HALF + m * 16;
;                     float s = 0.f;
; #pragma unroll
;                     for (int bj = 0; bj < 2; ++bj) {
;                         u32x4* px = (u32x4*)(X + (size_t)row * DM + col0 + bj * HALF);
;                         float xo[8]; unpack8(xin[mm][bj], xo);
;                         const f32x4 a0 = acc[ai][bj][m][0] + pv[mm][bj][0], a1 = acc[ai][bj][m][1] + pv[mm][bj][1];
;                         u32x4 w;
;                         w.x = cvt_pk(xo[0] + scale * a0[0], xo[1] + scale * a0[1]); w.y = cvt_pk(xo[2] + scale * a0[2], xo[3] + scale * a0[3]);
;                         w.z = cvt_pk(xo[4] + scale * a1[0], xo[5] + scale * a1[1]); w.w = cvt_pk(xo[6] + scale * a1[2], xo[7] + scale * a1[3]);
;                         *px = w;
;                         float xn[8]; unpack8(w, xn);
; #pragma unroll
;                         for (int j = 0; j < 8; ++j) s += xn[j] * xn[j];
;                     }
;                     s += __shfl_xor(s, 16); s += __shfl_xor(s, 32);
;                     if (fq == 0) unsafeAtomicAdd(ssn + row, s);
.LBB0_1181:
	s_or_b64 exec, exec, s[16:17]
	v_lshlrev_b32_e32 v140, 16, v132
	v_and_b32_e32 v141, 0xffff0000, v132
	v_lshlrev_b32_e32 v142, 16, v133
	v_and_b32_e32 v143, 0xffff0000, v133
	v_pk_add_f32 v[132:133], v[36:37], v[188:189]
	v_lshlrev_b32_e32 v170, 16, v134
	v_and_b32_e32 v171, 0xffff0000, v134
	v_lshlrev_b32_e32 v182, 16, v135
	v_and_b32_e32 v183, 0xffff0000, v135
	v_pk_add_f32 v[134:135], v[38:39], v[190:191]
	v_add_f32_e32 v132, v132, v140
	v_add_f32_e32 v133, v133, v141
	v_pk_add_f32 v[138:139], v[32:33], v[184:185]
	v_cvt_pk_bf16_f32 v132, v132, v133
	v_add_f32_e32 v133, v134, v142
	v_add_f32_e32 v134, v135, v143
	s_waitcnt lgkmcnt(0)
	v_pk_add_f32 v[136:137], v[34:35], v[186:187]
	v_cvt_pk_bf16_f32 v133, v133, v134
	v_add_f32_e32 v134, v138, v170
	v_add_f32_e32 v135, v139, v171
	v_cvt_pk_bf16_f32 v134, v134, v135
	v_add_f32_e32 v135, v136, v182
	v_add_f32_e32 v136, v137, v183
	v_and_b32_e32 v137, 0xffff0000, v132
	v_cvt_pk_bf16_f32 v135, v135, v136
	v_lshlrev_b32_e32 v136, 16, v132
	v_mul_f32_e32 v170, v137, v137
	v_lshlrev_b32_e32 v138, 16, v133
	v_fmac_f32_e32 v170, v136, v136
	v_and_b32_e32 v139, 0xffff0000, v133
	v_fmac_f32_e32 v170, v138, v138
	v_lshlrev_b32_e32 v140, 16, v134
	v_fmac_f32_e32 v170, v139, v139
	v_and_b32_e32 v141, 0xffff0000, v134
	v_fmac_f32_e32 v170, v140, v140
	v_lshlrev_b32_e32 v142, 16, v135
	v_fmac_f32_e32 v170, v141, v141
	v_and_b32_e32 v143, 0xffff0000, v135
	v_fmac_f32_e32 v170, v142, v142
	v_fmac_f32_e32 v170, v143, v143
	v_lshlrev_b32_e32 v136, 16, v128
	v_and_b32_e32 v137, 0xffff0000, v128
	v_lshlrev_b32_e32 v142, 16, v129
	v_and_b32_e32 v143, 0xffff0000, v129
	v_pk_add_f32 v[128:129], v[6:7], v[180:181]
	v_lshlrev_b32_e32 v171, 16, v130
	v_and_b32_e32 v182, 0xffff0000, v130
	v_lshlrev_b32_e32 v183, 16, v131
	v_and_b32_e32 v184, 0xffff0000, v131
	v_pk_add_f32 v[130:131], v[4:5], v[178:179]
	v_pk_add_f32 v[138:139], v[0:1], v[172:173]
	v_add_f32_e32 v128, v128, v142
	v_pk_add_f32 v[140:141], v[2:3], v[176:177]
	v_add_f32_e32 v131, v131, v137
	v_add_f32_e32 v129, v129, v143
	v_cvt_pk_bf16_f32 v137, v128, v129
	v_add_f32_e32 v128, v138, v171
	v_add_f32_e32 v129, v139, v182
	v_cvt_pk_bf16_f32 v138, v128, v129
	v_add_f32_e32 v128, v140, v183
	v_add_f32_e32 v130, v130, v136
	v_cvt_pk_bf16_f32 v136, v130, v131
	v_add_f32_e32 v129, v141, v184
	v_cvt_pk_bf16_f32 v139, v128, v129
	v_lshlrev_b32_e32 v128, 16, v136
	v_and_b32_e32 v129, 0xffff0000, v136
	v_fmac_f32_e32 v170, v128, v128
	v_lshlrev_b32_e32 v130, 16, v137
	v_fmac_f32_e32 v170, v129, v129
	v_and_b32_e32 v131, 0xffff0000, v137
	v_fmac_f32_e32 v170, v130, v130
	v_lshlrev_b32_e32 v140, 16, v138
	v_fmac_f32_e32 v170, v131, v131
	v_and_b32_e32 v141, 0xffff0000, v138
	v_fmac_f32_e32 v170, v140, v140
	v_lshlrev_b32_e32 v142, 16, v139
	v_fmac_f32_e32 v170, v141, v141
	v_and_b32_e32 v143, 0xffff0000, v139
	v_fmac_f32_e32 v170, v142, v142
	v_fmac_f32_e32 v170, v143, v143
	v_mov_b32_e32 v128, v170
	s_nop 1
	v_permlane16_swap_b32_e32 v128, v170
	v_lshl_add_u64 v[130:131], s[36:37], 0, v[174:175]
	v_lshl_add_u64 v[130:131], v[168:169], 1, v[130:131]
	global_store_dwordx4 v[130:131], v[132:135], off
	global_store_dwordx4 v[130:131], v[136:139], off offset:256
	s_waitcnt lgkmcnt(0)
	v_add_f32_e32 v128, v170, v128
	v_mov_b32_e32 v129, v128
	s_nop 1
	v_permlane32_swap_b32_e32 v129, v128
	s_and_saveexec_b64 s[16:17], s[12:13]
	s_cbranch_execz .LBB0_1183
	s_waitcnt lgkmcnt(0)
	v_add_f32_e32 v130, v128, v129
	v_lshl_add_u64 v[128:129], v[166:167], 2, s[4:5]
	global_atomic_add_f32 v[128:129], v130, off offset:704

;     __device__ __forceinline__ void operator()(const f32x4 (&acc)[2][2][4][2], const Unit& u, int wr, int wc, int fr, int fq) const {
;     ...
;         const int row0 = u.pm * BM + wr * 64 + fr, col0 = u.pn * BM + wc * 32 + 8 * fq;
; #pragma unroll
;         for (int ai = 0; ai < 2; ++ai)
; #pragma unroll
;             for (int mp = 0; mp < 2; ++mp) {
;                 u32x4 xin[2][2];
; #pragma unroll
;                 for (int mm = 0; mm < 2; ++mm)
; #pragma unroll
;                     for (int bj = 0; bj < 2; ++bj) xin[mm][bj] = *(const u32x4*)(X + (size_t)(row0 + ai * HALF + (mp * 2 + mm) * 16) * DM + col0 + bj * HALF);
;                 f32x4 pv[2][2][2];
; #pragma unroll
;                 for (int mm = 0; mm < 2; ++mm)
; #pragma unroll
;                     for (int bj = 0; bj < 2; ++bj)
; #pragma unroll
;                         for (int n = 0; n < 2; ++n) pv[mm][bj][n] = (f32x4){0.f, 0.f, 0.f, 0.f};
;                 if (src) {
;                     u32x4 pc[2][2];
;     ...
;                     asm volatile("global_load_dwordx4 %0, %4, off sc1\n\tglobal_load_dwordx4 %1, %5, off sc1\n\tglobal_load_dwordx4 %2, %6, off sc1\n\tglobal_load_dwordx4 %3, %7, off sc1\n\ts_waitcnt vmcnt(0)"
;                                  : "=&v"(pc[0][0]), "=&v"(pc[0][1]), "=&v"(pc[1][0]), "=&v"(pc[1][1])
;                                  : "v"(src + CI(0, 0)), "v"(src + CI(0, 1)), "v"(src + CI(1, 0)), "v"(src + CI(1, 1))
;                                  : "memory");
;     ...
; #pragma unroll
;                     for (int mm = 0; mm < 2; ++mm)
; #pragma unroll
;                         for (int bj = 0; bj < 2; ++bj) { float f[8]; unpack8(pc[mm][bj], f); pv[mm][bj][0] = (f32x4){f[0], f[1], f[2], f[3]}; pv[mm][bj][1] = (f32x4){f[4], f[5], f[6], f[7]}; }
;                 }
; #pragma unroll
;                 for (int mm = 0; mm < 2; ++mm) {
;                     const int m = mp * 2 + mm;
;                     const int row = row0 + ai * HALF + m * 16;
;                     float s = 0.f;
; #pragma unroll
;                     for (int bj = 0; bj < 2; ++bj) {
;                         u32x4* px = (u32x4*)(X + (size_t)row * DM + col0 + bj * HALF);
;                         float xo[8]; unpack8(xin[mm][bj], xo);
;                         const f32x4 a0 = acc[ai][bj][m][0] + pv[mm][bj][0], a1 = acc[ai][bj][m][1] + pv[mm][bj][1];
;                         u32x4 w;
.LBB0_1208:
	v_lshl_or_b32 v140, s22, 8, v158
	v_lshl_add_u32 v138, s24, 8, v156
	v_ashrrev_i32_e32 v141, 31, v140
	v_lshlrev_b64 v[168:169], 1, v[140:141]
	v_ashrrev_i32_e32 v139, 31, v138
	v_lshl_add_u64 v[142:143], s[36:37], 0, v[168:169]
	v_lshlrev_b64 v[154:155], 11, v[138:139]
	v_lshl_add_u64 v[164:165], v[142:143], 0, v[154:155]
	global_load_dwordx4 v[160:163], v[164:165], off
	s_nop 0
	global_load_dwordx4 v[164:167], v[164:165], off offset:256
	v_pk_add_f32 v[180:181], v[112:113], 0 op_sel_hi:[1,0]
	v_and_b32_e32 v113, 64, v221
	v_or_b32_e32 v112, 16, v138
	v_pk_add_f32 v[170:171], v[122:123], 0 op_sel_hi:[1,0]
	v_pk_add_f32 v[178:179], v[114:115], 0 op_sel_hi:[1,0]
	v_xor_b32_e32 v114, 16, v221
	v_add_u32_e32 v123, 64, v113
	v_ashrrev_i32_e32 v113, 31, v112
	v_pk_add_f32 v[172:173], v[120:121], 0 op_sel_hi:[1,0]
	v_cmp_lt_i32_e32 vcc, v114, v123
	v_lshlrev_b64 v[120:121], 11, v[112:113]
	v_lshl_add_u64 v[112:113], v[142:143], 0, v[120:121]
	v_cndmask_b32_e32 v114, v221, v114, vcc
	v_pk_add_f32 v[174:175], v[118:119], 0 op_sel_hi:[1,0]
	v_pk_add_f32 v[176:177], v[116:117], 0 op_sel_hi:[1,0]
	v_lshlrev_b32_e32 v122, 2, v114
	global_load_dwordx4 v[116:119], v[112:113], off
	s_nop 0
	global_load_dwordx4 v[112:115], v[112:113], off offset:256
	v_pk_add_f32 v[124:125], v[124:125], 0 op_sel_hi:[1,0]
	v_pk_add_f32 v[126:127], v[126:127], 0 op_sel_hi:[1,0]
	s_waitcnt vmcnt(0)
	v_lshlrev_b32_e32 v182, 16, v160
	v_and_b32_e32 v160, 0xffff0000, v160
	v_add_f32_e32 v125, v125, v160
	v_lshlrev_b32_e32 v183, 16, v161
	v_add_f32_e32 v124, v124, v182
	v_cvt_pk_bf16_f32 v160, v124, v125
	v_and_b32_e32 v161, 0xffff0000, v161
	v_and_b32_e32 v125, 0xffff0000, v160
	v_add_f32_e32 v126, v126, v183
	v_lshlrev_b32_e32 v124, 16, v160
	v_mul_f32_e32 v125, v125, v125
	v_lshlrev_b32_e32 v184, 16, v162
	v_and_b32_e32 v162, 0xffff0000, v162
	v_lshlrev_b32_e32 v185, 16, v163
	v_and_b32_e32 v163, 0xffff0000, v163
	v_add_f32_e32 v127, v127, v161
	v_cvt_pk_bf16_f32 v161, v126, v127
	v_fmac_f32_e32 v125, v124, v124
	v_lshlrev_b32_e32 v126, 16, v161
	v_lshlrev_b32_e32 v186, 16, v164
	v_and_b32_e32 v164, 0xffff0000, v164
	v_add_f32_e32 v162, v173, v162
	v_add_f32_e32 v170, v170, v185
	v_add_f32_e32 v163, v171, v163
	v_and_b32_e32 v127, 0xffff0000, v161
	v_fmac_f32_e32 v125, v126, v126
	v_add_f32_e32 v172, v172, v184
	v_add_f32_e32 v171, v176, v186
	v_add_f32_e32 v164, v177, v164
	v_cvt_pk_bf16_f32 v162, v172, v162
	v_cvt_pk_bf16_f32 v163, v170, v163
	v_fmac_f32_e32 v125, v127, v127
	v_lshlrev_b32_e32 v170, 16, v162
	v_lshlrev_b32_e32 v187, 16, v165
	v_and_b32_e32 v165, 0xffff0000, v165
	v_cvt_pk_bf16_f32 v164, v171, v164
	v_and_b32_e32 v171, 0xffff0000, v162
	v_fmac_f32_e32 v125, v170, v170
	v_lshlrev_b32_e32 v188, 16, v166
	v_and_b32_e32 v166, 0xffff0000, v166
	v_add_f32_e32 v173, v174, v187
	v_add_f32_e32 v165, v175, v165
	v_lshlrev_b32_e32 v172, 16, v163
	v_fmac_f32_e32 v125, v171, v171
	v_lshlrev_b32_e32 v189, 16, v167
	v_and_b32_e32 v167, 0xffff0000, v167
	v_add_f32_e32 v174, v180, v188
	v_add_f32_e32 v166, v181, v166
	v_cvt_pk_bf16_f32 v165, v173, v165
	v_and_b32_e32 v173, 0xffff0000, v163
	v_fmac_f32_e32 v125, v172, v172
	v_add_f32_e32 v175, v178, v189
	v_add_f32_e32 v167, v179, v167
	v_cvt_pk_bf16_f32 v166, v174, v166
	v_lshlrev_b32_e32 v174, 16, v164
	v_fmac_f32_e32 v125, v173, v173
	v_cvt_pk_bf16_f32 v167, v175, v167
	v_and_b32_e32 v175, 0xffff0000, v164
	v_fmac_f32_e32 v125, v174, v174
	v_lshlrev_b32_e32 v176, 16, v165
	v_fmac_f32_e32 v125, v175, v175
	v_and_b32_e32 v177, 0xffff0000, v165
	v_fmac_f32_e32 v125, v176, v176
	v_lshlrev_b32_e32 v178, 16, v166
	v_fmac_f32_e32 v125, v177, v177
	v_and_b32_e32 v179, 0xffff0000, v166
	v_fmac_f32_e32 v125, v178, v178
	v_lshlrev_b32_e32 v180, 16, v167
	v_fmac_f32_e32 v125, v179, v179
	v_and_b32_e32 v181, 0xffff0000, v167
	v_fmac_f32_e32 v125, v180, v180
	v_fmac_f32_e32 v125, v181, v181
	v_mov_b32_e32 v124, v125
	s_nop 1
	v_permlane16_swap_b32_e32 v124, v125
	v_xor_b32_e32 v126, 32, v221
	v_cmp_lt_i32_e32 vcc, v126, v123
	s_waitcnt lgkmcnt(0)
	v_add_f32_e32 v124, v125, v124
	v_cndmask_b32_e32 v123, v221, v126, vcc
	v_lshlrev_b32_e32 v123, 2, v123
	v_mov_b32_e32 v125, v124
	s_nop 1
	v_permlane32_swap_b32_e32 v125, v124
	v_lshl_add_u64 v[126:127], s[36:37], 0, v[154:155]
	v_lshl_add_u64 v[126:127], v[126:127], 0, v[168:169]
	global_store_dwordx4 v[126:127], v[160:163], off
	global_store_dwordx4 v[126:127], v[164:167], off offset:256
	s_and_saveexec_b64 s[22:23], s[10:11]
	s_cbranch_execz .LBB0_1210
	s_waitcnt lgkmcnt(0)
	v_add_f32_e32 v126, v124, v125
	v_lshl_add_u64 v[124:125], v[138:139], 2, s[4:5]
	global_atomic_add_f32 v[124:125], v126, off
;     __device__ __forceinline__ void operator()(const f32x4 (&acc)[2][2][4][2], const Unit& u, int wr, int wc, int fr, int fq) const {
;     ...
;                 u32x4 xin[2][2];
; #pragma unroll
;                 for (int mm = 0; mm < 2; ++mm)
; #pragma unroll
;                     for (int bj = 0; bj < 2; ++bj) xin[mm][bj] = *(const u32x4*)(X + (size_t)(row0 + ai * HALF + (mp * 2 + mm) * 16) * DM + col0 + bj * HALF);
;                 f32x4 pv[2][2][2];
; #pragma unroll
;                 for (int mm = 0; mm < 2; ++mm)
; #pragma unroll
;                     for (int bj = 0; bj < 2; ++bj)
; #pragma unroll
;                         for (int n = 0; n < 2; ++n) pv[mm][bj][n] = (f32x4){0.f, 0.f, 0.f, 0.f};
;                 if (src) {
;                     u32x4 pc[2][2];
;     ...
;                     asm volatile("global_load_dwordx4 %0, %4, off sc1\n\tglobal_load_dwordx4 %1, %5, off sc1\n\tglobal_load_dwordx4 %2, %6, off sc1\n\tglobal_load_dwordx4 %3, %7, off sc1\n\ts_waitcnt vmcnt(0)"
;                                  : "=&v"(pc[0][0]), "=&v"(pc[0][1]), "=&v"(pc[1][0]), "=&v"(pc[1][1])
;                                  : "v"(src + CI(0, 0)), "v"(src + CI(0, 1)), "v"(src + CI(1, 0)), "v"(src + CI(1, 1))
;                                  : "memory");
;     ...
; #pragma unroll
;                     for (int mm = 0; mm < 2; ++mm)
; #pragma unroll
;                         for (int bj = 0; bj < 2; ++bj) { float f[8]; unpack8(pc[mm][bj], f); pv[mm][bj][0] = (f32x4){f[0], f[1], f[2], f[3]}; pv[mm][bj][1] = (f32x4){f[4], f[5], f[6], f[7]}; }
;                 }
; #pragma unroll
;                 for (int mm = 0; mm < 2; ++mm) {
;                     const int m = mp * 2 + mm;
;                     const int row = row0 + ai * HALF + m * 16;
;                     float s = 0.f;
; #pragma unroll
;                     for (int bj = 0; bj < 2; ++bj) {
;                         u32x4* px = (u32x4*)(X + (size_t)row * DM + col0 + bj * HALF);
;                         float xo[8]; unpack8(xin[mm][bj], xo);
;                         const f32x4 a0 = acc[ai][bj][m][0] + pv[mm][bj][0], a1 = acc[ai][bj][m][1] + pv[mm][bj][1];
;                         u32x4 w;
;                         w.x = cvt_pk(xo[0] + scale * a0[0], xo[1] + scale * a0[1]); w.y = cvt_pk(xo[2] + scale * a0[2], xo[3] + scale * a0[3]);
.LBB0_1210:
	s_or_b64 exec, exec, s[22:23]
	v_lshlrev_b32_e32 v124, 16, v116
	s_waitcnt lgkmcnt(0)
	v_and_b32_e32 v125, 0xffff0000, v116
	v_pk_add_f32 v[108:109], v[108:109], 0 op_sel_hi:[1,0]
	v_lshlrev_b32_e32 v126, 16, v117
	v_and_b32_e32 v127, 0xffff0000, v117
	v_lshlrev_b32_e32 v160, 16, v118
	v_and_b32_e32 v118, 0xffff0000, v118
	v_pk_add_f32 v[110:111], v[110:111], 0 op_sel_hi:[1,0]
	v_pk_add_f32 v[116:117], v[106:107], 0 op_sel_hi:[1,0]
	v_pk_add_f32 v[106:107], v[104:105], 0 op_sel_hi:[1,0]
	v_add_f32_e32 v104, v108, v124
	v_add_f32_e32 v105, v109, v125
	v_lshlrev_b32_e32 v161, 16, v119
	v_and_b32_e32 v119, 0xffff0000, v119
	v_cvt_pk_bf16_f32 v104, v104, v105
	v_add_f32_e32 v105, v110, v126
	v_add_f32_e32 v108, v111, v127
	v_add_f32_e32 v106, v106, v160
	v_add_f32_e32 v107, v107, v118
	v_cvt_pk_bf16_f32 v105, v105, v108
	v_cvt_pk_bf16_f32 v106, v106, v107
	v_add_f32_e32 v107, v116, v161
	v_add_f32_e32 v108, v117, v119
	v_and_b32_e32 v109, 0xffff0000, v104
	v_cvt_pk_bf16_f32 v107, v107, v108
	v_lshlrev_b32_e32 v108, 16, v104
	v_mul_f32_e32 v124, v109, v109
	v_lshlrev_b32_e32 v110, 16, v105
	v_fmac_f32_e32 v124, v108, v108
	v_and_b32_e32 v111, 0xffff0000, v105
	v_fmac_f32_e32 v124, v110, v110
	v_lshlrev_b32_e32 v116, 16, v106
	v_fmac_f32_e32 v124, v111, v111
	v_lshlrev_b32_e32 v110, 16, v112
	v_and_b32_e32 v111, 0xffff0000, v112
	v_pk_add_f32 v[100:101], v[100:101], 0 op_sel_hi:[1,0]
	v_and_b32_e32 v117, 0xffff0000, v106
	v_fmac_f32_e32 v124, v116, v116
	v_lshlrev_b32_e32 v112, 16, v113
	v_and_b32_e32 v113, 0xffff0000, v113
	v_lshlrev_b32_e32 v116, 16, v114
	v_pk_add_f32 v[102:103], v[102:103], 0 op_sel_hi:[1,0]
	v_pk_add_f32 v[108:109], v[98:99], 0 op_sel_hi:[1,0]
	v_pk_add_f32 v[96:97], v[96:97], 0 op_sel_hi:[1,0]
	v_add_f32_e32 v98, v100, v110
	v_add_f32_e32 v99, v101, v111
	v_lshlrev_b32_e32 v118, 16, v107
	v_fmac_f32_e32 v124, v117, v117
	v_and_b32_e32 v114, 0xffff0000, v114
	v_lshlrev_b32_e32 v117, 16, v115
	v_cvt_pk_bf16_f32 v98, v98, v99
	v_add_f32_e32 v99, v102, v112
	v_add_f32_e32 v100, v103, v113
	v_add_f32_e32 v96, v96, v116
	v_and_b32_e32 v119, 0xffff0000, v107
	v_fmac_f32_e32 v124, v118, v118
	v_and_b32_e32 v115, 0xffff0000, v115
	v_cvt_pk_bf16_f32 v99, v99, v100
	v_add_f32_e32 v97, v97, v114
	v_cvt_pk_bf16_f32 v100, v96, v97
	v_add_f32_e32 v96, v108, v117
	v_fmac_f32_e32 v124, v119, v119
	v_add_f32_e32 v97, v109, v115
	v_cvt_pk_bf16_f32 v101, v96, v97
	v_lshlrev_b32_e32 v96, 16, v98
	v_and_b32_e32 v97, 0xffff0000, v98
	v_fmac_f32_e32 v124, v96, v96
	v_lshlrev_b32_e32 v102, 16, v99
	v_fmac_f32_e32 v124, v97, v97
	v_and_b32_e32 v103, 0xffff0000, v99
	v_fmac_f32_e32 v124, v102, v102
	v_lshlrev_b32_e32 v108, 16, v100
	v_fmac_f32_e32 v124, v103, v103
	v_and_b32_e32 v109, 0xffff0000, v100
	v_fmac_f32_e32 v124, v108, v108
	v_lshlrev_b32_e32 v110, 16, v101
	v_fmac_f32_e32 v124, v109, v109
	v_and_b32_e32 v111, 0xffff0000, v101
	v_fmac_f32_e32 v124, v110, v110
	v_fmac_f32_e32 v124, v111, v111
	v_mov_b32_e32 v96, v124
	s_nop 1
	v_permlane16_swap_b32_e32 v96, v124
	v_lshl_add_u64 v[102:103], s[36:37], 0, v[120:121]
	v_lshl_add_u64 v[102:103], v[140:141], 1, v[102:103]
	global_store_dwordx4 v[102:103], v[104:107], off
	global_store_dwordx4 v[102:103], v[98:101], off offset:256
	s_waitcnt lgkmcnt(0)
	v_add_f32_e32 v96, v124, v96
	v_mov_b32_e32 v97, v96
	s_nop 1
	v_permlane32_swap_b32_e32 v97, v96
	s_and_saveexec_b64 s[22:23], s[10:11]
	s_cbranch_execz .LBB0_1212
	s_waitcnt lgkmcnt(0)
	v_add_f32_e32 v98, v96, v97
	v_lshl_add_u64 v[96:97], v[138:139], 2, s[4:5]
	global_atomic_add_f32 v[96:97], v98, off offset:64
.LBB0_1212:
	s_or_b64 exec, exec, s[22:23]
	v_or_b32_e32 v96, 32, v138
	s_waitcnt lgkmcnt(0)
	v_ashrrev_i32_e32 v97, 31, v96
	v_lshlrev_b64 v[106:107], 11, v[96:97]
	v_lshl_add_u64 v[96:97], v[142:143], 0, v[106:107]
	global_load_dwordx4 v[108:111], v[96:97], off
	global_load_dwordx4 v[112:115], v[96:97], off offset:256
	v_or_b32_e32 v96, 48, v138
	v_ashrrev_i32_e32 v97, 31, v96
	v_lshlrev_b64 v[104:105], 11, v[96:97]
	v_lshl_add_u64 v[96:97], v[142:143], 0, v[104:105]
	global_load_dwordx4 v[100:103], v[96:97], off
	s_nop 0
	global_load_dwordx4 v[96:99], v[96:97], off offset:256
	v_pk_add_f32 v[92:93], v[92:93], 0 op_sel_hi:[1,0]
	v_pk_add_f32 v[94:95], v[94:95], 0 op_sel_hi:[1,0]
	v_lshl_add_u64 v[106:107], s[36:37], 0, v[106:107]
	v_lshl_add_u64 v[106:107], v[140:141], 1, v[106:107]
	v_pk_add_f32 v[84:85], v[84:85], 0 op_sel_hi:[1,0]
	v_pk_add_f32 v[86:87], v[86:87], 0 op_sel_hi:[1,0]
	s_waitcnt vmcnt(3)
	v_lshlrev_b32_e32 v116, 16, v108
	v_and_b32_e32 v117, 0xffff0000, v108
	v_lshlrev_b32_e32 v118, 16, v109
	v_and_b32_e32 v119, 0xffff0000, v109
	v_lshlrev_b32_e32 v120, 16, v110
	v_and_b32_e32 v110, 0xffff0000, v110
	v_pk_add_f32 v[108:109], v[90:91], 0 op_sel_hi:[1,0]
	v_pk_add_f32 v[90:91], v[88:89], 0 op_sel_hi:[1,0]
	v_add_f32_e32 v88, v92, v116
	v_add_f32_e32 v89, v93, v117
	v_lshlrev_b32_e32 v121, 16, v111
	v_and_b32_e32 v111, 0xffff0000, v111
	v_cvt_pk_bf16_f32 v88, v88, v89
	v_add_f32_e32 v89, v94, v118
	v_add_f32_e32 v92, v95, v119
	v_add_f32_e32 v90, v90, v120
	v_add_f32_e32 v91, v91, v110
	v_cvt_pk_bf16_f32 v89, v89, v92
	v_cvt_pk_bf16_f32 v90, v90, v91
	v_add_f32_e32 v91, v108, v121
	v_add_f32_e32 v92, v109, v111
	v_cvt_pk_bf16_f32 v91, v91, v92
	global_store_dwordx4 v[106:107], v[88:91], off
	v_lshlrev_b32_e32 v92, 16, v88
	v_lshlrev_b32_e32 v93, 16, v89
	v_and_b32_e32 v88, 0xffff0000, v88
	v_mul_f32_e32 v108, v88, v88
	v_fmac_f32_e32 v108, v92, v92
	v_and_b32_e32 v89, 0xffff0000, v89
	v_fmac_f32_e32 v108, v93, v93
	v_lshlrev_b32_e32 v94, 16, v90
	v_fmac_f32_e32 v108, v89, v89
	v_and_b32_e32 v90, 0xffff0000, v90
	v_fmac_f32_e32 v108, v94, v94
	v_lshlrev_b32_e32 v95, 16, v91
	v_fmac_f32_e32 v108, v90, v90
	v_and_b32_e32 v91, 0xffff0000, v91
	v_fmac_f32_e32 v108, v95, v95
	v_fmac_f32_e32 v108, v91, v91
	s_waitcnt vmcnt(3)
; DI unsigned cvt_pk(float lo, float hi) { unsigned r; asm("v_cvt_pk_bf16_f32 %0, %1, %2" : "=v"(r) : "v"(lo), "v"(hi)); return r; }
;     __device__ __forceinline__ void operator()(const f32x4 (&acc)[2][2][4][2], const Unit& u, int wr, int wc, int fr, int fq) const {
;     ...
; #pragma unroll
;                 for (int mm = 0; mm < 2; ++mm) {
;                     const int m = mp * 2 + mm;
;                     const int row = row0 + ai * HALF + m * 16;
;                     float s = 0.f;
; #pragma unroll
;                     for (int bj = 0; bj < 2; ++bj) {
;                         u32x4* px = (u32x4*)(X + (size_t)row * DM + col0 + bj * HALF);
;                         float xo[8]; unpack8(xin[mm][bj], xo);
;                         const f32x4 a0 = acc[ai][bj][m][0] + pv[mm][bj][0], a1 = acc[ai][bj][m][1] + pv[mm][bj][1];
;                         u32x4 w;
;                         w.x = cvt_pk(xo[0] + scale * a0[0], xo[1] + scale * a0[1]); w.y = cvt_pk(xo[2] + scale * a0[2], xo[3] + scale * a0[3]);
;                         w.z = cvt_pk(xo[4] + scale * a1[0], xo[5] + scale * a1[1]); w.w = cvt_pk(xo[6] + scale * a1[2], xo[7] + scale * a1[3]);
;                         *px = w;
;                         float xn[8]; unpack8(w, xn);
; #pragma unroll
;                         for (int j = 0; j < 8; ++j) s += xn[j] * xn[j];
;                     }
;                     s += __shfl_xor(s, 16); s += __shfl_xor(s, 32);
;                     if (fq == 0) unsafeAtomicAdd(ssn + row, s);
;                 }
	v_lshlrev_b32_e32 v90, 16, v112
	v_and_b32_e32 v91, 0xffff0000, v112
	v_lshlrev_b32_e32 v92, 16, v113
	v_and_b32_e32 v93, 0xffff0000, v113
	v_lshlrev_b32_e32 v94, 16, v114
	v_and_b32_e32 v95, 0xffff0000, v114
	v_pk_add_f32 v[88:89], v[82:83], 0 op_sel_hi:[1,0]
	v_pk_add_f32 v[82:83], v[80:81], 0 op_sel_hi:[1,0]
	v_add_f32_e32 v80, v84, v90
	v_add_f32_e32 v81, v85, v91
	v_lshlrev_b32_e32 v109, 16, v115
	v_and_b32_e32 v110, 0xffff0000, v115
	v_cvt_pk_bf16_f32 v80, v80, v81
	v_add_f32_e32 v81, v86, v92
	v_add_f32_e32 v84, v87, v93
	v_add_f32_e32 v82, v82, v94
	v_add_f32_e32 v83, v83, v95
	v_cvt_pk_bf16_f32 v81, v81, v84
	v_cvt_pk_bf16_f32 v82, v82, v83
	v_add_f32_e32 v83, v88, v109
	v_add_f32_e32 v84, v89, v110
	v_cvt_pk_bf16_f32 v83, v83, v84
	v_lshlrev_b32_e32 v84, 16, v80
	global_store_dwordx4 v[106:107], v[80:83], off offset:256
	v_fmac_f32_e32 v108, v84, v84
	v_lshlrev_b32_e32 v85, 16, v81
	v_and_b32_e32 v80, 0xffff0000, v80
	v_fmac_f32_e32 v108, v80, v80
	v_and_b32_e32 v81, 0xffff0000, v81
	v_fmac_f32_e32 v108, v85, v85
	v_lshlrev_b32_e32 v86, 16, v82
	v_fmac_f32_e32 v108, v81, v81
	v_and_b32_e32 v82, 0xffff0000, v82
	v_fmac_f32_e32 v108, v86, v86
	v_lshlrev_b32_e32 v87, 16, v83
	v_fmac_f32_e32 v108, v82, v82
	v_and_b32_e32 v83, 0xffff0000, v83
	v_fmac_f32_e32 v108, v87, v87
	v_fmac_f32_e32 v108, v83, v83
	v_mov_b32_e32 v80, v108
	s_nop 1
	v_permlane16_swap_b32_e32 v80, v108
	s_waitcnt lgkmcnt(0)
	v_add_f32_e32 v80, v108, v80
	v_mov_b32_e32 v81, v80
	s_nop 1
	v_permlane32_swap_b32_e32 v81, v80
	s_and_saveexec_b64 s[22:23], s[10:11]
	s_cbranch_execz .LBB0_1214
	s_waitcnt lgkmcnt(0)
	v_add_f32_e32 v82, v80, v81
	v_lshl_add_u64 v[80:81], v[138:139], 2, s[4:5]
	global_atomic_add_f32 v[80:81], v82, off offset:128
.LBB0_1214:
	s_or_b64 exec, exec, s[22:23]
	s_waitcnt vmcnt(3)
	v_lshlrev_b32_e32 v82, 16, v100
	v_and_b32_e32 v83, 0xffff0000, v100
	v_pk_add_f32 v[76:77], v[76:77], 0 op_sel_hi:[1,0]
	v_lshlrev_b32_e32 v84, 16, v101
	v_and_b32_e32 v85, 0xffff0000, v101
	v_lshlrev_b32_e32 v86, 16, v102
	v_and_b32_e32 v87, 0xffff0000, v102
	v_pk_add_f32 v[78:79], v[78:79], 0 op_sel_hi:[1,0]
	s_waitcnt lgkmcnt(0)
	v_pk_add_f32 v[80:81], v[74:75], 0 op_sel_hi:[1,0]
	v_pk_add_f32 v[74:75], v[72:73], 0 op_sel_hi:[1,0]
	v_add_f32_e32 v72, v76, v82
	v_add_f32_e32 v73, v77, v83
	v_lshlrev_b32_e32 v88, 16, v103
	v_and_b32_e32 v89, 0xffff0000, v103
	v_cvt_pk_bf16_f32 v72, v72, v73
	v_add_f32_e32 v73, v78, v84
	v_add_f32_e32 v76, v79, v85
	v_add_f32_e32 v74, v74, v86
	v_add_f32_e32 v75, v75, v87
	v_cvt_pk_bf16_f32 v73, v73, v76
	v_cvt_pk_bf16_f32 v74, v74, v75
	v_add_f32_e32 v75, v80, v88
	v_add_f32_e32 v76, v81, v89
	v_and_b32_e32 v77, 0xffff0000, v72
	v_cvt_pk_bf16_f32 v75, v75, v76
	v_lshlrev_b32_e32 v76, 16, v72
	v_mul_f32_e32 v84, v77, v77
	v_lshlrev_b32_e32 v78, 16, v73
	v_fmac_f32_e32 v84, v76, v76
	v_and_b32_e32 v79, 0xffff0000, v73
	v_fmac_f32_e32 v84, v78, v78
	v_lshlrev_b32_e32 v80, 16, v74
	v_fmac_f32_e32 v84, v79, v79
	v_and_b32_e32 v81, 0xffff0000, v74
	v_fmac_f32_e32 v84, v80, v80
	v_lshlrev_b32_e32 v82, 16, v75
	v_fmac_f32_e32 v84, v81, v81
	s_waitcnt vmcnt(2)
	v_lshlrev_b32_e32 v78, 16, v96
	v_and_b32_e32 v79, 0xffff0000, v96
	v_pk_add_f32 v[68:69], v[68:69], 0 op_sel_hi:[1,0]
	v_and_b32_e32 v83, 0xffff0000, v75
	v_fmac_f32_e32 v84, v82, v82
	v_lshlrev_b32_e32 v80, 16, v97
	v_and_b32_e32 v81, 0xffff0000, v97
	v_lshlrev_b32_e32 v82, 16, v98
	v_pk_add_f32 v[70:71], v[70:71], 0 op_sel_hi:[1,0]
	v_pk_add_f32 v[76:77], v[66:67], 0 op_sel_hi:[1,0]
	v_pk_add_f32 v[64:65], v[64:65], 0 op_sel_hi:[1,0]
	v_add_f32_e32 v66, v68, v78
	v_add_f32_e32 v67, v69, v79
	v_fmac_f32_e32 v84, v83, v83
	v_and_b32_e32 v83, 0xffff0000, v98
	v_lshlrev_b32_e32 v85, 16, v99
	v_cvt_pk_bf16_f32 v66, v66, v67
	v_add_f32_e32 v67, v70, v80
	v_add_f32_e32 v68, v71, v81
	v_add_f32_e32 v64, v64, v82
	v_and_b32_e32 v86, 0xffff0000, v99
	v_cvt_pk_bf16_f32 v67, v67, v68
	v_add_f32_e32 v65, v65, v83
	v_cvt_pk_bf16_f32 v68, v64, v65
	v_add_f32_e32 v64, v76, v85
	v_add_f32_e32 v65, v77, v86
	v_cvt_pk_bf16_f32 v69, v64, v65
	v_lshlrev_b32_e32 v64, 16, v66
	v_and_b32_e32 v65, 0xffff0000, v66
	v_fmac_f32_e32 v84, v64, v64
	v_lshlrev_b32_e32 v70, 16, v67
	v_fmac_f32_e32 v84, v65, v65
	v_and_b32_e32 v71, 0xffff0000, v67
	v_fmac_f32_e32 v84, v70, v70
	v_lshlrev_b32_e32 v76, 16, v68
	v_fmac_f32_e32 v84, v71, v71
	v_and_b32_e32 v77, 0xffff0000, v68
	v_fmac_f32_e32 v84, v76, v76
	v_lshlrev_b32_e32 v78, 16, v69
	v_fmac_f32_e32 v84, v77, v77
	v_and_b32_e32 v79, 0xffff0000, v69
	v_fmac_f32_e32 v84, v78, v78
	v_fmac_f32_e32 v84, v79, v79
	v_mov_b32_e32 v64, v84
	s_nop 1
	v_permlane16_swap_b32_e32 v64, v84
	v_lshl_add_u64 v[70:71], s[36:37], 0, v[104:105]
	v_lshl_add_u64 v[70:71], v[140:141], 1, v[70:71]
	global_store_dwordx4 v[70:71], v[72:75], off
	global_store_dwordx4 v[70:71], v[66:69], off offset:256
	s_waitcnt lgkmcnt(0)
	v_add_f32_e32 v64, v84, v64
	v_mov_b32_e32 v65, v64
	s_nop 1
	v_permlane32_swap_b32_e32 v65, v64
	s_and_saveexec_b64 s[22:23], s[10:11]
	s_cbranch_execz .LBB0_1216
	s_waitcnt lgkmcnt(0)
	v_add_f32_e32 v66, v64, v65
	v_lshl_add_u64 v[64:65], v[138:139], 2, s[4:5]
	global_atomic_add_f32 v[64:65], v66, off offset:192
;     __device__ __forceinline__ void operator()(const f32x4 (&acc)[2][2][4][2], const Unit& u, int wr, int wc, int fr, int fq) const {
;     ...
;                 u32x4 xin[2][2];
; #pragma unroll
;                 for (int mm = 0; mm < 2; ++mm)
; #pragma unroll
;                     for (int bj = 0; bj < 2; ++bj) xin[mm][bj] = *(const u32x4*)(X + (size_t)(row0 + ai * HALF + (mp * 2 + mm) * 16) * DM + col0 + bj * HALF);
;                 f32x4 pv[2][2][2];
; #pragma unroll
;                 for (int mm = 0; mm < 2; ++mm)
; #pragma unroll
;                     for (int bj = 0; bj < 2; ++bj)
; #pragma unroll
;                         for (int n = 0; n < 2; ++n) pv[mm][bj][n] = (f32x4){0.f, 0.f, 0.f, 0.f};
;                 if (src) {
;                     u32x4 pc[2][2];
;     ...
;                     asm volatile("global_load_dwordx4 %0, %4, off sc1\n\tglobal_load_dwordx4 %1, %5, off sc1\n\tglobal_load_dwordx4 %2, %6, off sc1\n\tglobal_load_dwordx4 %3, %7, off sc1\n\ts_waitcnt vmcnt(0)"
;                                  : "=&v"(pc[0][0]), "=&v"(pc[0][1]), "=&v"(pc[1][0]), "=&v"(pc[1][1])
;                                  : "v"(src + CI(0, 0)), "v"(src + CI(0, 1)), "v"(src + CI(1, 0)), "v"(src + CI(1, 1))
;                                  : "memory");
;     ...
; #pragma unroll
;                     for (int mm = 0; mm < 2; ++mm)
; #pragma unroll
;                         for (int bj = 0; bj < 2; ++bj) { float f[8]; unpack8(pc[mm][bj], f); pv[mm][bj][0] = (f32x4){f[0], f[1], f[2], f[3]}; pv[mm][bj][1] = (f32x4){f[4], f[5], f[6], f[7]}; }
;                 }
; #pragma unroll
;                 for (int mm = 0; mm < 2; ++mm) {
;                     const int m = mp * 2 + mm;
;                     const int row = row0 + ai * HALF + m * 16;
;                     float s = 0.f;
; #pragma unroll
;                     for (int bj = 0; bj < 2; ++bj) {
;                         u32x4* px = (u32x4*)(X + (size_t)row * DM + col0 + bj * HALF);
;                         float xo[8]; unpack8(xin[mm][bj], xo);
;                         const f32x4 a0 = acc[ai][bj][m][0] + pv[mm][bj][0], a1 = acc[ai][bj][m][1] + pv[mm][bj][1];
;                         u32x4 w;
;                         w.x = cvt_pk(xo[0] + scale * a0[0], xo[1] + scale * a0[1]); w.y = cvt_pk(xo[2] + scale * a0[2], xo[3] + scale * a0[3]);
.LBB0_1216:
	s_or_b64 exec, exec, s[22:23]
	s_mov_b64 s[22:23], 0x40000
	v_lshl_add_u64 v[74:75], v[154:155], 0, s[22:23]
	s_waitcnt lgkmcnt(0)
	v_lshl_add_u64 v[64:65], v[142:143], 0, v[74:75]
	global_load_dwordx4 v[76:79], v[64:65], off
	global_load_dwordx4 v[80:83], v[64:65], off offset:256
	s_mov_b64 s[22:23], 0x48000
	v_lshl_add_u64 v[72:73], v[154:155], 0, s[22:23]
	v_lshl_add_u64 v[64:65], v[142:143], 0, v[72:73]
	global_load_dwordx4 v[68:71], v[64:65], off
	s_nop 0
	global_load_dwordx4 v[64:67], v[64:65], off offset:256
	v_pk_add_f32 v[60:61], v[60:61], 0 op_sel_hi:[1,0]
	v_pk_add_f32 v[62:63], v[62:63], 0 op_sel_hi:[1,0]
	v_lshl_add_u64 v[74:75], s[36:37], 0, v[74:75]
	v_lshl_add_u64 v[74:75], v[140:141], 1, v[74:75]
	v_pk_add_f32 v[52:53], v[52:53], 0 op_sel_hi:[1,0]
	v_pk_add_f32 v[54:55], v[54:55], 0 op_sel_hi:[1,0]
	s_waitcnt vmcnt(3)
	v_lshlrev_b32_e32 v84, 16, v76
	v_and_b32_e32 v85, 0xffff0000, v76
	v_lshlrev_b32_e32 v86, 16, v77
	v_and_b32_e32 v87, 0xffff0000, v77
	v_lshlrev_b32_e32 v88, 16, v78
	v_and_b32_e32 v78, 0xffff0000, v78
	v_pk_add_f32 v[76:77], v[58:59], 0 op_sel_hi:[1,0]
	v_pk_add_f32 v[58:59], v[56:57], 0 op_sel_hi:[1,0]
	v_add_f32_e32 v56, v60, v84
	v_add_f32_e32 v57, v61, v85
	v_lshlrev_b32_e32 v89, 16, v79
	v_and_b32_e32 v79, 0xffff0000, v79
	v_cvt_pk_bf16_f32 v56, v56, v57
	v_add_f32_e32 v57, v62, v86
	v_add_f32_e32 v60, v63, v87
	v_add_f32_e32 v58, v58, v88
	v_add_f32_e32 v59, v59, v78
	v_cvt_pk_bf16_f32 v57, v57, v60
	v_cvt_pk_bf16_f32 v58, v58, v59
	v_add_f32_e32 v59, v76, v89
	v_add_f32_e32 v60, v77, v79
	v_cvt_pk_bf16_f32 v59, v59, v60
	global_store_dwordx4 v[74:75], v[56:59], off
	v_lshlrev_b32_e32 v60, 16, v56
	v_lshlrev_b32_e32 v61, 16, v57
	v_and_b32_e32 v56, 0xffff0000, v56
	v_mul_f32_e32 v76, v56, v56
	v_fmac_f32_e32 v76, v60, v60
	v_and_b32_e32 v57, 0xffff0000, v57
	v_fmac_f32_e32 v76, v61, v61
	v_lshlrev_b32_e32 v62, 16, v58
	v_fmac_f32_e32 v76, v57, v57
	v_and_b32_e32 v58, 0xffff0000, v58
	v_fmac_f32_e32 v76, v62, v62
	v_lshlrev_b32_e32 v63, 16, v59
	v_fmac_f32_e32 v76, v58, v58
	v_and_b32_e32 v59, 0xffff0000, v59
	v_fmac_f32_e32 v76, v63, v63
	v_fmac_f32_e32 v76, v59, v59
	s_waitcnt vmcnt(3)
	v_lshlrev_b32_e32 v58, 16, v80
	v_and_b32_e32 v59, 0xffff0000, v80
	v_lshlrev_b32_e32 v60, 16, v81
	v_and_b32_e32 v61, 0xffff0000, v81
	v_lshlrev_b32_e32 v62, 16, v82
	v_and_b32_e32 v63, 0xffff0000, v82
	v_pk_add_f32 v[56:57], v[50:51], 0 op_sel_hi:[1,0]
	v_pk_add_f32 v[50:51], v[48:49], 0 op_sel_hi:[1,0]
	v_add_f32_e32 v48, v52, v58
	v_add_f32_e32 v49, v53, v59
	v_lshlrev_b32_e32 v77, 16, v83
	v_and_b32_e32 v78, 0xffff0000, v83
	v_cvt_pk_bf16_f32 v48, v48, v49
	v_add_f32_e32 v49, v54, v60
	v_add_f32_e32 v52, v55, v61
	v_add_f32_e32 v50, v50, v62
	v_add_f32_e32 v51, v51, v63
	v_cvt_pk_bf16_f32 v49, v49, v52
	v_cvt_pk_bf16_f32 v50, v50, v51
	v_add_f32_e32 v51, v56, v77
	v_add_f32_e32 v52, v57, v78
	v_cvt_pk_bf16_f32 v51, v51, v52
	v_lshlrev_b32_e32 v52, 16, v48
	global_store_dwordx4 v[74:75], v[48:51], off offset:256
	v_fmac_f32_e32 v76, v52, v52
	v_lshlrev_b32_e32 v53, 16, v49
	v_and_b32_e32 v48, 0xffff0000, v48
	v_fmac_f32_e32 v76, v48, v48
	v_and_b32_e32 v49, 0xffff0000, v49
	v_fmac_f32_e32 v76, v53, v53
	v_lshlrev_b32_e32 v54, 16, v50
	v_fmac_f32_e32 v76, v49, v49
	v_and_b32_e32 v50, 0xffff0000, v50
	v_fmac_f32_e32 v76, v54, v54
	v_lshlrev_b32_e32 v55, 16, v51
	v_fmac_f32_e32 v76, v50, v50
	v_and_b32_e32 v51, 0xffff0000, v51
	v_fmac_f32_e32 v76, v55, v55
	v_fmac_f32_e32 v76, v51, v51
	v_mov_b32_e32 v48, v76
	s_nop 1
	v_permlane16_swap_b32_e32 v48, v76
	s_waitcnt lgkmcnt(0)
	v_add_f32_e32 v48, v76, v48
	v_mov_b32_e32 v49, v48
	s_nop 1
	v_permlane32_swap_b32_e32 v49, v48
	s_and_saveexec_b64 s[22:23], s[10:11]
	s_cbranch_execz .LBB0_1218
	s_waitcnt lgkmcnt(0)
	v_add_f32_e32 v50, v48, v49
	v_lshl_add_u64 v[48:49], v[138:139], 2, s[4:5]
	global_atomic_add_f32 v[48:49], v50, off offset:512
.LBB0_1218:
	s_or_b64 exec, exec, s[22:23]
	s_waitcnt vmcnt(3)
	v_lshlrev_b32_e32 v50, 16, v68
	v_and_b32_e32 v51, 0xffff0000, v68
	v_pk_add_f32 v[44:45], v[44:45], 0 op_sel_hi:[1,0]
	v_lshlrev_b32_e32 v52, 16, v69
	v_and_b32_e32 v53, 0xffff0000, v69
	v_lshlrev_b32_e32 v54, 16, v70
	v_and_b32_e32 v55, 0xffff0000, v70
	v_pk_add_f32 v[46:47], v[46:47], 0 op_sel_hi:[1,0]
	s_waitcnt lgkmcnt(0)
	v_pk_add_f32 v[48:49], v[42:43], 0 op_sel_hi:[1,0]
	v_pk_add_f32 v[42:43], v[40:41], 0 op_sel_hi:[1,0]
	v_add_f32_e32 v40, v44, v50
	v_add_f32_e32 v41, v45, v51
	v_lshlrev_b32_e32 v56, 16, v71
	v_and_b32_e32 v57, 0xffff0000, v71
	v_cvt_pk_bf16_f32 v40, v40, v41
	v_add_f32_e32 v41, v46, v52
	v_add_f32_e32 v44, v47, v53
	v_add_f32_e32 v42, v42, v54
	v_add_f32_e32 v43, v43, v55
	v_cvt_pk_bf16_f32 v41, v41, v44
	v_cvt_pk_bf16_f32 v42, v42, v43
	v_add_f32_e32 v43, v48, v56
	v_add_f32_e32 v44, v49, v57
	v_and_b32_e32 v45, 0xffff0000, v40
	v_cvt_pk_bf16_f32 v43, v43, v44
	v_lshlrev_b32_e32 v44, 16, v40
	v_mul_f32_e32 v52, v45, v45
	v_lshlrev_b32_e32 v46, 16, v41
	v_fmac_f32_e32 v52, v44, v44
	v_and_b32_e32 v47, 0xffff0000, v41
	v_fmac_f32_e32 v52, v46, v46
	v_lshlrev_b32_e32 v48, 16, v42
	v_fmac_f32_e32 v52, v47, v47
	v_and_b32_e32 v49, 0xffff0000, v42
	v_fmac_f32_e32 v52, v48, v48
	v_lshlrev_b32_e32 v50, 16, v43
	v_fmac_f32_e32 v52, v49, v49
	s_waitcnt vmcnt(2)
;     __device__ __forceinline__ void operator()(const f32x4 (&acc)[2][2][4][2], const Unit& u, int wr, int wc, int fr, int fq) const {
;     ...
;                 u32x4 xin[2][2];
; #pragma unroll
;                 for (int mm = 0; mm < 2; ++mm)
; #pragma unroll
;                     for (int bj = 0; bj < 2; ++bj) xin[mm][bj] = *(const u32x4*)(X + (size_t)(row0 + ai * HALF + (mp * 2 + mm) * 16) * DM + col0 + bj * HALF);
;                 f32x4 pv[2][2][2];
; #pragma unroll
;                 for (int mm = 0; mm < 2; ++mm)
; #pragma unroll
;                     for (int bj = 0; bj < 2; ++bj)
; #pragma unroll
;                         for (int n = 0; n < 2; ++n) pv[mm][bj][n] = (f32x4){0.f, 0.f, 0.f, 0.f};
;                 if (src) {
;                     u32x4 pc[2][2];
;     ...
;                     asm volatile("global_load_dwordx4 %0, %4, off sc1\n\tglobal_load_dwordx4 %1, %5, off sc1\n\tglobal_load_dwordx4 %2, %6, off sc1\n\tglobal_load_dwordx4 %3, %7, off sc1\n\ts_waitcnt vmcnt(0)"
;                                  : "=&v"(pc[0][0]), "=&v"(pc[0][1]), "=&v"(pc[1][0]), "=&v"(pc[1][1])
;                                  : "v"(src + CI(0, 0)), "v"(src + CI(0, 1)), "v"(src + CI(1, 0)), "v"(src + CI(1, 1))
;                                  : "memory");
;     ...
; #pragma unroll
;                     for (int mm = 0; mm < 2; ++mm)
; #pragma unroll
;                         for (int bj = 0; bj < 2; ++bj) { float f[8]; unpack8(pc[mm][bj], f); pv[mm][bj][0] = (f32x4){f[0], f[1], f[2], f[3]}; pv[mm][bj][1] = (f32x4){f[4], f[5], f[6], f[7]}; }
;                 }
; #pragma unroll
;                 for (int mm = 0; mm < 2; ++mm) {
;                     const int m = mp * 2 + mm;
;                     const int row = row0 + ai * HALF + m * 16;
;                     float s = 0.f;
; #pragma unroll
;                     for (int bj = 0; bj < 2; ++bj) {
;                         u32x4* px = (u32x4*)(X + (size_t)row * DM + col0 + bj * HALF);
;                         float xo[8]; unpack8(xin[mm][bj], xo);
;                         const f32x4 a0 = acc[ai][bj][m][0] + pv[mm][bj][0], a1 = acc[ai][bj][m][1] + pv[mm][bj][1];
;                         u32x4 w;
;                         w.x = cvt_pk(xo[0] + scale * a0[0], xo[1] + scale * a0[1]); w.y = cvt_pk(xo[2] + scale * a0[2], xo[3] + scale * a0[3]);
	v_lshlrev_b32_e32 v46, 16, v64
	v_and_b32_e32 v47, 0xffff0000, v64
	v_pk_add_f32 v[36:37], v[36:37], 0 op_sel_hi:[1,0]
	v_and_b32_e32 v51, 0xffff0000, v43
	v_fmac_f32_e32 v52, v50, v50
	v_lshlrev_b32_e32 v48, 16, v65
	v_and_b32_e32 v49, 0xffff0000, v65
	v_lshlrev_b32_e32 v50, 16, v66
	v_pk_add_f32 v[38:39], v[38:39], 0 op_sel_hi:[1,0]
	v_pk_add_f32 v[44:45], v[34:35], 0 op_sel_hi:[1,0]
	v_pk_add_f32 v[32:33], v[32:33], 0 op_sel_hi:[1,0]
	v_add_f32_e32 v34, v36, v46
	v_add_f32_e32 v35, v37, v47
	v_fmac_f32_e32 v52, v51, v51
	v_and_b32_e32 v51, 0xffff0000, v66
	v_lshlrev_b32_e32 v53, 16, v67
	v_cvt_pk_bf16_f32 v34, v34, v35
	v_add_f32_e32 v35, v38, v48
	v_add_f32_e32 v36, v39, v49
	v_add_f32_e32 v32, v32, v50
	v_and_b32_e32 v54, 0xffff0000, v67
	v_cvt_pk_bf16_f32 v35, v35, v36
	v_add_f32_e32 v33, v33, v51
	v_cvt_pk_bf16_f32 v36, v32, v33
	v_add_f32_e32 v32, v44, v53
	v_add_f32_e32 v33, v45, v54
	v_cvt_pk_bf16_f32 v37, v32, v33
	v_lshlrev_b32_e32 v32, 16, v34
	v_and_b32_e32 v33, 0xffff0000, v34
	v_fmac_f32_e32 v52, v32, v32
	v_lshlrev_b32_e32 v38, 16, v35
	v_fmac_f32_e32 v52, v33, v33
	v_and_b32_e32 v39, 0xffff0000, v35
	v_fmac_f32_e32 v52, v38, v38
	v_lshlrev_b32_e32 v44, 16, v36
	v_fmac_f32_e32 v52, v39, v39
	v_and_b32_e32 v45, 0xffff0000, v36
	v_fmac_f32_e32 v52, v44, v44
	v_lshlrev_b32_e32 v46, 16, v37
	v_fmac_f32_e32 v52, v45, v45
	v_and_b32_e32 v47, 0xffff0000, v37
	v_fmac_f32_e32 v52, v46, v46
	v_fmac_f32_e32 v52, v47, v47
	v_mov_b32_e32 v32, v52
	s_nop 1
	v_permlane16_swap_b32_e32 v32, v52
	v_lshl_add_u64 v[38:39], s[36:37], 0, v[72:73]
	v_lshl_add_u64 v[38:39], v[140:141], 1, v[38:39]
	global_store_dwordx4 v[38:39], v[40:43], off
	global_store_dwordx4 v[38:39], v[34:37], off offset:256
	s_waitcnt lgkmcnt(0)
	v_add_f32_e32 v32, v52, v32
	v_mov_b32_e32 v33, v32
	s_nop 1
	v_permlane32_swap_b32_e32 v33, v32
	s_and_saveexec_b64 s[22:23], s[10:11]
	s_cbranch_execz .LBB0_1220
	s_waitcnt lgkmcnt(0)
	v_add_f32_e32 v34, v32, v33
	v_lshl_add_u64 v[32:33], v[138:139], 2, s[4:5]
	global_atomic_add_f32 v[32:33], v34, off offset:576
.LBB0_1220:
	s_or_b64 exec, exec, s[22:23]
	s_mov_b64 s[22:23], 0x50000
	v_lshl_add_u64 v[42:43], v[154:155], 0, s[22:23]
	s_waitcnt lgkmcnt(0)
	v_lshl_add_u64 v[32:33], v[142:143], 0, v[42:43]
	global_load_dwordx4 v[44:47], v[32:33], off
	global_load_dwordx4 v[48:51], v[32:33], off offset:256
	s_mov_b64 s[22:23], 0x58000
	v_lshl_add_u64 v[40:41], v[154:155], 0, s[22:23]
	v_lshl_add_u64 v[32:33], v[142:143], 0, v[40:41]
	global_load_dwordx4 v[36:39], v[32:33], off
	s_nop 0
	global_load_dwordx4 v[32:35], v[32:33], off offset:256
	v_pk_add_f32 v[28:29], v[28:29], 0 op_sel_hi:[1,0]
	v_pk_add_f32 v[30:31], v[30:31], 0 op_sel_hi:[1,0]
	v_lshl_add_u64 v[42:43], s[36:37], 0, v[42:43]
	v_lshl_add_u64 v[42:43], v[140:141], 1, v[42:43]
	v_pk_add_f32 v[20:21], v[20:21], 0 op_sel_hi:[1,0]
	v_pk_add_f32 v[22:23], v[22:23], 0 op_sel_hi:[1,0]
	s_waitcnt vmcnt(3)
	v_lshlrev_b32_e32 v52, 16, v44
	v_and_b32_e32 v53, 0xffff0000, v44
	v_lshlrev_b32_e32 v54, 16, v45
	v_and_b32_e32 v55, 0xffff0000, v45
	v_lshlrev_b32_e32 v56, 16, v46
	v_and_b32_e32 v46, 0xffff0000, v46
	v_pk_add_f32 v[44:45], v[26:27], 0 op_sel_hi:[1,0]
	v_pk_add_f32 v[26:27], v[24:25], 0 op_sel_hi:[1,0]
	v_add_f32_e32 v24, v28, v52
	v_add_f32_e32 v25, v29, v53
	v_lshlrev_b32_e32 v57, 16, v47
	v_and_b32_e32 v47, 0xffff0000, v47
	v_cvt_pk_bf16_f32 v24, v24, v25
	v_add_f32_e32 v25, v30, v54
	v_add_f32_e32 v28, v31, v55
	v_add_f32_e32 v26, v26, v56
	v_add_f32_e32 v27, v27, v46
	v_cvt_pk_bf16_f32 v25, v25, v28
	v_cvt_pk_bf16_f32 v26, v26, v27
	v_add_f32_e32 v27, v44, v57
	v_add_f32_e32 v28, v45, v47
	v_cvt_pk_bf16_f32 v27, v27, v28
	global_store_dwordx4 v[42:43], v[24:27], off
	v_lshlrev_b32_e32 v28, 16, v24
	v_lshlrev_b32_e32 v29, 16, v25
	v_and_b32_e32 v24, 0xffff0000, v24
	v_mul_f32_e32 v44, v24, v24
	v_fmac_f32_e32 v44, v28, v28
	v_and_b32_e32 v25, 0xffff0000, v25
	v_fmac_f32_e32 v44, v29, v29
	v_lshlrev_b32_e32 v30, 16, v26
	v_fmac_f32_e32 v44, v25, v25
	v_and_b32_e32 v26, 0xffff0000, v26
	v_fmac_f32_e32 v44, v30, v30
	v_lshlrev_b32_e32 v31, 16, v27
	v_fmac_f32_e32 v44, v26, v26
	v_and_b32_e32 v27, 0xffff0000, v27
	v_fmac_f32_e32 v44, v31, v31
	v_fmac_f32_e32 v44, v27, v27
	s_waitcnt vmcnt(3)
	v_lshlrev_b32_e32 v26, 16, v48
	v_and_b32_e32 v27, 0xffff0000, v48
	v_lshlrev_b32_e32 v28, 16, v49
	v_and_b32_e32 v29, 0xffff0000, v49
	v_lshlrev_b32_e32 v30, 16, v50
	v_and_b32_e32 v31, 0xffff0000, v50
	v_pk_add_f32 v[24:25], v[18:19], 0 op_sel_hi:[1,0]
	v_pk_add_f32 v[18:19], v[16:17], 0 op_sel_hi:[1,0]
	v_add_f32_e32 v16, v20, v26
	v_add_f32_e32 v17, v21, v27
	v_lshlrev_b32_e32 v45, 16, v51
	v_and_b32_e32 v46, 0xffff0000, v51
	v_cvt_pk_bf16_f32 v16, v16, v17
	v_add_f32_e32 v17, v22, v28
	v_add_f32_e32 v20, v23, v29
	v_add_f32_e32 v18, v18, v30
	v_add_f32_e32 v19, v19, v31
	v_cvt_pk_bf16_f32 v17, v17, v20
	v_cvt_pk_bf16_f32 v18, v18, v19
	v_add_f32_e32 v19, v24, v45
	v_add_f32_e32 v20, v25, v46
	v_cvt_pk_bf16_f32 v19, v19, v20
	v_lshlrev_b32_e32 v20, 16, v16
	global_store_dwordx4 v[42:43], v[16:19], off offset:256
	v_fmac_f32_e32 v44, v20, v20
	v_lshlrev_b32_e32 v21, 16, v17
	v_and_b32_e32 v16, 0xffff0000, v16
	v_fmac_f32_e32 v44, v16, v16
	v_and_b32_e32 v17, 0xffff0000, v17
	v_fmac_f32_e32 v44, v21, v21
	v_lshlrev_b32_e32 v22, 16, v18
	v_fmac_f32_e32 v44, v17, v17
	v_and_b32_e32 v18, 0xffff0000, v18
	v_fmac_f32_e32 v44, v22, v22
	v_lshlrev_b32_e32 v23, 16, v19
	v_fmac_f32_e32 v44, v18, v18
	v_and_b32_e32 v19, 0xffff0000, v19
	v_fmac_f32_e32 v44, v23, v23
	v_fmac_f32_e32 v44, v19, v19
	v_mov_b32_e32 v16, v44
	s_nop 1
	v_permlane16_swap_b32_e32 v16, v44
	s_waitcnt lgkmcnt(0)
	v_add_f32_e32 v16, v44, v16
	v_mov_b32_e32 v17, v16
	s_nop 1
	v_permlane32_swap_b32_e32 v17, v16
	s_and_saveexec_b64 s[22:23], s[10:11]
	s_cbranch_execz .LBB0_1222
	s_waitcnt lgkmcnt(0)
	v_add_f32_e32 v18, v16, v17
	v_lshl_add_u64 v[16:17], v[138:139], 2, s[4:5]
	global_atomic_add_f32 v[16:17], v18, off offset:640
; DI unsigned cvt_pk(float lo, float hi) { unsigned r; asm("v_cvt_pk_bf16_f32 %0, %1, %2" : "=v"(r) : "v"(lo), "v"(hi)); return r; }
;     __device__ __forceinline__ void operator()(const f32x4 (&acc)[2][2][4][2], const Unit& u, int wr, int wc, int fr, int fq) const {
;     ...
; #pragma unroll
;                 for (int mm = 0; mm < 2; ++mm) {
;                     const int m = mp * 2 + mm;
;                     const int row = row0 + ai * HALF + m * 16;
;                     float s = 0.f;
; #pragma unroll
;                     for (int bj = 0; bj < 2; ++bj) {
;                         u32x4* px = (u32x4*)(X + (size_t)row * DM + col0 + bj * HALF);
;                         float xo[8]; unpack8(xin[mm][bj], xo);
;                         const f32x4 a0 = acc[ai][bj][m][0] + pv[mm][bj][0], a1 = acc[ai][bj][m][1] + pv[mm][bj][1];
;                         u32x4 w;
;                         w.x = cvt_pk(xo[0] + scale * a0[0], xo[1] + scale * a0[1]); w.y = cvt_pk(xo[2] + scale * a0[2], xo[3] + scale * a0[3]);
;                         w.z = cvt_pk(xo[4] + scale * a1[0], xo[5] + scale * a1[1]); w.w = cvt_pk(xo[6] + scale * a1[2], xo[7] + scale * a1[3]);
;                         *px = w;
;                         float xn[8]; unpack8(w, xn);
; #pragma unroll
;                         for (int j = 0; j < 8; ++j) s += xn[j] * xn[j];
;                     }
;                     s += __shfl_xor(s, 16); s += __shfl_xor(s, 32);
;                     if (fq == 0) unsafeAtomicAdd(ssn + row, s);
;                 }
.LBB0_1222:
	s_or_b64 exec, exec, s[22:23]
	s_waitcnt vmcnt(3)
	v_lshlrev_b32_e32 v18, 16, v36
	v_and_b32_e32 v19, 0xffff0000, v36
	v_pk_add_f32 v[12:13], v[12:13], 0 op_sel_hi:[1,0]
	v_lshlrev_b32_e32 v20, 16, v37
	v_and_b32_e32 v21, 0xffff0000, v37
	v_lshlrev_b32_e32 v22, 16, v38
	v_and_b32_e32 v23, 0xffff0000, v38
	v_pk_add_f32 v[14:15], v[14:15], 0 op_sel_hi:[1,0]
	s_waitcnt lgkmcnt(0)
	v_pk_add_f32 v[16:17], v[10:11], 0 op_sel_hi:[1,0]
	v_pk_add_f32 v[10:11], v[8:9], 0 op_sel_hi:[1,0]
	v_add_f32_e32 v8, v12, v18
	v_add_f32_e32 v9, v13, v19
	v_lshlrev_b32_e32 v24, 16, v39
	v_and_b32_e32 v25, 0xffff0000, v39
	v_cvt_pk_bf16_f32 v8, v8, v9
	v_add_f32_e32 v9, v14, v20
	v_add_f32_e32 v12, v15, v21
	v_add_f32_e32 v10, v10, v22
	v_add_f32_e32 v11, v11, v23
	v_cvt_pk_bf16_f32 v9, v9, v12
	v_cvt_pk_bf16_f32 v10, v10, v11
	v_add_f32_e32 v11, v16, v24
	v_add_f32_e32 v12, v17, v25
	v_and_b32_e32 v13, 0xffff0000, v8
	v_cvt_pk_bf16_f32 v11, v11, v12
	v_lshlrev_b32_e32 v12, 16, v8
	v_mul_f32_e32 v20, v13, v13
	v_lshlrev_b32_e32 v14, 16, v9
	v_fmac_f32_e32 v20, v12, v12
	v_and_b32_e32 v15, 0xffff0000, v9
	v_fmac_f32_e32 v20, v14, v14
	v_lshlrev_b32_e32 v16, 16, v10
	v_fmac_f32_e32 v20, v15, v15
	v_and_b32_e32 v17, 0xffff0000, v10
	v_fmac_f32_e32 v20, v16, v16
	v_lshlrev_b32_e32 v18, 16, v11
	v_fmac_f32_e32 v20, v17, v17
	s_waitcnt vmcnt(2)
	v_lshlrev_b32_e32 v14, 16, v32
	v_and_b32_e32 v15, 0xffff0000, v32
	v_pk_add_f32 v[4:5], v[4:5], 0 op_sel_hi:[1,0]
	v_and_b32_e32 v19, 0xffff0000, v11
	v_fmac_f32_e32 v20, v18, v18
	v_lshlrev_b32_e32 v16, 16, v33
	v_and_b32_e32 v17, 0xffff0000, v33
	v_lshlrev_b32_e32 v18, 16, v34
	v_pk_add_f32 v[6:7], v[6:7], 0 op_sel_hi:[1,0]
	v_pk_add_f32 v[12:13], v[2:3], 0 op_sel_hi:[1,0]
	v_pk_add_f32 v[0:1], v[0:1], 0 op_sel_hi:[1,0]
	v_add_f32_e32 v2, v4, v14
	v_add_f32_e32 v3, v5, v15
	v_fmac_f32_e32 v20, v19, v19
	v_and_b32_e32 v19, 0xffff0000, v34
	v_lshlrev_b32_e32 v21, 16, v35
	v_cvt_pk_bf16_f32 v2, v2, v3
	v_add_f32_e32 v3, v6, v16
	v_add_f32_e32 v4, v7, v17
	v_add_f32_e32 v0, v0, v18
	v_and_b32_e32 v22, 0xffff0000, v35
	v_cvt_pk_bf16_f32 v3, v3, v4
	v_add_f32_e32 v1, v1, v19
	v_cvt_pk_bf16_f32 v4, v0, v1
	v_add_f32_e32 v0, v12, v21
	v_add_f32_e32 v1, v13, v22
	v_cvt_pk_bf16_f32 v5, v0, v1
	v_lshlrev_b32_e32 v0, 16, v2
	v_and_b32_e32 v1, 0xffff0000, v2
	v_fmac_f32_e32 v20, v0, v0
	v_lshlrev_b32_e32 v6, 16, v3
	v_fmac_f32_e32 v20, v1, v1
	v_and_b32_e32 v7, 0xffff0000, v3
	v_fmac_f32_e32 v20, v6, v6
	v_lshlrev_b32_e32 v12, 16, v4
	v_fmac_f32_e32 v20, v7, v7
	v_and_b32_e32 v13, 0xffff0000, v4
	v_fmac_f32_e32 v20, v12, v12
	v_lshlrev_b32_e32 v14, 16, v5
	v_fmac_f32_e32 v20, v13, v13
	v_and_b32_e32 v15, 0xffff0000, v5
	v_fmac_f32_e32 v20, v14, v14
	v_fmac_f32_e32 v20, v15, v15
	v_mov_b32_e32 v0, v20
	s_nop 1
	v_permlane16_swap_b32_e32 v0, v20
	v_lshl_add_u64 v[6:7], s[36:37], 0, v[40:41]
	v_lshl_add_u64 v[6:7], v[140:141], 1, v[6:7]
	global_store_dwordx4 v[6:7], v[8:11], off
	global_store_dwordx4 v[6:7], v[2:5], off offset:256
	s_waitcnt lgkmcnt(0)
	v_add_f32_e32 v0, v20, v0
	v_mov_b32_e32 v1, v0
	s_nop 1
	v_permlane32_swap_b32_e32 v1, v0
	s_and_saveexec_b64 s[22:23], s[10:11]
	s_cbranch_execz .LBB0_1224
	s_waitcnt lgkmcnt(0)
	v_add_f32_e32 v2, v0, v1
	v_lshl_add_u64 v[0:1], v[138:139], 2, s[4:5]
	global_atomic_add_f32 v[0:1], v2, off offset:704

; DI unsigned cvt_pk(float lo, float hi) { unsigned r; asm("v_cvt_pk_bf16_f32 %0, %1, %2" : "=v"(r) : "v"(lo), "v"(hi)); return r; }
;     __device__ __forceinline__ void operator()(const f32x4 (&acc)[2][2][4][2], const Unit& u, int wr, int wc, int fr, int fq) const {
;     ...
; #pragma unroll
;                 for (int mm = 0; mm < 2; ++mm) {
;                     const int m = mp * 2 + mm;
;                     const int row = row0 + ai * HALF + m * 16;
;                     float s = 0.f;
; #pragma unroll
;                     for (int bj = 0; bj < 2; ++bj) {
;                         u32x4* px = (u32x4*)(X + (size_t)row * DM + col0 + bj * HALF);
;                         float xo[8]; unpack8(xin[mm][bj], xo);
;                         const f32x4 a0 = acc[ai][bj][m][0] + pv[mm][bj][0], a1 = acc[ai][bj][m][1] + pv[mm][bj][1];
;                         u32x4 w;
;                         w.x = cvt_pk(xo[0] + scale * a0[0], xo[1] + scale * a0[1]); w.y = cvt_pk(xo[2] + scale * a0[2], xo[3] + scale * a0[3]);
;                         w.z = cvt_pk(xo[4] + scale * a1[0], xo[5] + scale * a1[1]); w.w = cvt_pk(xo[6] + scale * a1[2], xo[7] + scale * a1[3]);
;                         *px = w;
;                         float xn[8]; unpack8(w, xn);
; #pragma unroll
;                         for (int j = 0; j < 8; ++j) s += xn[j] * xn[j];
;                     }
;                     s += __shfl_xor(s, 16); s += __shfl_xor(s, 32);
;                     if (fq == 0) unsafeAtomicAdd(ssn + row, s);
;                 }
.LBB0_1406:
	s_or_b64 exec, exec, s[12:13]
	s_waitcnt vmcnt(0)
	v_lshlrev_b32_e32 v210, 16, v140
	v_and_b32_e32 v211, 0xffff0000, v140
	v_lshlrev_b32_e32 v214, 16, v141
	v_and_b32_e32 v215, 0xffff0000, v141
	v_and_b32_e32 v238, 0xffff0000, v142
	v_pk_add_f32 v[140:141], v[124:125], v[206:207]
	v_pk_add_f32 v[202:203], v[120:121], v[202:203]
	v_lshlrev_b32_e32 v237, 16, v142
	v_fmac_f32_e32 v210, 0.5, v140
	v_fmac_f32_e32 v211, 0.5, v141
	v_cvt_pk_bf16_f32 v140, v210, v211
	v_fmac_f32_e32 v238, 0.5, v203
	v_and_b32_e32 v203, 0xffff0000, v140
	v_lshlrev_b32_e32 v244, 16, v143
	v_and_b32_e32 v245, 0xffff0000, v143
	v_pk_add_f32 v[142:143], v[126:127], v[208:209]
	v_pk_add_f32 v[204:205], v[122:123], v[204:205]
	v_fmac_f32_e32 v237, 0.5, v202
	v_lshlrev_b32_e32 v202, 16, v140
	v_mul_f32_e32 v203, v203, v203
	v_fmac_f32_e32 v214, 0.5, v142
	v_fmac_f32_e32 v215, 0.5, v143
	v_cvt_pk_bf16_f32 v141, v214, v215
	v_fmac_f32_e32 v244, 0.5, v204
	v_lshlrev_b32_e32 v204, 16, v141
	v_fmac_f32_e32 v203, v202, v202
	v_fmac_f32_e32 v245, 0.5, v205
	v_and_b32_e32 v205, 0xffff0000, v141
	v_fmac_f32_e32 v203, v204, v204
	v_cvt_pk_bf16_f32 v142, v237, v238
	v_fmac_f32_e32 v203, v205, v205
	v_lshlrev_b32_e32 v206, 16, v142
	v_and_b32_e32 v207, 0xffff0000, v142
	v_fmac_f32_e32 v203, v206, v206
	v_cvt_pk_bf16_f32 v143, v244, v245
	v_fmac_f32_e32 v203, v207, v207
	v_lshlrev_b32_e32 v208, 16, v143
	v_and_b32_e32 v209, 0xffff0000, v143
	v_fmac_f32_e32 v203, v208, v208
	v_fmac_f32_e32 v203, v209, v209
	v_lshlrev_b32_e32 v202, 16, v136
	v_and_b32_e32 v204, 0xffff0000, v136
	v_lshlrev_b32_e32 v205, 16, v137
	v_and_b32_e32 v206, 0xffff0000, v137
	v_lshlrev_b32_e32 v207, 16, v138
	v_and_b32_e32 v208, 0xffff0000, v138
	v_lshlrev_b32_e32 v209, 16, v139
	v_and_b32_e32 v210, 0xffff0000, v139
	v_pk_add_f32 v[136:137], v[94:95], v[200:201]
	v_pk_add_f32 v[138:139], v[92:93], v[198:199]
	v_pk_add_f32 v[198:199], v[90:91], v[196:197]
	v_pk_add_f32 v[196:197], v[88:89], v[194:195]
	v_fmac_f32_e32 v202, 0.5, v138
	v_fmac_f32_e32 v204, 0.5, v139
	v_cvt_pk_bf16_f32 v194, v202, v204
	v_fmac_f32_e32 v205, 0.5, v136
	v_lshlrev_b32_e32 v136, 16, v194
	v_fmac_f32_e32 v206, 0.5, v137
	v_and_b32_e32 v137, 0xffff0000, v194
	v_fmac_f32_e32 v203, v136, v136
	v_cvt_pk_bf16_f32 v195, v205, v206
	v_fmac_f32_e32 v203, v137, v137
	v_lshlrev_b32_e32 v138, 16, v195
	v_and_b32_e32 v139, 0xffff0000, v195
	v_fmac_f32_e32 v203, v138, v138
	v_fmac_f32_e32 v207, 0.5, v196
	v_fmac_f32_e32 v208, 0.5, v197
	v_cvt_pk_bf16_f32 v196, v207, v208
	v_fmac_f32_e32 v209, 0.5, v198
	v_lshlrev_b32_e32 v198, 16, v196
	v_fmac_f32_e32 v203, v139, v139
	v_and_b32_e32 v137, 64, v221
	v_fmac_f32_e32 v210, 0.5, v199
	v_and_b32_e32 v199, 0xffff0000, v196
	v_fmac_f32_e32 v203, v198, v198
	v_xor_b32_e32 v136, 16, v221
	v_add_u32_e32 v137, 64, v137
	v_cvt_pk_bf16_f32 v197, v209, v210
	v_fmac_f32_e32 v203, v199, v199
	v_lshlrev_b32_e32 v200, 16, v197
	v_cmp_lt_i32_e64 s[12:13], v136, v137
	v_and_b32_e32 v201, 0xffff0000, v197
	v_fmac_f32_e32 v203, v200, v200
	v_cndmask_b32_e64 v136, v221, v136, s[12:13]
	v_fmac_f32_e32 v203, v201, v201
	v_lshlrev_b32_e32 v237, 2, v136
	v_mov_b32_e32 v136, v203
	s_nop 1
	v_permlane16_swap_b32_e32 v136, v203
	v_xor_b32_e32 v138, 32, v221
	v_cmp_lt_i32_e64 s[12:13], v138, v137
	s_waitcnt lgkmcnt(0)
	v_add_f32_e32 v136, v203, v136
	v_cndmask_b32_e64 v137, v221, v138, s[12:13]
	v_lshlrev_b32_e32 v238, 2, v137
	v_mov_b32_e32 v137, v136
	s_nop 1
	v_permlane32_swap_b32_e32 v137, v136
	v_lshl_add_u64 v[138:139], s[28:29], 0, v[174:175]
	v_lshl_add_u64 v[138:139], v[168:169], 1, v[138:139]
	global_store_dwordx4 v[138:139], v[140:143], off
	global_store_dwordx4 v[138:139], v[194:197], off offset:256
	s_and_saveexec_b64 s[12:13], s[8:9]
	s_cbranch_execz .LBB0_1408
	s_waitcnt lgkmcnt(0)
	v_add_f32_e32 v138, v136, v137
	v_lshl_add_u64 v[136:137], v[166:167], 2, s[14:15]
	global_atomic_add_f32 v[136:137], v138, off
; DI unsigned cvt_pk(float lo, float hi) { unsigned r; asm("v_cvt_pk_bf16_f32 %0, %1, %2" : "=v"(r) : "v"(lo), "v"(hi)); return r; }
;     __device__ __forceinline__ void operator()(const f32x4 (&acc)[2][2][4][2], const Unit& u, int wr, int wc, int fr, int fq) const {
;     ...
; #pragma unroll
;                 for (int mm = 0; mm < 2; ++mm) {
;                     const int m = mp * 2 + mm;
;                     const int row = row0 + ai * HALF + m * 16;
;                     float s = 0.f;
; #pragma unroll
;                     for (int bj = 0; bj < 2; ++bj) {
;                         u32x4* px = (u32x4*)(X + (size_t)row * DM + col0 + bj * HALF);
;                         float xo[8]; unpack8(xin[mm][bj], xo);
;                         const f32x4 a0 = acc[ai][bj][m][0] + pv[mm][bj][0], a1 = acc[ai][bj][m][1] + pv[mm][bj][1];
;                         u32x4 w;
;                         w.x = cvt_pk(xo[0] + scale * a0[0], xo[1] + scale * a0[1]); w.y = cvt_pk(xo[2] + scale * a0[2], xo[3] + scale * a0[3]);
;                         w.z = cvt_pk(xo[4] + scale * a1[0], xo[5] + scale * a1[1]); w.w = cvt_pk(xo[6] + scale * a1[2], xo[7] + scale * a1[3]);
;                         *px = w;
;                         float xn[8]; unpack8(w, xn);
; #pragma unroll
;                         for (int j = 0; j < 8; ++j) s += xn[j] * xn[j];
;                     }
;                     s += __shfl_xor(s, 16); s += __shfl_xor(s, 32);
;                     if (fq == 0) unsafeAtomicAdd(ssn + row, s);
;                 }
.LBB0_1408:
	s_or_b64 exec, exec, s[12:13]
	v_lshlrev_b32_e32 v140, 16, v132
	v_and_b32_e32 v141, 0xffff0000, v132
	v_lshlrev_b32_e32 v142, 16, v133
	v_and_b32_e32 v143, 0xffff0000, v133
	v_and_b32_e32 v197, 0xffff0000, v135
	v_pk_add_f32 v[132:133], v[116:117], v[190:191]
	s_waitcnt lgkmcnt(0)
	v_pk_add_f32 v[136:137], v[114:115], v[188:189]
	v_lshlrev_b32_e32 v196, 16, v135
	v_fmac_f32_e32 v140, 0.5, v132
	v_fmac_f32_e32 v141, 0.5, v133
	v_cvt_pk_bf16_f32 v132, v140, v141
	v_fmac_f32_e32 v197, 0.5, v137
	v_and_b32_e32 v137, 0xffff0000, v132
	v_lshlrev_b32_e32 v194, 16, v134
	v_and_b32_e32 v195, 0xffff0000, v134
	v_pk_add_f32 v[134:135], v[118:119], v[192:193]
	v_pk_add_f32 v[138:139], v[112:113], v[186:187]
	v_fmac_f32_e32 v196, 0.5, v136
	v_lshlrev_b32_e32 v136, 16, v132
	v_mul_f32_e32 v186, v137, v137
	v_fmac_f32_e32 v142, 0.5, v134
	v_fmac_f32_e32 v143, 0.5, v135
	v_cvt_pk_bf16_f32 v133, v142, v143
	v_fmac_f32_e32 v194, 0.5, v138
	v_lshlrev_b32_e32 v138, 16, v133
	v_fmac_f32_e32 v186, v136, v136
	v_fmac_f32_e32 v195, 0.5, v139
	v_and_b32_e32 v139, 0xffff0000, v133
	v_fmac_f32_e32 v186, v138, v138
	v_cvt_pk_bf16_f32 v134, v194, v195
	v_fmac_f32_e32 v186, v139, v139
	v_lshlrev_b32_e32 v140, 16, v134
	v_and_b32_e32 v141, 0xffff0000, v134
	v_fmac_f32_e32 v186, v140, v140
	v_cvt_pk_bf16_f32 v135, v196, v197
	v_fmac_f32_e32 v186, v141, v141
	v_lshlrev_b32_e32 v142, 16, v135
	v_and_b32_e32 v143, 0xffff0000, v135
	v_fmac_f32_e32 v186, v142, v142
	v_lshlrev_b32_e32 v136, 16, v128
	v_lshlrev_b32_e32 v187, 16, v130
	v_and_b32_e32 v188, 0xffff0000, v130
	v_lshlrev_b32_e32 v189, 16, v131
	v_and_b32_e32 v190, 0xffff0000, v131
	v_pk_add_f32 v[130:131], v[84:85], v[182:183]
	v_fmac_f32_e32 v186, v143, v143
	v_and_b32_e32 v137, 0xffff0000, v128
	v_lshlrev_b32_e32 v142, 16, v129
	v_and_b32_e32 v143, 0xffff0000, v129
	v_pk_add_f32 v[128:129], v[86:87], v[184:185]
	v_fmac_f32_e32 v136, 0.5, v130
	v_fmac_f32_e32 v137, 0.5, v131
	v_cvt_pk_bf16_f32 v136, v136, v137
	v_fmac_f32_e32 v142, 0.5, v128
	v_lshlrev_b32_e32 v128, 16, v136
	v_fmac_f32_e32 v143, 0.5, v129
	v_and_b32_e32 v129, 0xffff0000, v136
	v_fmac_f32_e32 v186, v128, v128
	v_cvt_pk_bf16_f32 v137, v142, v143
	v_fmac_f32_e32 v186, v129, v129
	v_lshlrev_b32_e32 v130, 16, v137
	v_pk_add_f32 v[140:141], v[82:83], v[180:181]
	v_pk_add_f32 v[138:139], v[80:81], v[178:179]
	v_and_b32_e32 v131, 0xffff0000, v137
	v_fmac_f32_e32 v186, v130, v130
	v_fmac_f32_e32 v187, 0.5, v138
	v_fmac_f32_e32 v188, 0.5, v139
	v_cvt_pk_bf16_f32 v138, v187, v188
	v_fmac_f32_e32 v189, 0.5, v140
	v_lshlrev_b32_e32 v140, 16, v138
	v_fmac_f32_e32 v186, v131, v131
	v_fmac_f32_e32 v190, 0.5, v141
	v_and_b32_e32 v141, 0xffff0000, v138
	v_fmac_f32_e32 v186, v140, v140
	v_cvt_pk_bf16_f32 v139, v189, v190
	v_fmac_f32_e32 v186, v141, v141
	v_lshlrev_b32_e32 v142, 16, v139
	v_and_b32_e32 v143, 0xffff0000, v139
	v_fmac_f32_e32 v186, v142, v142
	v_fmac_f32_e32 v186, v143, v143
	v_mov_b32_e32 v128, v186
	s_nop 1
	v_permlane16_swap_b32_e32 v128, v186
	v_lshl_add_u64 v[130:131], s[28:29], 0, v[176:177]
	v_lshl_add_u64 v[130:131], v[168:169], 1, v[130:131]
	global_store_dwordx4 v[130:131], v[132:135], off
	global_store_dwordx4 v[130:131], v[136:139], off offset:256
	s_waitcnt lgkmcnt(0)
	v_add_f32_e32 v128, v186, v128
	v_mov_b32_e32 v129, v128
	s_nop 1
	v_permlane32_swap_b32_e32 v129, v128
	s_and_saveexec_b64 s[12:13], s[8:9]
	s_cbranch_execz .LBB0_1410
	s_waitcnt lgkmcnt(0)
	v_add_f32_e32 v130, v128, v129
	v_lshl_add_u64 v[128:129], v[166:167], 2, s[14:15]
	global_atomic_add_f32 v[128:129], v130, off offset:64

;     __device__ __forceinline__ void operator()(const f32x4 (&acc)[2][2][4][2], const Unit& u, int wr, int wc, int fr, int fq) const {
;     ...
;                 u32x4 xin[2][2];
; #pragma unroll
;                 for (int mm = 0; mm < 2; ++mm)
; #pragma unroll
;                     for (int bj = 0; bj < 2; ++bj) xin[mm][bj] = *(const u32x4*)(X + (size_t)(row0 + ai * HALF + (mp * 2 + mm) * 16) * DM + col0 + bj * HALF);
;                 f32x4 pv[2][2][2];
; #pragma unroll
;                 for (int mm = 0; mm < 2; ++mm)
; #pragma unroll
;                     for (int bj = 0; bj < 2; ++bj)
; #pragma unroll
;                         for (int n = 0; n < 2; ++n) pv[mm][bj][n] = (f32x4){0.f, 0.f, 0.f, 0.f};
;                 if (src) {
;                     u32x4 pc[2][2];
;     ...
;                     asm volatile("global_load_dwordx4 %0, %4, off sc1\n\tglobal_load_dwordx4 %1, %5, off sc1\n\tglobal_load_dwordx4 %2, %6, off sc1\n\tglobal_load_dwordx4 %3, %7, off sc1\n\ts_waitcnt vmcnt(0)"
;                                  : "=&v"(pc[0][0]), "=&v"(pc[0][1]), "=&v"(pc[1][0]), "=&v"(pc[1][1])
;                                  : "v"(src + CI(0, 0)), "v"(src + CI(0, 1)), "v"(src + CI(1, 0)), "v"(src + CI(1, 1))
;                                  : "memory");
;     ...
; #pragma unroll
;                     for (int mm = 0; mm < 2; ++mm)
; #pragma unroll
;                         for (int bj = 0; bj < 2; ++bj) { float f[8]; unpack8(pc[mm][bj], f); pv[mm][bj][0] = (f32x4){f[0], f[1], f[2], f[3]}; pv[mm][bj][1] = (f32x4){f[4], f[5], f[6], f[7]}; }
;                 }
; #pragma unroll
;                 for (int mm = 0; mm < 2; ++mm) {
;                     const int m = mp * 2 + mm;
;                     const int row = row0 + ai * HALF + m * 16;
;                     float s = 0.f;
; #pragma unroll
;                     for (int bj = 0; bj < 2; ++bj) {
;                         u32x4* px = (u32x4*)(X + (size_t)row * DM + col0 + bj * HALF);
;                         float xo[8]; unpack8(xin[mm][bj], xo);
;                         const f32x4 a0 = acc[ai][bj][m][0] + pv[mm][bj][0], a1 = acc[ai][bj][m][1] + pv[mm][bj][1];
;                         u32x4 w;
;                         w.x = cvt_pk(xo[0] + scale * a0[0], xo[1] + scale * a0[1]); w.y = cvt_pk(xo[2] + scale * a0[2], xo[3] + scale * a0[3]);
.LBB0_1412:
	s_or_b64 exec, exec, s[12:13]
	s_waitcnt vmcnt(0)
	s_mov_b64 s[30:31], 0x40000
	v_lshl_add_u64 v[250:251], v[174:175], 0, s[30:31]
	v_lshl_add_u64 v[250:251], v[172:173], 0, v[250:251]
	global_load_dwordx4 v[80:83], v[250:251], off
	global_load_dwordx4 v[84:87], v[250:251], off offset:256
	s_mov_b64 s[30:31], 0x48000
	v_lshl_add_u64 v[252:253], v[174:175], 0, s[30:31]
	v_lshl_add_u64 v[252:253], v[172:173], 0, v[252:253]
	global_load_dwordx4 v[88:91], v[252:253], off
	global_load_dwordx4 v[92:95], v[252:253], off offset:256
	s_and_saveexec_b64 s[12:13], vcc
	s_mov_b64 s[30:31], 0x2000
	v_lshl_add_u64 v[250:251], v[170:171], 0, s[30:31]
	global_load_dwordx4 v[112:115], v[250:251], off sc1
	s_mov_b64 s[30:31], 0x3000
	v_lshl_add_u64 v[252:253], v[170:171], 0, s[30:31]
	global_load_dwordx4 v[116:119], v[252:253], off sc1
	s_mov_b64 s[30:31], 0x2400
	v_lshl_add_u64 v[250:251], v[170:171], 0, s[30:31]
	global_load_dwordx4 v[120:123], v[250:251], off sc1
	s_mov_b64 s[30:31], 0x3400
	v_lshl_add_u64 v[252:253], v[170:171], 0, s[30:31]
	global_load_dwordx4 v[124:127], v[252:253], off sc1
	s_or_b64 exec, exec, s[12:13]
	v_lshlrev_b32_e32 v214, 16, v140
	v_and_b32_e32 v215, 0xffff0000, v140
	v_lshlrev_b32_e32 v244, 16, v141
	v_and_b32_e32 v245, 0xffff0000, v141
	v_and_b32_e32 v247, 0xffff0000, v142
	v_pk_add_f32 v[140:141], v[108:109], v[208:209]
	v_pk_add_f32 v[204:205], v[104:105], v[204:205]
	v_lshlrev_b32_e32 v246, 16, v142
	v_fmac_f32_e32 v214, 0.5, v140
	v_fmac_f32_e32 v215, 0.5, v141
	v_cvt_pk_bf16_f32 v140, v214, v215
	v_fmac_f32_e32 v247, 0.5, v205
	v_and_b32_e32 v205, 0xffff0000, v140
	v_lshlrev_b32_e32 v248, 16, v143
	v_and_b32_e32 v249, 0xffff0000, v143
	v_pk_add_f32 v[142:143], v[110:111], v[210:211]
	v_pk_add_f32 v[206:207], v[106:107], v[206:207]
	v_fmac_f32_e32 v246, 0.5, v204
	v_lshlrev_b32_e32 v204, 16, v140
	v_mul_f32_e32 v205, v205, v205
	v_fmac_f32_e32 v244, 0.5, v142
	v_fmac_f32_e32 v245, 0.5, v143
	v_cvt_pk_bf16_f32 v141, v244, v245
	v_fmac_f32_e32 v248, 0.5, v206
	v_lshlrev_b32_e32 v206, 16, v141
	v_fmac_f32_e32 v205, v204, v204
	v_fmac_f32_e32 v249, 0.5, v207
	v_and_b32_e32 v207, 0xffff0000, v141
	v_fmac_f32_e32 v205, v206, v206
	v_cvt_pk_bf16_f32 v142, v246, v247
	v_fmac_f32_e32 v205, v207, v207
	v_lshlrev_b32_e32 v208, 16, v142
	v_and_b32_e32 v209, 0xffff0000, v142
	v_fmac_f32_e32 v205, v208, v208
	v_cvt_pk_bf16_f32 v143, v248, v249
	v_fmac_f32_e32 v205, v209, v209
	v_lshlrev_b32_e32 v210, 16, v143
	v_and_b32_e32 v211, 0xffff0000, v143
	v_fmac_f32_e32 v205, v210, v210
	v_fmac_f32_e32 v205, v211, v211
	v_lshlrev_b32_e32 v204, 16, v136
	v_and_b32_e32 v206, 0xffff0000, v136
	v_lshlrev_b32_e32 v207, 16, v137
	v_and_b32_e32 v208, 0xffff0000, v137
	v_lshlrev_b32_e32 v209, 16, v138
	v_and_b32_e32 v210, 0xffff0000, v138
	v_lshlrev_b32_e32 v211, 16, v139
	v_and_b32_e32 v214, 0xffff0000, v139
	v_pk_add_f32 v[136:137], v[78:79], v[202:203]
	v_pk_add_f32 v[138:139], v[76:77], v[200:201]
	v_pk_add_f32 v[200:201], v[74:75], v[198:199]
	v_pk_add_f32 v[198:199], v[72:73], v[196:197]
	v_fmac_f32_e32 v204, 0.5, v138
	v_fmac_f32_e32 v206, 0.5, v139
	v_cvt_pk_bf16_f32 v196, v204, v206
	v_fmac_f32_e32 v207, 0.5, v136
	v_lshlrev_b32_e32 v136, 16, v196
	v_fmac_f32_e32 v208, 0.5, v137
	v_and_b32_e32 v137, 0xffff0000, v196
	v_fmac_f32_e32 v205, v136, v136
	v_cvt_pk_bf16_f32 v197, v207, v208
	v_fmac_f32_e32 v205, v137, v137
	v_lshlrev_b32_e32 v138, 16, v197
	v_and_b32_e32 v139, 0xffff0000, v197
	v_fmac_f32_e32 v205, v138, v138
	v_fmac_f32_e32 v209, 0.5, v198
	v_fmac_f32_e32 v210, 0.5, v199
	v_cvt_pk_bf16_f32 v198, v209, v210
	v_fmac_f32_e32 v211, 0.5, v200
	v_lshlrev_b32_e32 v200, 16, v198
	v_fmac_f32_e32 v205, v139, v139
	v_fmac_f32_e32 v214, 0.5, v201
	v_and_b32_e32 v201, 0xffff0000, v198
	v_fmac_f32_e32 v205, v200, v200
	v_cvt_pk_bf16_f32 v199, v211, v214
	v_fmac_f32_e32 v205, v201, v201
	v_lshlrev_b32_e32 v202, 16, v199
	v_and_b32_e32 v203, 0xffff0000, v199
	v_fmac_f32_e32 v205, v202, v202
	v_fmac_f32_e32 v205, v203, v203
	v_mov_b32_e32 v136, v205
	s_nop 1
	v_permlane16_swap_b32_e32 v136, v205
	v_lshl_add_u64 v[138:139], s[28:29], 0, v[186:187]
	v_lshl_add_u64 v[138:139], v[168:169], 1, v[138:139]
	global_store_dwordx4 v[138:139], v[140:143], off
	global_store_dwordx4 v[138:139], v[196:199], off offset:256
	s_waitcnt lgkmcnt(0)
	v_add_f32_e32 v136, v205, v136
	v_mov_b32_e32 v137, v136
	s_nop 1
	v_permlane32_swap_b32_e32 v137, v136
	s_and_saveexec_b64 s[12:13], s[8:9]
	s_cbranch_execz .LBB0_1414
	s_waitcnt lgkmcnt(0)
	v_add_f32_e32 v138, v136, v137
	v_lshl_add_u64 v[136:137], v[166:167], 2, s[14:15]
	global_atomic_add_f32 v[136:137], v138, off offset:128
; DI unsigned cvt_pk(float lo, float hi) { unsigned r; asm("v_cvt_pk_bf16_f32 %0, %1, %2" : "=v"(r) : "v"(lo), "v"(hi)); return r; }
;     __device__ __forceinline__ void operator()(const f32x4 (&acc)[2][2][4][2], const Unit& u, int wr, int wc, int fr, int fq) const {
;     ...
; #pragma unroll
;                 for (int mm = 0; mm < 2; ++mm) {
;                     const int m = mp * 2 + mm;
;                     const int row = row0 + ai * HALF + m * 16;
;                     float s = 0.f;
; #pragma unroll
;                     for (int bj = 0; bj < 2; ++bj) {
;                         u32x4* px = (u32x4*)(X + (size_t)row * DM + col0 + bj * HALF);
;                         float xo[8]; unpack8(xin[mm][bj], xo);
;                         const f32x4 a0 = acc[ai][bj][m][0] + pv[mm][bj][0], a1 = acc[ai][bj][m][1] + pv[mm][bj][1];
;                         u32x4 w;
;                         w.x = cvt_pk(xo[0] + scale * a0[0], xo[1] + scale * a0[1]); w.y = cvt_pk(xo[2] + scale * a0[2], xo[3] + scale * a0[3]);
;                         w.z = cvt_pk(xo[4] + scale * a1[0], xo[5] + scale * a1[1]); w.w = cvt_pk(xo[6] + scale * a1[2], xo[7] + scale * a1[3]);
;                         *px = w;
;                         float xn[8]; unpack8(w, xn);
; #pragma unroll
;                         for (int j = 0; j < 8; ++j) s += xn[j] * xn[j];
;                     }
;                     s += __shfl_xor(s, 16); s += __shfl_xor(s, 32);
;                     if (fq == 0) unsafeAtomicAdd(ssn + row, s);
;                 }
.LBB0_1414:
	s_or_b64 exec, exec, s[12:13]
	v_lshlrev_b32_e32 v140, 16, v132
	v_and_b32_e32 v141, 0xffff0000, v132
	v_lshlrev_b32_e32 v142, 16, v133
	v_and_b32_e32 v143, 0xffff0000, v133
	v_lshlrev_b32_e32 v186, 16, v134
	v_and_b32_e32 v197, 0xffff0000, v135
	v_pk_add_f32 v[132:133], v[100:101], v[192:193]
	s_waitcnt lgkmcnt(0)
	v_pk_add_f32 v[136:137], v[98:99], v[190:191]
	v_pk_add_f32 v[138:139], v[96:97], v[188:189]
	v_and_b32_e32 v187, 0xffff0000, v134
	v_lshlrev_b32_e32 v196, 16, v135
	v_pk_add_f32 v[134:135], v[102:103], v[194:195]
	v_fmac_f32_e32 v140, 0.5, v132
	v_fmac_f32_e32 v141, 0.5, v133
	v_cvt_pk_bf16_f32 v132, v140, v141
	v_fmac_f32_e32 v186, 0.5, v138
	v_fmac_f32_e32 v197, 0.5, v137
	v_and_b32_e32 v137, 0xffff0000, v132
	v_fmac_f32_e32 v142, 0.5, v134
	v_fmac_f32_e32 v187, 0.5, v139
	v_cvt_pk_bf16_f32 v134, v186, v187
	v_fmac_f32_e32 v196, 0.5, v136
	v_lshlrev_b32_e32 v136, 16, v132
	v_mul_f32_e32 v186, v137, v137
	v_fmac_f32_e32 v143, 0.5, v135
	v_cvt_pk_bf16_f32 v133, v142, v143
	v_fmac_f32_e32 v186, v136, v136
	v_lshlrev_b32_e32 v138, 16, v133
	v_and_b32_e32 v139, 0xffff0000, v133
	v_fmac_f32_e32 v186, v138, v138
	v_lshlrev_b32_e32 v140, 16, v134
	v_fmac_f32_e32 v186, v139, v139
	v_and_b32_e32 v141, 0xffff0000, v134
	v_fmac_f32_e32 v186, v140, v140
	v_cvt_pk_bf16_f32 v135, v196, v197
	v_fmac_f32_e32 v186, v141, v141
	v_lshlrev_b32_e32 v142, 16, v135
	v_and_b32_e32 v143, 0xffff0000, v135
	v_fmac_f32_e32 v186, v142, v142
	v_lshlrev_b32_e32 v136, 16, v128
	v_lshlrev_b32_e32 v187, 16, v130
	v_and_b32_e32 v188, 0xffff0000, v130
	v_lshlrev_b32_e32 v189, 16, v131
	v_and_b32_e32 v190, 0xffff0000, v131
	v_pk_add_f32 v[130:131], v[68:69], v[182:183]
	v_fmac_f32_e32 v186, v143, v143
	v_and_b32_e32 v137, 0xffff0000, v128
	v_lshlrev_b32_e32 v142, 16, v129
	v_and_b32_e32 v143, 0xffff0000, v129
	v_pk_add_f32 v[128:129], v[70:71], v[184:185]
	v_fmac_f32_e32 v136, 0.5, v130
	v_fmac_f32_e32 v137, 0.5, v131
	v_cvt_pk_bf16_f32 v136, v136, v137
	v_fmac_f32_e32 v142, 0.5, v128
	v_lshlrev_b32_e32 v128, 16, v136
	v_fmac_f32_e32 v143, 0.5, v129
	v_and_b32_e32 v129, 0xffff0000, v136
	v_fmac_f32_e32 v186, v128, v128
	v_cvt_pk_bf16_f32 v137, v142, v143
	v_fmac_f32_e32 v186, v129, v129
	v_lshlrev_b32_e32 v130, 16, v137
	v_pk_add_f32 v[140:141], v[66:67], v[180:181]
	v_pk_add_f32 v[138:139], v[64:65], v[178:179]
	v_and_b32_e32 v131, 0xffff0000, v137
	v_fmac_f32_e32 v186, v130, v130
	v_fmac_f32_e32 v187, 0.5, v138
	v_fmac_f32_e32 v188, 0.5, v139
	v_cvt_pk_bf16_f32 v138, v187, v188
	v_fmac_f32_e32 v189, 0.5, v140
	v_lshlrev_b32_e32 v140, 16, v138
	v_fmac_f32_e32 v186, v131, v131
	v_fmac_f32_e32 v190, 0.5, v141
	v_and_b32_e32 v141, 0xffff0000, v138
	v_fmac_f32_e32 v186, v140, v140
	v_cvt_pk_bf16_f32 v139, v189, v190
	v_fmac_f32_e32 v186, v141, v141
	v_lshlrev_b32_e32 v142, 16, v139
	v_and_b32_e32 v143, 0xffff0000, v139
	v_fmac_f32_e32 v186, v142, v142
	v_fmac_f32_e32 v186, v143, v143
	v_mov_b32_e32 v128, v186
	s_nop 1
	v_permlane16_swap_b32_e32 v128, v186
	v_lshl_add_u64 v[130:131], s[28:29], 0, v[176:177]
	v_lshl_add_u64 v[130:131], v[168:169], 1, v[130:131]
	global_store_dwordx4 v[130:131], v[132:135], off
	global_store_dwordx4 v[130:131], v[136:139], off offset:256
	s_waitcnt lgkmcnt(0)
	v_add_f32_e32 v128, v186, v128
	v_mov_b32_e32 v129, v128
	s_nop 1
	v_permlane32_swap_b32_e32 v129, v128
	s_and_saveexec_b64 s[12:13], s[8:9]
	s_cbranch_execz .LBB0_1416
	s_waitcnt lgkmcnt(0)
	v_add_f32_e32 v130, v128, v129
	v_lshl_add_u64 v[128:129], v[166:167], 2, s[14:15]
	global_atomic_add_f32 v[128:129], v130, off offset:192

;     __device__ __forceinline__ void operator()(const f32x4 (&acc)[2][2][4][2], const Unit& u, int wr, int wc, int fr, int fq) const {
;     ...
;                 u32x4 xin[2][2];
; #pragma unroll
;                 for (int mm = 0; mm < 2; ++mm)
; #pragma unroll
;                     for (int bj = 0; bj < 2; ++bj) xin[mm][bj] = *(const u32x4*)(X + (size_t)(row0 + ai * HALF + (mp * 2 + mm) * 16) * DM + col0 + bj * HALF);
;                 f32x4 pv[2][2][2];
; #pragma unroll
;                 for (int mm = 0; mm < 2; ++mm)
; #pragma unroll
;                     for (int bj = 0; bj < 2; ++bj)
; #pragma unroll
;                         for (int n = 0; n < 2; ++n) pv[mm][bj][n] = (f32x4){0.f, 0.f, 0.f, 0.f};
;                 if (src) {
;                     u32x4 pc[2][2];
;     ...
;                     asm volatile("global_load_dwordx4 %0, %4, off sc1\n\tglobal_load_dwordx4 %1, %5, off sc1\n\tglobal_load_dwordx4 %2, %6, off sc1\n\tglobal_load_dwordx4 %3, %7, off sc1\n\ts_waitcnt vmcnt(0)"
;                                  : "=&v"(pc[0][0]), "=&v"(pc[0][1]), "=&v"(pc[1][0]), "=&v"(pc[1][1])
;                                  : "v"(src + CI(0, 0)), "v"(src + CI(0, 1)), "v"(src + CI(1, 0)), "v"(src + CI(1, 1))
;                                  : "memory");
;     ...
; #pragma unroll
;                     for (int mm = 0; mm < 2; ++mm)
; #pragma unroll
;                         for (int bj = 0; bj < 2; ++bj) { float f[8]; unpack8(pc[mm][bj], f); pv[mm][bj][0] = (f32x4){f[0], f[1], f[2], f[3]}; pv[mm][bj][1] = (f32x4){f[4], f[5], f[6], f[7]}; }
;                 }
; #pragma unroll
;                 for (int mm = 0; mm < 2; ++mm) {
;                     const int m = mp * 2 + mm;
;                     const int row = row0 + ai * HALF + m * 16;
;                     float s = 0.f;
; #pragma unroll
;                     for (int bj = 0; bj < 2; ++bj) {
;                         u32x4* px = (u32x4*)(X + (size_t)row * DM + col0 + bj * HALF);
;                         float xo[8]; unpack8(xin[mm][bj], xo);
;                         const f32x4 a0 = acc[ai][bj][m][0] + pv[mm][bj][0], a1 = acc[ai][bj][m][1] + pv[mm][bj][1];
;                         u32x4 w;
;                         w.x = cvt_pk(xo[0] + scale * a0[0], xo[1] + scale * a0[1]); w.y = cvt_pk(xo[2] + scale * a0[2], xo[3] + scale * a0[3]);
.LBB0_1418:
	s_or_b64 exec, exec, s[12:13]
	s_mov_b64 s[30:31], 0x50000
	v_lshl_add_u64 v[250:251], v[174:175], 0, s[30:31]
	v_lshl_add_u64 v[250:251], v[172:173], 0, v[250:251]
	global_load_dwordx4 v[64:67], v[250:251], off
	global_load_dwordx4 v[68:71], v[250:251], off offset:256
	s_mov_b64 s[30:31], 0x58000
	v_lshl_add_u64 v[252:253], v[174:175], 0, s[30:31]
	v_lshl_add_u64 v[252:253], v[172:173], 0, v[252:253]
	global_load_dwordx4 v[72:75], v[252:253], off
	global_load_dwordx4 v[76:79], v[252:253], off offset:256
	s_and_saveexec_b64 s[12:13], vcc
	s_mov_b64 s[30:31], 0x2800
	v_lshl_add_u64 v[250:251], v[170:171], 0, s[30:31]
	global_load_dwordx4 v[96:99], v[250:251], off sc1
	s_mov_b64 s[30:31], 0x3800
	v_lshl_add_u64 v[252:253], v[170:171], 0, s[30:31]
	global_load_dwordx4 v[100:103], v[252:253], off sc1
	s_mov_b64 s[30:31], 0x2c00
	v_lshl_add_u64 v[250:251], v[170:171], 0, s[30:31]
	global_load_dwordx4 v[104:107], v[250:251], off sc1
	s_mov_b64 s[30:31], 0x3c00
	v_lshl_add_u64 v[252:253], v[170:171], 0, s[30:31]
	global_load_dwordx4 v[108:111], v[252:253], off sc1
	s_or_b64 exec, exec, s[12:13]
	v_lshlrev_b32_e32 v214, 16, v140
	v_and_b32_e32 v215, 0xffff0000, v140
	v_lshlrev_b32_e32 v244, 16, v141
	v_and_b32_e32 v245, 0xffff0000, v141
	v_and_b32_e32 v247, 0xffff0000, v142
	v_pk_add_f32 v[140:141], v[60:61], v[208:209]
	v_pk_add_f32 v[204:205], v[56:57], v[204:205]
	v_lshlrev_b32_e32 v246, 16, v142
	v_fmac_f32_e32 v214, 0.5, v140
	v_fmac_f32_e32 v215, 0.5, v141
	v_cvt_pk_bf16_f32 v140, v214, v215
	v_fmac_f32_e32 v247, 0.5, v205
	v_and_b32_e32 v205, 0xffff0000, v140
	v_lshlrev_b32_e32 v248, 16, v143
	v_and_b32_e32 v249, 0xffff0000, v143
	v_pk_add_f32 v[142:143], v[62:63], v[210:211]
	v_pk_add_f32 v[206:207], v[58:59], v[206:207]
	v_fmac_f32_e32 v246, 0.5, v204
	v_lshlrev_b32_e32 v204, 16, v140
	v_mul_f32_e32 v205, v205, v205
	v_fmac_f32_e32 v244, 0.5, v142
	v_fmac_f32_e32 v245, 0.5, v143
	v_cvt_pk_bf16_f32 v141, v244, v245
	v_fmac_f32_e32 v248, 0.5, v206
	v_lshlrev_b32_e32 v206, 16, v141
	v_fmac_f32_e32 v205, v204, v204
	v_fmac_f32_e32 v249, 0.5, v207
	v_and_b32_e32 v207, 0xffff0000, v141
	v_fmac_f32_e32 v205, v206, v206
	v_cvt_pk_bf16_f32 v142, v246, v247
	v_fmac_f32_e32 v205, v207, v207
	v_lshlrev_b32_e32 v208, 16, v142
	v_and_b32_e32 v209, 0xffff0000, v142
	v_fmac_f32_e32 v205, v208, v208
	v_cvt_pk_bf16_f32 v143, v248, v249
	v_fmac_f32_e32 v205, v209, v209
	v_lshlrev_b32_e32 v210, 16, v143
	v_and_b32_e32 v211, 0xffff0000, v143
	v_fmac_f32_e32 v205, v210, v210
	v_fmac_f32_e32 v205, v211, v211
	v_lshlrev_b32_e32 v204, 16, v136
	v_and_b32_e32 v206, 0xffff0000, v136
	v_lshlrev_b32_e32 v207, 16, v137
	v_and_b32_e32 v208, 0xffff0000, v137
	v_lshlrev_b32_e32 v209, 16, v138
	v_and_b32_e32 v210, 0xffff0000, v138
	v_lshlrev_b32_e32 v211, 16, v139
	v_and_b32_e32 v214, 0xffff0000, v139
	v_pk_add_f32 v[136:137], v[30:31], v[202:203]
	v_pk_add_f32 v[138:139], v[28:29], v[200:201]
	v_pk_add_f32 v[200:201], v[26:27], v[198:199]
	v_pk_add_f32 v[198:199], v[24:25], v[196:197]
	v_fmac_f32_e32 v204, 0.5, v138
	v_fmac_f32_e32 v206, 0.5, v139
	v_cvt_pk_bf16_f32 v196, v204, v206
	v_fmac_f32_e32 v207, 0.5, v136
	v_lshlrev_b32_e32 v136, 16, v196
	v_fmac_f32_e32 v208, 0.5, v137
	v_and_b32_e32 v137, 0xffff0000, v196
	v_fmac_f32_e32 v205, v136, v136
	v_cvt_pk_bf16_f32 v197, v207, v208
	v_fmac_f32_e32 v205, v137, v137
	v_lshlrev_b32_e32 v138, 16, v197
	v_and_b32_e32 v139, 0xffff0000, v197
	v_fmac_f32_e32 v205, v138, v138
	v_fmac_f32_e32 v209, 0.5, v198
	v_fmac_f32_e32 v210, 0.5, v199
	v_cvt_pk_bf16_f32 v198, v209, v210
	v_fmac_f32_e32 v211, 0.5, v200
	v_lshlrev_b32_e32 v200, 16, v198
	v_fmac_f32_e32 v205, v139, v139
	v_fmac_f32_e32 v214, 0.5, v201
	v_and_b32_e32 v201, 0xffff0000, v198
	v_fmac_f32_e32 v205, v200, v200
	v_cvt_pk_bf16_f32 v199, v211, v214
	v_fmac_f32_e32 v205, v201, v201
	v_lshlrev_b32_e32 v202, 16, v199
	v_and_b32_e32 v203, 0xffff0000, v199
	v_fmac_f32_e32 v205, v202, v202
	v_fmac_f32_e32 v205, v203, v203
	v_mov_b32_e32 v136, v205
	s_nop 1
	v_permlane16_swap_b32_e32 v136, v205
	v_lshl_add_u64 v[138:139], s[28:29], 0, v[186:187]
	v_lshl_add_u64 v[138:139], v[168:169], 1, v[138:139]
	global_store_dwordx4 v[138:139], v[140:143], off
	global_store_dwordx4 v[138:139], v[196:199], off offset:256
	s_waitcnt lgkmcnt(0)
	v_add_f32_e32 v136, v205, v136
	v_mov_b32_e32 v137, v136
	s_nop 1
	v_permlane32_swap_b32_e32 v137, v136
	s_and_saveexec_b64 s[12:13], s[8:9]
	s_cbranch_execz .LBB0_1420
	s_waitcnt lgkmcnt(0)
	v_add_f32_e32 v138, v136, v137
	v_lshl_add_u64 v[136:137], v[166:167], 2, s[14:15]
	global_atomic_add_f32 v[136:137], v138, off offset:512
; DI unsigned cvt_pk(float lo, float hi) { unsigned r; asm("v_cvt_pk_bf16_f32 %0, %1, %2" : "=v"(r) : "v"(lo), "v"(hi)); return r; }
;     __device__ __forceinline__ void operator()(const f32x4 (&acc)[2][2][4][2], const Unit& u, int wr, int wc, int fr, int fq) const {
;     ...
; #pragma unroll
;                 for (int mm = 0; mm < 2; ++mm) {
;                     const int m = mp * 2 + mm;
;                     const int row = row0 + ai * HALF + m * 16;
;                     float s = 0.f;
; #pragma unroll
;                     for (int bj = 0; bj < 2; ++bj) {
;                         u32x4* px = (u32x4*)(X + (size_t)row * DM + col0 + bj * HALF);
;                         float xo[8]; unpack8(xin[mm][bj], xo);
;                         const f32x4 a0 = acc[ai][bj][m][0] + pv[mm][bj][0], a1 = acc[ai][bj][m][1] + pv[mm][bj][1];
;                         u32x4 w;
;                         w.x = cvt_pk(xo[0] + scale * a0[0], xo[1] + scale * a0[1]); w.y = cvt_pk(xo[2] + scale * a0[2], xo[3] + scale * a0[3]);
;                         w.z = cvt_pk(xo[4] + scale * a1[0], xo[5] + scale * a1[1]); w.w = cvt_pk(xo[6] + scale * a1[2], xo[7] + scale * a1[3]);
;                         *px = w;
;                         float xn[8]; unpack8(w, xn);
; #pragma unroll
;                         for (int j = 0; j < 8; ++j) s += xn[j] * xn[j];
;                     }
;                     s += __shfl_xor(s, 16); s += __shfl_xor(s, 32);
;                     if (fq == 0) unsafeAtomicAdd(ssn + row, s);
;                 }
.LBB0_1420:
	s_or_b64 exec, exec, s[12:13]
	v_lshlrev_b32_e32 v140, 16, v132
	v_and_b32_e32 v141, 0xffff0000, v132
	v_lshlrev_b32_e32 v142, 16, v133
	v_and_b32_e32 v143, 0xffff0000, v133
	v_lshlrev_b32_e32 v186, 16, v134
	v_and_b32_e32 v197, 0xffff0000, v135
	v_pk_add_f32 v[132:133], v[52:53], v[192:193]
	s_waitcnt lgkmcnt(0)
	v_pk_add_f32 v[136:137], v[50:51], v[190:191]
	v_pk_add_f32 v[138:139], v[48:49], v[188:189]
	v_and_b32_e32 v187, 0xffff0000, v134
	v_lshlrev_b32_e32 v196, 16, v135
	v_pk_add_f32 v[134:135], v[54:55], v[194:195]
	v_fmac_f32_e32 v140, 0.5, v132
	v_fmac_f32_e32 v141, 0.5, v133
	v_cvt_pk_bf16_f32 v132, v140, v141
	v_fmac_f32_e32 v186, 0.5, v138
	v_fmac_f32_e32 v197, 0.5, v137
	v_and_b32_e32 v137, 0xffff0000, v132
	v_fmac_f32_e32 v142, 0.5, v134
	v_fmac_f32_e32 v187, 0.5, v139
	v_cvt_pk_bf16_f32 v134, v186, v187
	v_fmac_f32_e32 v196, 0.5, v136
	v_lshlrev_b32_e32 v136, 16, v132
	v_mul_f32_e32 v186, v137, v137
	v_fmac_f32_e32 v143, 0.5, v135
	v_cvt_pk_bf16_f32 v133, v142, v143
	v_fmac_f32_e32 v186, v136, v136
	v_lshlrev_b32_e32 v138, 16, v133
	v_and_b32_e32 v139, 0xffff0000, v133
	v_fmac_f32_e32 v186, v138, v138
	v_lshlrev_b32_e32 v140, 16, v134
	v_fmac_f32_e32 v186, v139, v139
	v_and_b32_e32 v141, 0xffff0000, v134
	v_fmac_f32_e32 v186, v140, v140
	v_cvt_pk_bf16_f32 v135, v196, v197
	v_fmac_f32_e32 v186, v141, v141
	v_lshlrev_b32_e32 v142, 16, v135
	v_and_b32_e32 v143, 0xffff0000, v135
	v_fmac_f32_e32 v186, v142, v142
	v_lshlrev_b32_e32 v136, 16, v128
	v_lshlrev_b32_e32 v187, 16, v130
	v_and_b32_e32 v188, 0xffff0000, v130
	v_lshlrev_b32_e32 v189, 16, v131
	v_and_b32_e32 v190, 0xffff0000, v131
	v_pk_add_f32 v[130:131], v[20:21], v[182:183]
	v_fmac_f32_e32 v186, v143, v143
	v_and_b32_e32 v137, 0xffff0000, v128
	v_lshlrev_b32_e32 v142, 16, v129
	v_and_b32_e32 v143, 0xffff0000, v129
	v_pk_add_f32 v[128:129], v[22:23], v[184:185]
	v_fmac_f32_e32 v136, 0.5, v130
	v_fmac_f32_e32 v137, 0.5, v131
	v_cvt_pk_bf16_f32 v136, v136, v137
	v_fmac_f32_e32 v142, 0.5, v128
	v_lshlrev_b32_e32 v128, 16, v136
	v_fmac_f32_e32 v143, 0.5, v129
	v_and_b32_e32 v129, 0xffff0000, v136
	v_fmac_f32_e32 v186, v128, v128
	v_cvt_pk_bf16_f32 v137, v142, v143
	v_fmac_f32_e32 v186, v129, v129
	v_lshlrev_b32_e32 v130, 16, v137
	v_pk_add_f32 v[140:141], v[18:19], v[180:181]
	v_pk_add_f32 v[138:139], v[16:17], v[178:179]
	v_and_b32_e32 v131, 0xffff0000, v137
	v_fmac_f32_e32 v186, v130, v130
	v_fmac_f32_e32 v187, 0.5, v138
	v_fmac_f32_e32 v188, 0.5, v139
	v_cvt_pk_bf16_f32 v138, v187, v188
	v_fmac_f32_e32 v189, 0.5, v140
	v_lshlrev_b32_e32 v140, 16, v138
	v_fmac_f32_e32 v186, v131, v131
	v_fmac_f32_e32 v190, 0.5, v141
	v_and_b32_e32 v141, 0xffff0000, v138
	v_fmac_f32_e32 v186, v140, v140
	v_cvt_pk_bf16_f32 v139, v189, v190
	v_fmac_f32_e32 v186, v141, v141
	v_lshlrev_b32_e32 v142, 16, v139
	v_and_b32_e32 v143, 0xffff0000, v139
	v_fmac_f32_e32 v186, v142, v142
	v_fmac_f32_e32 v186, v143, v143
	v_mov_b32_e32 v128, v186
	s_nop 1
	v_permlane16_swap_b32_e32 v128, v186
	v_lshl_add_u64 v[130:131], s[28:29], 0, v[176:177]
	v_lshl_add_u64 v[130:131], v[168:169], 1, v[130:131]
	global_store_dwordx4 v[130:131], v[132:135], off
	global_store_dwordx4 v[130:131], v[136:139], off offset:256
	s_waitcnt lgkmcnt(0)
	v_add_f32_e32 v128, v186, v128
	v_mov_b32_e32 v129, v128
	s_nop 1
	v_permlane32_swap_b32_e32 v129, v128
	s_and_saveexec_b64 s[12:13], s[8:9]
	s_cbranch_execz .LBB0_1422
	s_waitcnt lgkmcnt(0)
	v_add_f32_e32 v130, v128, v129
	v_lshl_add_u64 v[128:129], v[166:167], 2, s[14:15]
	global_atomic_add_f32 v[128:129], v130, off offset:576

; DI unsigned cvt_pk(float lo, float hi) { unsigned r; asm("v_cvt_pk_bf16_f32 %0, %1, %2" : "=v"(r) : "v"(lo), "v"(hi)); return r; }
;     __device__ __forceinline__ void operator()(const f32x4 (&acc)[2][2][4][2], const Unit& u, int wr, int wc, int fr, int fq) const {
;     ...
; #pragma unroll
;                 for (int mm = 0; mm < 2; ++mm) {
;                     const int m = mp * 2 + mm;
;                     const int row = row0 + ai * HALF + m * 16;
;                     float s = 0.f;
; #pragma unroll
;                     for (int bj = 0; bj < 2; ++bj) {
;                         u32x4* px = (u32x4*)(X + (size_t)row * DM + col0 + bj * HALF);
;                         float xo[8]; unpack8(xin[mm][bj], xo);
;                         const f32x4 a0 = acc[ai][bj][m][0] + pv[mm][bj][0], a1 = acc[ai][bj][m][1] + pv[mm][bj][1];
;                         u32x4 w;
;                         w.x = cvt_pk(xo[0] + scale * a0[0], xo[1] + scale * a0[1]); w.y = cvt_pk(xo[2] + scale * a0[2], xo[3] + scale * a0[3]);
;                         w.z = cvt_pk(xo[4] + scale * a1[0], xo[5] + scale * a1[1]); w.w = cvt_pk(xo[6] + scale * a1[2], xo[7] + scale * a1[3]);
;                         *px = w;
;                         float xn[8]; unpack8(w, xn);
; #pragma unroll
;                         for (int j = 0; j < 8; ++j) s += xn[j] * xn[j];
;                     }
;                     s += __shfl_xor(s, 16); s += __shfl_xor(s, 32);
;                     if (fq == 0) unsafeAtomicAdd(ssn + row, s);
;                 }
.LBB0_1424:
	s_or_b64 exec, exec, s[12:13]
	v_lshlrev_b32_e32 v208, 16, v140
	v_and_b32_e32 v209, 0xffff0000, v140
	v_lshlrev_b32_e32 v210, 16, v141
	v_and_b32_e32 v211, 0xffff0000, v141
	v_and_b32_e32 v245, 0xffff0000, v143
	v_pk_add_f32 v[140:141], v[44:45], v[204:205]
	v_pk_add_f32 v[170:171], v[42:43], v[202:203]
	v_lshlrev_b32_e32 v244, 16, v143
	v_fmac_f32_e32 v208, 0.5, v140
	v_fmac_f32_e32 v209, 0.5, v141
	v_cvt_pk_bf16_f32 v140, v208, v209
	v_fmac_f32_e32 v245, 0.5, v171
	v_and_b32_e32 v171, 0xffff0000, v140
	v_lshlrev_b32_e32 v214, 16, v142
	v_and_b32_e32 v215, 0xffff0000, v142
	v_pk_add_f32 v[142:143], v[46:47], v[206:207]
	v_pk_add_f32 v[200:201], v[40:41], v[200:201]
	v_fmac_f32_e32 v244, 0.5, v170
	v_lshlrev_b32_e32 v170, 16, v140
	v_mul_f32_e32 v206, v171, v171
	v_fmac_f32_e32 v210, 0.5, v142
	v_fmac_f32_e32 v211, 0.5, v143
	v_cvt_pk_bf16_f32 v141, v210, v211
	v_fmac_f32_e32 v214, 0.5, v200
	v_lshlrev_b32_e32 v200, 16, v141
	v_fmac_f32_e32 v206, v170, v170
	v_fmac_f32_e32 v215, 0.5, v201
	v_and_b32_e32 v201, 0xffff0000, v141
	v_fmac_f32_e32 v206, v200, v200
	v_cvt_pk_bf16_f32 v142, v214, v215
	v_fmac_f32_e32 v206, v201, v201
	v_lshlrev_b32_e32 v202, 16, v142
	v_and_b32_e32 v203, 0xffff0000, v142
	v_fmac_f32_e32 v206, v202, v202
	v_cvt_pk_bf16_f32 v143, v244, v245
	v_fmac_f32_e32 v206, v203, v203
	v_lshlrev_b32_e32 v204, 16, v143
	v_and_b32_e32 v205, 0xffff0000, v143
	v_fmac_f32_e32 v206, v204, v204
	v_fmac_f32_e32 v206, v205, v205
	v_lshlrev_b32_e32 v200, 16, v136
	v_and_b32_e32 v201, 0xffff0000, v136
	v_lshlrev_b32_e32 v202, 16, v137
	v_and_b32_e32 v203, 0xffff0000, v137
	v_lshlrev_b32_e32 v204, 16, v138
	v_and_b32_e32 v205, 0xffff0000, v138
	v_lshlrev_b32_e32 v207, 16, v139
	v_and_b32_e32 v208, 0xffff0000, v139
	v_pk_add_f32 v[136:137], v[14:15], v[198:199]
	v_pk_add_f32 v[138:139], v[12:13], v[196:197]
	v_pk_add_f32 v[170:171], v[10:11], v[194:195]
	v_pk_add_f32 v[194:195], v[8:9], v[192:193]
	v_fmac_f32_e32 v200, 0.5, v138
	v_fmac_f32_e32 v201, 0.5, v139
	v_cvt_pk_bf16_f32 v192, v200, v201
	v_fmac_f32_e32 v202, 0.5, v136
	v_lshlrev_b32_e32 v136, 16, v192
	v_fmac_f32_e32 v203, 0.5, v137
	v_and_b32_e32 v137, 0xffff0000, v192
	v_fmac_f32_e32 v206, v136, v136
	v_cvt_pk_bf16_f32 v193, v202, v203
	v_fmac_f32_e32 v206, v137, v137
	v_lshlrev_b32_e32 v138, 16, v193
	v_and_b32_e32 v139, 0xffff0000, v193
	v_fmac_f32_e32 v206, v138, v138
	v_fmac_f32_e32 v204, 0.5, v194
	v_fmac_f32_e32 v205, 0.5, v195
	v_cvt_pk_bf16_f32 v194, v204, v205
	v_fmac_f32_e32 v207, 0.5, v170
	v_lshlrev_b32_e32 v170, 16, v194
	v_fmac_f32_e32 v206, v139, v139
	v_fmac_f32_e32 v208, 0.5, v171
	v_and_b32_e32 v171, 0xffff0000, v194
	v_fmac_f32_e32 v206, v170, v170
	v_cvt_pk_bf16_f32 v195, v207, v208
	v_fmac_f32_e32 v206, v171, v171
	v_lshlrev_b32_e32 v196, 16, v195
	v_and_b32_e32 v197, 0xffff0000, v195
	v_fmac_f32_e32 v206, v196, v196
	v_fmac_f32_e32 v206, v197, v197
	v_mov_b32_e32 v136, v206
	s_nop 1
	v_permlane16_swap_b32_e32 v136, v206
	v_lshl_add_u64 v[138:139], s[28:29], 0, v[182:183]
	v_lshl_add_u64 v[138:139], v[168:169], 1, v[138:139]
	global_store_dwordx4 v[138:139], v[140:143], off
	global_store_dwordx4 v[138:139], v[192:195], off offset:256
	s_waitcnt lgkmcnt(0)
	v_add_f32_e32 v136, v206, v136
	v_mov_b32_e32 v137, v136
	s_nop 1
	v_permlane32_swap_b32_e32 v137, v136
	s_and_saveexec_b64 s[12:13], s[8:9]
	s_cbranch_execz .LBB0_1426
	s_waitcnt lgkmcnt(0)
	v_add_f32_e32 v138, v136, v137
	v_lshl_add_u64 v[136:137], v[166:167], 2, s[14:15]
	global_atomic_add_f32 v[136:137], v138, off offset:640
; DI unsigned cvt_pk(float lo, float hi) { unsigned r; asm("v_cvt_pk_bf16_f32 %0, %1, %2" : "=v"(r) : "v"(lo), "v"(hi)); return r; }
;     __device__ __forceinline__ void operator()(const f32x4 (&acc)[2][2][4][2], const Unit& u, int wr, int wc, int fr, int fq) const {
;     ...
; #pragma unroll
;                 for (int mm = 0; mm < 2; ++mm) {
;                     const int m = mp * 2 + mm;
;                     const int row = row0 + ai * HALF + m * 16;
;                     float s = 0.f;
; #pragma unroll
;                     for (int bj = 0; bj < 2; ++bj) {
;                         u32x4* px = (u32x4*)(X + (size_t)row * DM + col0 + bj * HALF);
;                         float xo[8]; unpack8(xin[mm][bj], xo);
;                         const f32x4 a0 = acc[ai][bj][m][0] + pv[mm][bj][0], a1 = acc[ai][bj][m][1] + pv[mm][bj][1];
;                         u32x4 w;
;                         w.x = cvt_pk(xo[0] + scale * a0[0], xo[1] + scale * a0[1]); w.y = cvt_pk(xo[2] + scale * a0[2], xo[3] + scale * a0[3]);
;                         w.z = cvt_pk(xo[4] + scale * a1[0], xo[5] + scale * a1[1]); w.w = cvt_pk(xo[6] + scale * a1[2], xo[7] + scale * a1[3]);
;                         *px = w;
;                         float xn[8]; unpack8(w, xn);
; #pragma unroll
;                         for (int j = 0; j < 8; ++j) s += xn[j] * xn[j];
;                     }
;                     s += __shfl_xor(s, 16); s += __shfl_xor(s, 32);
;                     if (fq == 0) unsafeAtomicAdd(ssn + row, s);
;                 }
.LBB0_1426:
	s_or_b64 exec, exec, s[12:13]
	v_lshlrev_b32_e32 v140, 16, v132
	v_and_b32_e32 v141, 0xffff0000, v132
	v_lshlrev_b32_e32 v142, 16, v133
	v_and_b32_e32 v143, 0xffff0000, v133
	v_lshlrev_b32_e32 v170, 16, v134
	v_and_b32_e32 v183, 0xffff0000, v135
	v_pk_add_f32 v[132:133], v[36:37], v[188:189]
	s_waitcnt lgkmcnt(0)
	v_pk_add_f32 v[136:137], v[34:35], v[186:187]
	v_pk_add_f32 v[138:139], v[32:33], v[184:185]
	v_and_b32_e32 v171, 0xffff0000, v134
	v_lshlrev_b32_e32 v182, 16, v135
	v_pk_add_f32 v[134:135], v[38:39], v[190:191]
	v_fmac_f32_e32 v140, 0.5, v132
	v_fmac_f32_e32 v141, 0.5, v133
	v_cvt_pk_bf16_f32 v132, v140, v141
	v_fmac_f32_e32 v170, 0.5, v138
	v_fmac_f32_e32 v183, 0.5, v137
	v_and_b32_e32 v137, 0xffff0000, v132
	v_fmac_f32_e32 v142, 0.5, v134
	v_fmac_f32_e32 v171, 0.5, v139
	v_cvt_pk_bf16_f32 v134, v170, v171
	v_fmac_f32_e32 v182, 0.5, v136
	v_lshlrev_b32_e32 v136, 16, v132
	v_mul_f32_e32 v170, v137, v137
	v_fmac_f32_e32 v143, 0.5, v135
	v_cvt_pk_bf16_f32 v133, v142, v143
	v_fmac_f32_e32 v170, v136, v136
	v_lshlrev_b32_e32 v138, 16, v133
	v_and_b32_e32 v139, 0xffff0000, v133
	v_fmac_f32_e32 v170, v138, v138
	v_lshlrev_b32_e32 v140, 16, v134
	v_fmac_f32_e32 v170, v139, v139
	v_and_b32_e32 v141, 0xffff0000, v134
	v_fmac_f32_e32 v170, v140, v140
	v_cvt_pk_bf16_f32 v135, v182, v183
	v_fmac_f32_e32 v170, v141, v141
	v_lshlrev_b32_e32 v142, 16, v135
	v_and_b32_e32 v143, 0xffff0000, v135
	v_fmac_f32_e32 v170, v142, v142
	v_lshlrev_b32_e32 v136, 16, v128
	v_lshlrev_b32_e32 v171, 16, v130
	v_and_b32_e32 v182, 0xffff0000, v130
	v_lshlrev_b32_e32 v183, 16, v131
	v_and_b32_e32 v184, 0xffff0000, v131
	v_pk_add_f32 v[130:131], v[4:5], v[178:179]
	v_fmac_f32_e32 v170, v143, v143
	v_and_b32_e32 v137, 0xffff0000, v128
	v_lshlrev_b32_e32 v142, 16, v129
	v_and_b32_e32 v143, 0xffff0000, v129
	v_pk_add_f32 v[128:129], v[6:7], v[180:181]
	v_fmac_f32_e32 v136, 0.5, v130
	v_fmac_f32_e32 v137, 0.5, v131
	v_cvt_pk_bf16_f32 v136, v136, v137
	v_fmac_f32_e32 v142, 0.5, v128
	v_lshlrev_b32_e32 v128, 16, v136
	v_fmac_f32_e32 v143, 0.5, v129
	v_and_b32_e32 v129, 0xffff0000, v136
	v_fmac_f32_e32 v170, v128, v128
	v_cvt_pk_bf16_f32 v137, v142, v143
	v_fmac_f32_e32 v170, v129, v129
	v_lshlrev_b32_e32 v130, 16, v137
	v_pk_add_f32 v[140:141], v[2:3], v[176:177]
	v_pk_add_f32 v[138:139], v[0:1], v[172:173]
	v_and_b32_e32 v131, 0xffff0000, v137
	v_fmac_f32_e32 v170, v130, v130
	v_fmac_f32_e32 v171, 0.5, v138
	v_fmac_f32_e32 v182, 0.5, v139
	v_cvt_pk_bf16_f32 v138, v171, v182
	v_fmac_f32_e32 v183, 0.5, v140
	v_lshlrev_b32_e32 v140, 16, v138
	v_fmac_f32_e32 v170, v131, v131
	v_fmac_f32_e32 v184, 0.5, v141
	v_and_b32_e32 v141, 0xffff0000, v138
	v_fmac_f32_e32 v170, v140, v140
	v_cvt_pk_bf16_f32 v139, v183, v184
	v_fmac_f32_e32 v170, v141, v141
	v_lshlrev_b32_e32 v142, 16, v139
	v_and_b32_e32 v143, 0xffff0000, v139
	v_fmac_f32_e32 v170, v142, v142
	v_fmac_f32_e32 v170, v143, v143
	v_mov_b32_e32 v128, v170
	s_nop 1
	v_permlane16_swap_b32_e32 v128, v170
	v_lshl_add_u64 v[130:131], s[28:29], 0, v[174:175]
	v_lshl_add_u64 v[130:131], v[168:169], 1, v[130:131]
	global_store_dwordx4 v[130:131], v[132:135], off
	global_store_dwordx4 v[130:131], v[136:139], off offset:256
	s_waitcnt lgkmcnt(0)
	v_add_f32_e32 v128, v170, v128
	v_mov_b32_e32 v129, v128
	s_nop 1
	v_permlane32_swap_b32_e32 v129, v128
	s_and_saveexec_b64 s[12:13], s[8:9]
	s_cbranch_execz .LBB0_1428
	s_waitcnt lgkmcnt(0)
	v_add_f32_e32 v130, v128, v129
	v_lshl_add_u64 v[128:129], v[166:167], 2, s[14:15]
	global_atomic_add_f32 v[128:129], v130, off offset:704

;     __device__ __forceinline__ void operator()(const f32x4 (&acc)[2][2][4][2], const Unit& u, int wr, int wc, int fr, int fq) const {
;     ...
;         const int row0 = u.pm * BM + wr * 64 + fr, col0 = u.pn * BM + wc * 32 + 8 * fq;
; #pragma unroll
;         for (int ai = 0; ai < 2; ++ai)
; #pragma unroll
;             for (int mp = 0; mp < 2; ++mp) {
;                 u32x4 xin[2][2];
; #pragma unroll
;                 for (int mm = 0; mm < 2; ++mm)
; #pragma unroll
;                     for (int bj = 0; bj < 2; ++bj) xin[mm][bj] = *(const u32x4*)(X + (size_t)(row0 + ai * HALF + (mp * 2 + mm) * 16) * DM + col0 + bj * HALF);
;                 f32x4 pv[2][2][2];
; #pragma unroll
;                 for (int mm = 0; mm < 2; ++mm)
; #pragma unroll
;                     for (int bj = 0; bj < 2; ++bj)
; #pragma unroll
;                         for (int n = 0; n < 2; ++n) pv[mm][bj][n] = (f32x4){0.f, 0.f, 0.f, 0.f};
;                 if (src) {
;                     u32x4 pc[2][2];
;     ...
;                     asm volatile("global_load_dwordx4 %0, %4, off sc1\n\tglobal_load_dwordx4 %1, %5, off sc1\n\tglobal_load_dwordx4 %2, %6, off sc1\n\tglobal_load_dwordx4 %3, %7, off sc1\n\ts_waitcnt vmcnt(0)"
;                                  : "=&v"(pc[0][0]), "=&v"(pc[0][1]), "=&v"(pc[1][0]), "=&v"(pc[1][1])
;                                  : "v"(src + CI(0, 0)), "v"(src + CI(0, 1)), "v"(src + CI(1, 0)), "v"(src + CI(1, 1))
;                                  : "memory");
;     ...
; #pragma unroll
;                     for (int mm = 0; mm < 2; ++mm)
; #pragma unroll
;                         for (int bj = 0; bj < 2; ++bj) { float f[8]; unpack8(pc[mm][bj], f); pv[mm][bj][0] = (f32x4){f[0], f[1], f[2], f[3]}; pv[mm][bj][1] = (f32x4){f[4], f[5], f[6], f[7]}; }
;                 }
; #pragma unroll
;                 for (int mm = 0; mm < 2; ++mm) {
;                     const int m = mp * 2 + mm;
;                     const int row = row0 + ai * HALF + m * 16;
;                     float s = 0.f;
; #pragma unroll
;                     for (int bj = 0; bj < 2; ++bj) {
;                         u32x4* px = (u32x4*)(X + (size_t)row * DM + col0 + bj * HALF);
;                         float xo[8]; unpack8(xin[mm][bj], xo);
;                         const f32x4 a0 = acc[ai][bj][m][0] + pv[mm][bj][0], a1 = acc[ai][bj][m][1] + pv[mm][bj][1];
;                         u32x4 w;
.LBB0_1457:
	v_lshl_or_b32 v140, s37, 8, v158
	v_lshl_add_u32 v138, s41, 8, v156
	v_ashrrev_i32_e32 v141, 31, v140
	v_lshlrev_b64 v[168:169], 1, v[140:141]
	v_ashrrev_i32_e32 v139, 31, v138
	v_lshl_add_u64 v[142:143], s[28:29], 0, v[168:169]
	v_lshlrev_b64 v[154:155], 11, v[138:139]
	v_lshl_add_u64 v[164:165], v[142:143], 0, v[154:155]
	global_load_dwordx4 v[160:163], v[164:165], off
	s_nop 0
	global_load_dwordx4 v[164:167], v[164:165], off offset:256
	v_pk_add_f32 v[180:181], v[112:113], 0 op_sel_hi:[1,0]
	v_and_b32_e32 v113, 64, v221
	v_or_b32_e32 v112, 16, v138
	v_pk_add_f32 v[170:171], v[122:123], 0 op_sel_hi:[1,0]
	v_pk_add_f32 v[178:179], v[114:115], 0 op_sel_hi:[1,0]
	v_xor_b32_e32 v114, 16, v221
	v_add_u32_e32 v123, 64, v113
	v_ashrrev_i32_e32 v113, 31, v112
	v_pk_add_f32 v[172:173], v[120:121], 0 op_sel_hi:[1,0]
	v_cmp_lt_i32_e32 vcc, v114, v123
	v_lshlrev_b64 v[120:121], 11, v[112:113]
	v_lshl_add_u64 v[112:113], v[142:143], 0, v[120:121]
	v_cndmask_b32_e32 v114, v221, v114, vcc
	v_pk_add_f32 v[174:175], v[118:119], 0 op_sel_hi:[1,0]
	v_pk_add_f32 v[176:177], v[116:117], 0 op_sel_hi:[1,0]
	v_lshlrev_b32_e32 v122, 2, v114
	global_load_dwordx4 v[116:119], v[112:113], off
	s_nop 0
	global_load_dwordx4 v[112:115], v[112:113], off offset:256
	v_pk_add_f32 v[124:125], v[124:125], 0 op_sel_hi:[1,0]
	v_pk_add_f32 v[126:127], v[126:127], 0 op_sel_hi:[1,0]
	s_waitcnt vmcnt(0)
	v_lshlrev_b32_e32 v182, 16, v160
	v_and_b32_e32 v160, 0xffff0000, v160
	v_fmac_f32_e32 v160, 0.5, v125
	v_lshlrev_b32_e32 v183, 16, v161
	v_and_b32_e32 v161, 0xffff0000, v161
	v_fmac_f32_e32 v182, 0.5, v124
	v_cvt_pk_bf16_f32 v160, v182, v160
	v_fmac_f32_e32 v161, 0.5, v127
	v_and_b32_e32 v125, 0xffff0000, v160
	v_lshlrev_b32_e32 v124, 16, v160
	v_mul_f32_e32 v125, v125, v125
	v_lshlrev_b32_e32 v184, 16, v162
	v_and_b32_e32 v162, 0xffff0000, v162
	v_fmac_f32_e32 v183, 0.5, v126
	v_cvt_pk_bf16_f32 v161, v183, v161
	v_fmac_f32_e32 v125, v124, v124
	v_lshlrev_b32_e32 v126, 16, v161
	v_lshlrev_b32_e32 v185, 16, v163
	v_fmac_f32_e32 v162, 0.5, v173
	v_and_b32_e32 v127, 0xffff0000, v161
	v_fmac_f32_e32 v125, v126, v126
	v_and_b32_e32 v163, 0xffff0000, v163
	v_fmac_f32_e32 v184, 0.5, v172
	v_fmac_f32_e32 v185, 0.5, v170
	v_cvt_pk_bf16_f32 v162, v184, v162
	v_fmac_f32_e32 v125, v127, v127
	v_lshlrev_b32_e32 v170, 16, v162
	v_fmac_f32_e32 v163, 0.5, v171
	v_and_b32_e32 v171, 0xffff0000, v162
	v_fmac_f32_e32 v125, v170, v170
	v_lshlrev_b32_e32 v186, 16, v164
	v_and_b32_e32 v164, 0xffff0000, v164
	v_cvt_pk_bf16_f32 v163, v185, v163
	v_fmac_f32_e32 v125, v171, v171
	v_lshlrev_b32_e32 v172, 16, v163
	v_lshlrev_b32_e32 v187, 16, v165
	v_fmac_f32_e32 v164, 0.5, v177
	v_and_b32_e32 v173, 0xffff0000, v163
	v_fmac_f32_e32 v125, v172, v172
	v_and_b32_e32 v165, 0xffff0000, v165
	v_fmac_f32_e32 v186, 0.5, v176
	v_fmac_f32_e32 v187, 0.5, v174
	v_cvt_pk_bf16_f32 v164, v186, v164
	v_fmac_f32_e32 v125, v173, v173
	v_lshlrev_b32_e32 v174, 16, v164
	v_fmac_f32_e32 v165, 0.5, v175
	v_and_b32_e32 v175, 0xffff0000, v164
	v_fmac_f32_e32 v125, v174, v174
	v_lshlrev_b32_e32 v188, 16, v166
	v_and_b32_e32 v166, 0xffff0000, v166
	v_cvt_pk_bf16_f32 v165, v187, v165
	v_fmac_f32_e32 v125, v175, v175
	v_lshlrev_b32_e32 v176, 16, v165
	v_lshlrev_b32_e32 v189, 16, v167
	v_fmac_f32_e32 v166, 0.5, v181
	v_and_b32_e32 v177, 0xffff0000, v165
	v_fmac_f32_e32 v125, v176, v176
	v_and_b32_e32 v167, 0xffff0000, v167
	v_fmac_f32_e32 v188, 0.5, v180
	v_fmac_f32_e32 v189, 0.5, v178
	v_cvt_pk_bf16_f32 v166, v188, v166
	v_fmac_f32_e32 v125, v177, v177
	v_lshlrev_b32_e32 v178, 16, v166
	v_fmac_f32_e32 v167, 0.5, v179
	v_and_b32_e32 v179, 0xffff0000, v166
	v_fmac_f32_e32 v125, v178, v178
	v_cvt_pk_bf16_f32 v167, v189, v167
	v_fmac_f32_e32 v125, v179, v179
	v_lshlrev_b32_e32 v180, 16, v167
	v_and_b32_e32 v181, 0xffff0000, v167
	v_fmac_f32_e32 v125, v180, v180
	v_fmac_f32_e32 v125, v181, v181
	v_mov_b32_e32 v124, v125
	s_nop 1
	v_permlane16_swap_b32_e32 v124, v125
	v_xor_b32_e32 v126, 32, v221
	v_cmp_lt_i32_e32 vcc, v126, v123
	s_waitcnt lgkmcnt(0)
	v_add_f32_e32 v124, v125, v124
	v_cndmask_b32_e32 v123, v221, v126, vcc
	v_lshlrev_b32_e32 v123, 2, v123
	v_mov_b32_e32 v125, v124
	s_nop 1
	v_permlane32_swap_b32_e32 v125, v124
	v_lshl_add_u64 v[126:127], s[28:29], 0, v[154:155]
	v_lshl_add_u64 v[126:127], v[126:127], 0, v[168:169]
	global_store_dwordx4 v[126:127], v[160:163], off
	global_store_dwordx4 v[126:127], v[164:167], off offset:256
	s_and_saveexec_b64 s[16:17], s[4:5]
	s_cbranch_execz .LBB0_1459
	s_waitcnt lgkmcnt(0)
	v_add_f32_e32 v126, v124, v125
	v_lshl_add_u64 v[124:125], v[138:139], 2, s[14:15]
	global_atomic_add_f32 v[124:125], v126, off
;     __device__ __forceinline__ void operator()(const f32x4 (&acc)[2][2][4][2], const Unit& u, int wr, int wc, int fr, int fq) const {
;     ...
;                 u32x4 xin[2][2];
; #pragma unroll
;                 for (int mm = 0; mm < 2; ++mm)
; #pragma unroll
;                     for (int bj = 0; bj < 2; ++bj) xin[mm][bj] = *(const u32x4*)(X + (size_t)(row0 + ai * HALF + (mp * 2 + mm) * 16) * DM + col0 + bj * HALF);
;                 f32x4 pv[2][2][2];
; #pragma unroll
;                 for (int mm = 0; mm < 2; ++mm)
; #pragma unroll
;                     for (int bj = 0; bj < 2; ++bj)
; #pragma unroll
;                         for (int n = 0; n < 2; ++n) pv[mm][bj][n] = (f32x4){0.f, 0.f, 0.f, 0.f};
;                 if (src) {
;                     u32x4 pc[2][2];
;     ...
;                     asm volatile("global_load_dwordx4 %0, %4, off sc1\n\tglobal_load_dwordx4 %1, %5, off sc1\n\tglobal_load_dwordx4 %2, %6, off sc1\n\tglobal_load_dwordx4 %3, %7, off sc1\n\ts_waitcnt vmcnt(0)"
;                                  : "=&v"(pc[0][0]), "=&v"(pc[0][1]), "=&v"(pc[1][0]), "=&v"(pc[1][1])
;                                  : "v"(src + CI(0, 0)), "v"(src + CI(0, 1)), "v"(src + CI(1, 0)), "v"(src + CI(1, 1))
;                                  : "memory");
;     ...
; #pragma unroll
;                     for (int mm = 0; mm < 2; ++mm)
; #pragma unroll
;                         for (int bj = 0; bj < 2; ++bj) { float f[8]; unpack8(pc[mm][bj], f); pv[mm][bj][0] = (f32x4){f[0], f[1], f[2], f[3]}; pv[mm][bj][1] = (f32x4){f[4], f[5], f[6], f[7]}; }
;                 }
; #pragma unroll
;                 for (int mm = 0; mm < 2; ++mm) {
;                     const int m = mp * 2 + mm;
;                     const int row = row0 + ai * HALF + m * 16;
;                     float s = 0.f;
; #pragma unroll
;                     for (int bj = 0; bj < 2; ++bj) {
;                         u32x4* px = (u32x4*)(X + (size_t)row * DM + col0 + bj * HALF);
;                         float xo[8]; unpack8(xin[mm][bj], xo);
;                         const f32x4 a0 = acc[ai][bj][m][0] + pv[mm][bj][0], a1 = acc[ai][bj][m][1] + pv[mm][bj][1];
;                         u32x4 w;
;                         w.x = cvt_pk(xo[0] + scale * a0[0], xo[1] + scale * a0[1]); w.y = cvt_pk(xo[2] + scale * a0[2], xo[3] + scale * a0[3]);
.LBB0_1459:
	s_or_b64 exec, exec, s[16:17]
	v_lshlrev_b32_e32 v124, 16, v116
	s_waitcnt lgkmcnt(0)
	v_and_b32_e32 v125, 0xffff0000, v116
	v_pk_add_f32 v[108:109], v[108:109], 0 op_sel_hi:[1,0]
	v_lshlrev_b32_e32 v126, 16, v117
	v_and_b32_e32 v127, 0xffff0000, v117
	v_pk_add_f32 v[116:117], v[106:107], 0 op_sel_hi:[1,0]
	v_pk_add_f32 v[106:107], v[104:105], 0 op_sel_hi:[1,0]
	v_fmac_f32_e32 v124, 0.5, v108
	v_fmac_f32_e32 v125, 0.5, v109
	v_cvt_pk_bf16_f32 v104, v124, v125
	v_pk_add_f32 v[110:111], v[110:111], 0 op_sel_hi:[1,0]
	v_and_b32_e32 v109, 0xffff0000, v104
	v_lshlrev_b32_e32 v108, 16, v104
	v_mul_f32_e32 v124, v109, v109
	v_fmac_f32_e32 v126, 0.5, v110
	v_fmac_f32_e32 v127, 0.5, v111
	v_cvt_pk_bf16_f32 v105, v126, v127
	v_fmac_f32_e32 v124, v108, v108
	v_lshlrev_b32_e32 v110, 16, v105
	v_lshlrev_b32_e32 v160, 16, v118
	v_and_b32_e32 v118, 0xffff0000, v118
	v_lshlrev_b32_e32 v161, 16, v119
	v_and_b32_e32 v111, 0xffff0000, v105
	v_fmac_f32_e32 v124, v110, v110
	v_and_b32_e32 v119, 0xffff0000, v119
	v_fmac_f32_e32 v160, 0.5, v106
	v_fmac_f32_e32 v118, 0.5, v107
	v_cvt_pk_bf16_f32 v106, v160, v118
	v_fmac_f32_e32 v161, 0.5, v116
	v_lshlrev_b32_e32 v116, 16, v106
	v_fmac_f32_e32 v124, v111, v111
	v_fmac_f32_e32 v119, 0.5, v117
	v_and_b32_e32 v117, 0xffff0000, v106
	v_fmac_f32_e32 v124, v116, v116
	v_cvt_pk_bf16_f32 v107, v161, v119
	v_fmac_f32_e32 v124, v117, v117
	v_lshlrev_b32_e32 v118, 16, v107
	v_and_b32_e32 v119, 0xffff0000, v107
	v_fmac_f32_e32 v124, v118, v118
	v_lshlrev_b32_e32 v110, 16, v112
	v_and_b32_e32 v111, 0xffff0000, v112
	v_lshlrev_b32_e32 v116, 16, v114
	v_pk_add_f32 v[100:101], v[100:101], 0 op_sel_hi:[1,0]
	v_pk_add_f32 v[96:97], v[96:97], 0 op_sel_hi:[1,0]
	v_fmac_f32_e32 v124, v119, v119
	v_and_b32_e32 v114, 0xffff0000, v114
	v_pk_add_f32 v[108:109], v[98:99], 0 op_sel_hi:[1,0]
	v_fmac_f32_e32 v110, 0.5, v100
	v_fmac_f32_e32 v111, 0.5, v101
	v_cvt_pk_bf16_f32 v98, v110, v111
	v_fmac_f32_e32 v116, 0.5, v96
	v_lshlrev_b32_e32 v96, 16, v98
	v_lshlrev_b32_e32 v112, 16, v113
	v_and_b32_e32 v113, 0xffff0000, v113
	v_pk_add_f32 v[102:103], v[102:103], 0 op_sel_hi:[1,0]
	v_fmac_f32_e32 v114, 0.5, v97
	v_and_b32_e32 v97, 0xffff0000, v98
	v_fmac_f32_e32 v124, v96, v96
	v_fmac_f32_e32 v112, 0.5, v102
	v_fmac_f32_e32 v113, 0.5, v103
	v_cvt_pk_bf16_f32 v99, v112, v113
	v_fmac_f32_e32 v124, v97, v97
	v_lshlrev_b32_e32 v102, 16, v99
	v_lshlrev_b32_e32 v117, 16, v115
	v_and_b32_e32 v103, 0xffff0000, v99
	v_fmac_f32_e32 v124, v102, v102
	v_and_b32_e32 v115, 0xffff0000, v115
	v_cvt_pk_bf16_f32 v100, v116, v114
	v_fmac_f32_e32 v117, 0.5, v108
	v_lshlrev_b32_e32 v108, 16, v100
	v_fmac_f32_e32 v124, v103, v103
	v_fmac_f32_e32 v115, 0.5, v109
	v_and_b32_e32 v109, 0xffff0000, v100
	v_fmac_f32_e32 v124, v108, v108
	v_cvt_pk_bf16_f32 v101, v117, v115
	v_fmac_f32_e32 v124, v109, v109
	v_lshlrev_b32_e32 v110, 16, v101
	v_and_b32_e32 v111, 0xffff0000, v101
	v_fmac_f32_e32 v124, v110, v110
	v_fmac_f32_e32 v124, v111, v111
	v_mov_b32_e32 v96, v124
	s_nop 1
	v_permlane16_swap_b32_e32 v96, v124
	v_lshl_add_u64 v[102:103], s[28:29], 0, v[120:121]
	v_lshl_add_u64 v[102:103], v[140:141], 1, v[102:103]
	global_store_dwordx4 v[102:103], v[104:107], off
	global_store_dwordx4 v[102:103], v[98:101], off offset:256
	s_waitcnt lgkmcnt(0)
	v_add_f32_e32 v96, v124, v96
	v_mov_b32_e32 v97, v96
	s_nop 1
	v_permlane32_swap_b32_e32 v97, v96
	s_and_saveexec_b64 s[16:17], s[4:5]
	s_cbranch_execz .LBB0_1461
	s_waitcnt lgkmcnt(0)
	v_add_f32_e32 v98, v96, v97
	v_lshl_add_u64 v[96:97], v[138:139], 2, s[14:15]
	global_atomic_add_f32 v[96:97], v98, off offset:64
.LBB0_1461:
	s_or_b64 exec, exec, s[16:17]
	v_or_b32_e32 v96, 32, v138
	s_waitcnt lgkmcnt(0)
	v_ashrrev_i32_e32 v97, 31, v96
	v_lshlrev_b64 v[106:107], 11, v[96:97]
	v_lshl_add_u64 v[96:97], v[142:143], 0, v[106:107]
	global_load_dwordx4 v[108:111], v[96:97], off
	global_load_dwordx4 v[112:115], v[96:97], off offset:256
	v_or_b32_e32 v96, 48, v138
	v_ashrrev_i32_e32 v97, 31, v96
	v_lshlrev_b64 v[104:105], 11, v[96:97]
	v_lshl_add_u64 v[96:97], v[142:143], 0, v[104:105]
	global_load_dwordx4 v[100:103], v[96:97], off
	s_nop 0
	global_load_dwordx4 v[96:99], v[96:97], off offset:256
	v_lshl_add_u64 v[106:107], s[28:29], 0, v[106:107]
	v_pk_add_f32 v[92:93], v[92:93], 0 op_sel_hi:[1,0]
	v_lshl_add_u64 v[106:107], v[140:141], 1, v[106:107]
	v_pk_add_f32 v[94:95], v[94:95], 0 op_sel_hi:[1,0]
	v_pk_add_f32 v[84:85], v[84:85], 0 op_sel_hi:[1,0]
	v_pk_add_f32 v[86:87], v[86:87], 0 op_sel_hi:[1,0]
	s_waitcnt vmcnt(3)
	v_lshlrev_b32_e32 v116, 16, v108
	v_and_b32_e32 v117, 0xffff0000, v108
	v_lshlrev_b32_e32 v118, 16, v109
	v_and_b32_e32 v119, 0xffff0000, v109
	v_lshlrev_b32_e32 v120, 16, v110
	v_and_b32_e32 v110, 0xffff0000, v110
	v_lshlrev_b32_e32 v121, 16, v111
	v_and_b32_e32 v111, 0xffff0000, v111
	v_pk_add_f32 v[108:109], v[90:91], 0 op_sel_hi:[1,0]
	v_pk_add_f32 v[90:91], v[88:89], 0 op_sel_hi:[1,0]
	v_fmac_f32_e32 v116, 0.5, v92
	v_fmac_f32_e32 v117, 0.5, v93
	v_cvt_pk_bf16_f32 v88, v116, v117
	v_fmac_f32_e32 v118, 0.5, v94
	v_fmac_f32_e32 v119, 0.5, v95
	v_cvt_pk_bf16_f32 v89, v118, v119
	v_fmac_f32_e32 v120, 0.5, v90
	v_fmac_f32_e32 v110, 0.5, v91
	v_cvt_pk_bf16_f32 v90, v120, v110
	v_fmac_f32_e32 v121, 0.5, v108
	v_fmac_f32_e32 v111, 0.5, v109
	v_cvt_pk_bf16_f32 v91, v121, v111
	global_store_dwordx4 v[106:107], v[88:91], off
	v_lshlrev_b32_e32 v92, 16, v88
	v_lshlrev_b32_e32 v93, 16, v89
	v_and_b32_e32 v88, 0xffff0000, v88
	v_mul_f32_e32 v108, v88, v88
	v_fmac_f32_e32 v108, v92, v92
	v_and_b32_e32 v89, 0xffff0000, v89
	v_fmac_f32_e32 v108, v93, v93
	v_lshlrev_b32_e32 v94, 16, v90
	v_fmac_f32_e32 v108, v89, v89
	v_and_b32_e32 v90, 0xffff0000, v90
	v_fmac_f32_e32 v108, v94, v94
	v_lshlrev_b32_e32 v95, 16, v91
	v_fmac_f32_e32 v108, v90, v90
	v_and_b32_e32 v91, 0xffff0000, v91
	v_fmac_f32_e32 v108, v95, v95
	v_fmac_f32_e32 v108, v91, v91
	s_waitcnt vmcnt(3)
; DI unsigned cvt_pk(float lo, float hi) { unsigned r; asm("v_cvt_pk_bf16_f32 %0, %1, %2" : "=v"(r) : "v"(lo), "v"(hi)); return r; }
;     __device__ __forceinline__ void operator()(const f32x4 (&acc)[2][2][4][2], const Unit& u, int wr, int wc, int fr, int fq) const {
;     ...
; #pragma unroll
;                 for (int mm = 0; mm < 2; ++mm) {
;                     const int m = mp * 2 + mm;
;                     const int row = row0 + ai * HALF + m * 16;
;                     float s = 0.f;
; #pragma unroll
;                     for (int bj = 0; bj < 2; ++bj) {
;                         u32x4* px = (u32x4*)(X + (size_t)row * DM + col0 + bj * HALF);
;                         float xo[8]; unpack8(xin[mm][bj], xo);
;                         const f32x4 a0 = acc[ai][bj][m][0] + pv[mm][bj][0], a1 = acc[ai][bj][m][1] + pv[mm][bj][1];
;                         u32x4 w;
;                         w.x = cvt_pk(xo[0] + scale * a0[0], xo[1] + scale * a0[1]); w.y = cvt_pk(xo[2] + scale * a0[2], xo[3] + scale * a0[3]);
;                         w.z = cvt_pk(xo[4] + scale * a1[0], xo[5] + scale * a1[1]); w.w = cvt_pk(xo[6] + scale * a1[2], xo[7] + scale * a1[3]);
;                         *px = w;
;                         float xn[8]; unpack8(w, xn);
; #pragma unroll
;                         for (int j = 0; j < 8; ++j) s += xn[j] * xn[j];
;                     }
;                     s += __shfl_xor(s, 16); s += __shfl_xor(s, 32);
;                     if (fq == 0) unsafeAtomicAdd(ssn + row, s);
;                 }
	v_lshlrev_b32_e32 v90, 16, v112
	v_and_b32_e32 v91, 0xffff0000, v112
	v_lshlrev_b32_e32 v92, 16, v113
	v_and_b32_e32 v93, 0xffff0000, v113
	v_lshlrev_b32_e32 v94, 16, v114
	v_and_b32_e32 v95, 0xffff0000, v114
	v_lshlrev_b32_e32 v109, 16, v115
	v_and_b32_e32 v110, 0xffff0000, v115
	v_pk_add_f32 v[88:89], v[82:83], 0 op_sel_hi:[1,0]
	v_pk_add_f32 v[82:83], v[80:81], 0 op_sel_hi:[1,0]
	v_fmac_f32_e32 v90, 0.5, v84
	v_fmac_f32_e32 v91, 0.5, v85
	v_cvt_pk_bf16_f32 v80, v90, v91
	v_fmac_f32_e32 v92, 0.5, v86
	v_lshlrev_b32_e32 v84, 16, v80
	v_fmac_f32_e32 v93, 0.5, v87
	v_cvt_pk_bf16_f32 v81, v92, v93
	v_fmac_f32_e32 v94, 0.5, v82
	v_fmac_f32_e32 v95, 0.5, v83
	v_cvt_pk_bf16_f32 v82, v94, v95
	v_fmac_f32_e32 v109, 0.5, v88
	v_fmac_f32_e32 v110, 0.5, v89
	v_cvt_pk_bf16_f32 v83, v109, v110
	global_store_dwordx4 v[106:107], v[80:83], off offset:256
	v_fmac_f32_e32 v108, v84, v84
	v_lshlrev_b32_e32 v85, 16, v81
	v_and_b32_e32 v80, 0xffff0000, v80
	v_fmac_f32_e32 v108, v80, v80
	v_and_b32_e32 v81, 0xffff0000, v81
	v_fmac_f32_e32 v108, v85, v85
	v_lshlrev_b32_e32 v86, 16, v82
	v_fmac_f32_e32 v108, v81, v81
	v_and_b32_e32 v82, 0xffff0000, v82
	v_fmac_f32_e32 v108, v86, v86
	v_lshlrev_b32_e32 v87, 16, v83
	v_fmac_f32_e32 v108, v82, v82
	v_and_b32_e32 v83, 0xffff0000, v83
	v_fmac_f32_e32 v108, v87, v87
	v_fmac_f32_e32 v108, v83, v83
	v_mov_b32_e32 v80, v108
	s_nop 1
	v_permlane16_swap_b32_e32 v80, v108
	s_waitcnt lgkmcnt(0)
	v_add_f32_e32 v80, v108, v80
	v_mov_b32_e32 v81, v80
	s_nop 1
	v_permlane32_swap_b32_e32 v81, v80
	s_and_saveexec_b64 s[16:17], s[4:5]
	s_cbranch_execz .LBB0_1463
	s_waitcnt lgkmcnt(0)
	v_add_f32_e32 v82, v80, v81
	v_lshl_add_u64 v[80:81], v[138:139], 2, s[14:15]
	global_atomic_add_f32 v[80:81], v82, off offset:128
.LBB0_1463:
	s_or_b64 exec, exec, s[16:17]
	s_waitcnt vmcnt(3)
	v_lshlrev_b32_e32 v82, 16, v100
	v_and_b32_e32 v83, 0xffff0000, v100
	v_lshlrev_b32_e32 v84, 16, v101
	v_pk_add_f32 v[78:79], v[78:79], 0 op_sel_hi:[1,0]
	v_pk_add_f32 v[76:77], v[76:77], 0 op_sel_hi:[1,0]
	v_and_b32_e32 v85, 0xffff0000, v101
	s_waitcnt lgkmcnt(0)
	v_pk_add_f32 v[80:81], v[74:75], 0 op_sel_hi:[1,0]
	v_pk_add_f32 v[74:75], v[72:73], 0 op_sel_hi:[1,0]
	v_fmac_f32_e32 v82, 0.5, v76
	v_fmac_f32_e32 v83, 0.5, v77
	v_cvt_pk_bf16_f32 v72, v82, v83
	v_fmac_f32_e32 v84, 0.5, v78
	v_and_b32_e32 v77, 0xffff0000, v72
	v_fmac_f32_e32 v85, 0.5, v79
	v_cvt_pk_bf16_f32 v73, v84, v85
	v_lshlrev_b32_e32 v76, 16, v72
	v_mul_f32_e32 v84, v77, v77
	v_lshlrev_b32_e32 v78, 16, v73
	v_fmac_f32_e32 v84, v76, v76
	v_lshlrev_b32_e32 v86, 16, v102
	v_and_b32_e32 v87, 0xffff0000, v102
	v_lshlrev_b32_e32 v88, 16, v103
	v_and_b32_e32 v79, 0xffff0000, v73
	v_fmac_f32_e32 v84, v78, v78
	v_and_b32_e32 v89, 0xffff0000, v103
	v_fmac_f32_e32 v86, 0.5, v74
	v_fmac_f32_e32 v87, 0.5, v75
	v_cvt_pk_bf16_f32 v74, v86, v87
	v_fmac_f32_e32 v88, 0.5, v80
	v_lshlrev_b32_e32 v80, 16, v74
	v_fmac_f32_e32 v84, v79, v79
	v_fmac_f32_e32 v89, 0.5, v81
	v_and_b32_e32 v81, 0xffff0000, v74
	v_fmac_f32_e32 v84, v80, v80
	v_cvt_pk_bf16_f32 v75, v88, v89
	v_fmac_f32_e32 v84, v81, v81
	v_lshlrev_b32_e32 v82, 16, v75
	v_and_b32_e32 v83, 0xffff0000, v75
	v_fmac_f32_e32 v84, v82, v82
	s_waitcnt vmcnt(2)
	v_lshlrev_b32_e32 v78, 16, v96
	v_and_b32_e32 v79, 0xffff0000, v96
	v_lshlrev_b32_e32 v82, 16, v98
	v_pk_add_f32 v[68:69], v[68:69], 0 op_sel_hi:[1,0]
	v_pk_add_f32 v[64:65], v[64:65], 0 op_sel_hi:[1,0]
	v_fmac_f32_e32 v84, v83, v83
	v_and_b32_e32 v83, 0xffff0000, v98
	v_pk_add_f32 v[76:77], v[66:67], 0 op_sel_hi:[1,0]
	v_fmac_f32_e32 v78, 0.5, v68
	v_fmac_f32_e32 v79, 0.5, v69
	v_cvt_pk_bf16_f32 v66, v78, v79
	v_fmac_f32_e32 v82, 0.5, v64
	v_lshlrev_b32_e32 v64, 16, v66
	v_lshlrev_b32_e32 v80, 16, v97
	v_and_b32_e32 v81, 0xffff0000, v97
	v_pk_add_f32 v[70:71], v[70:71], 0 op_sel_hi:[1,0]
	v_fmac_f32_e32 v83, 0.5, v65
	v_and_b32_e32 v65, 0xffff0000, v66
	v_fmac_f32_e32 v84, v64, v64
	v_fmac_f32_e32 v80, 0.5, v70
	v_fmac_f32_e32 v81, 0.5, v71
	v_cvt_pk_bf16_f32 v67, v80, v81
	v_fmac_f32_e32 v84, v65, v65
	v_lshlrev_b32_e32 v70, 16, v67
	v_lshlrev_b32_e32 v85, 16, v99
	v_and_b32_e32 v71, 0xffff0000, v67
	v_fmac_f32_e32 v84, v70, v70
	v_and_b32_e32 v86, 0xffff0000, v99
	v_cvt_pk_bf16_f32 v68, v82, v83
	v_fmac_f32_e32 v85, 0.5, v76
	v_lshlrev_b32_e32 v76, 16, v68
	v_fmac_f32_e32 v84, v71, v71
	v_fmac_f32_e32 v86, 0.5, v77
	v_and_b32_e32 v77, 0xffff0000, v68
	v_fmac_f32_e32 v84, v76, v76
	v_cvt_pk_bf16_f32 v69, v85, v86
	v_fmac_f32_e32 v84, v77, v77
	v_lshlrev_b32_e32 v78, 16, v69
	v_and_b32_e32 v79, 0xffff0000, v69
	v_fmac_f32_e32 v84, v78, v78
	v_fmac_f32_e32 v84, v79, v79
	v_mov_b32_e32 v64, v84
	s_nop 1
	v_permlane16_swap_b32_e32 v64, v84
	v_lshl_add_u64 v[70:71], s[28:29], 0, v[104:105]
	v_lshl_add_u64 v[70:71], v[140:141], 1, v[70:71]
	global_store_dwordx4 v[70:71], v[72:75], off
	global_store_dwordx4 v[70:71], v[66:69], off offset:256
	s_waitcnt lgkmcnt(0)
	v_add_f32_e32 v64, v84, v64
	v_mov_b32_e32 v65, v64
	s_nop 1
	v_permlane32_swap_b32_e32 v65, v64
	s_and_saveexec_b64 s[16:17], s[4:5]
	s_cbranch_execz .LBB0_1465
	s_waitcnt lgkmcnt(0)
	v_add_f32_e32 v66, v64, v65
	v_lshl_add_u64 v[64:65], v[138:139], 2, s[14:15]
	global_atomic_add_f32 v[64:65], v66, off offset:192
;     __device__ __forceinline__ void operator()(const f32x4 (&acc)[2][2][4][2], const Unit& u, int wr, int wc, int fr, int fq) const {
;     ...
;                 u32x4 xin[2][2];
; #pragma unroll
;                 for (int mm = 0; mm < 2; ++mm)
; #pragma unroll
;                     for (int bj = 0; bj < 2; ++bj) xin[mm][bj] = *(const u32x4*)(X + (size_t)(row0 + ai * HALF + (mp * 2 + mm) * 16) * DM + col0 + bj * HALF);
;                 f32x4 pv[2][2][2];
; #pragma unroll
;                 for (int mm = 0; mm < 2; ++mm)
; #pragma unroll
;                     for (int bj = 0; bj < 2; ++bj)
; #pragma unroll
;                         for (int n = 0; n < 2; ++n) pv[mm][bj][n] = (f32x4){0.f, 0.f, 0.f, 0.f};
;                 if (src) {
;                     u32x4 pc[2][2];
;     ...
;                     asm volatile("global_load_dwordx4 %0, %4, off sc1\n\tglobal_load_dwordx4 %1, %5, off sc1\n\tglobal_load_dwordx4 %2, %6, off sc1\n\tglobal_load_dwordx4 %3, %7, off sc1\n\ts_waitcnt vmcnt(0)"
;                                  : "=&v"(pc[0][0]), "=&v"(pc[0][1]), "=&v"(pc[1][0]), "=&v"(pc[1][1])
;                                  : "v"(src + CI(0, 0)), "v"(src + CI(0, 1)), "v"(src + CI(1, 0)), "v"(src + CI(1, 1))
;                                  : "memory");
;     ...
; #pragma unroll
;                     for (int mm = 0; mm < 2; ++mm)
; #pragma unroll
;                         for (int bj = 0; bj < 2; ++bj) { float f[8]; unpack8(pc[mm][bj], f); pv[mm][bj][0] = (f32x4){f[0], f[1], f[2], f[3]}; pv[mm][bj][1] = (f32x4){f[4], f[5], f[6], f[7]}; }
;                 }
; #pragma unroll
;                 for (int mm = 0; mm < 2; ++mm) {
;                     const int m = mp * 2 + mm;
;                     const int row = row0 + ai * HALF + m * 16;
;                     float s = 0.f;
; #pragma unroll
;                     for (int bj = 0; bj < 2; ++bj) {
;                         u32x4* px = (u32x4*)(X + (size_t)row * DM + col0 + bj * HALF);
;                         float xo[8]; unpack8(xin[mm][bj], xo);
;                         const f32x4 a0 = acc[ai][bj][m][0] + pv[mm][bj][0], a1 = acc[ai][bj][m][1] + pv[mm][bj][1];
;                         u32x4 w;
;                         w.x = cvt_pk(xo[0] + scale * a0[0], xo[1] + scale * a0[1]); w.y = cvt_pk(xo[2] + scale * a0[2], xo[3] + scale * a0[3]);
.LBB0_1465:
	s_or_b64 exec, exec, s[16:17]
	s_mov_b64 s[16:17], 0x40000
	v_lshl_add_u64 v[74:75], v[154:155], 0, s[16:17]
	s_waitcnt lgkmcnt(0)
	v_lshl_add_u64 v[64:65], v[142:143], 0, v[74:75]
	global_load_dwordx4 v[76:79], v[64:65], off
	global_load_dwordx4 v[80:83], v[64:65], off offset:256
	s_mov_b64 s[16:17], 0x48000
	v_lshl_add_u64 v[72:73], v[154:155], 0, s[16:17]
	v_lshl_add_u64 v[64:65], v[142:143], 0, v[72:73]
	global_load_dwordx4 v[68:71], v[64:65], off
	s_nop 0
	global_load_dwordx4 v[64:67], v[64:65], off offset:256
	v_lshl_add_u64 v[74:75], s[28:29], 0, v[74:75]
	v_pk_add_f32 v[60:61], v[60:61], 0 op_sel_hi:[1,0]
	v_lshl_add_u64 v[74:75], v[140:141], 1, v[74:75]
	v_pk_add_f32 v[62:63], v[62:63], 0 op_sel_hi:[1,0]
	v_pk_add_f32 v[52:53], v[52:53], 0 op_sel_hi:[1,0]
	v_pk_add_f32 v[54:55], v[54:55], 0 op_sel_hi:[1,0]
	s_waitcnt vmcnt(3)
	v_lshlrev_b32_e32 v84, 16, v76
	v_and_b32_e32 v85, 0xffff0000, v76
	v_lshlrev_b32_e32 v86, 16, v77
	v_and_b32_e32 v87, 0xffff0000, v77
	v_lshlrev_b32_e32 v88, 16, v78
	v_and_b32_e32 v78, 0xffff0000, v78
	v_lshlrev_b32_e32 v89, 16, v79
	v_and_b32_e32 v79, 0xffff0000, v79
	v_pk_add_f32 v[76:77], v[58:59], 0 op_sel_hi:[1,0]
	v_pk_add_f32 v[58:59], v[56:57], 0 op_sel_hi:[1,0]
	v_fmac_f32_e32 v84, 0.5, v60
	v_fmac_f32_e32 v85, 0.5, v61
	v_cvt_pk_bf16_f32 v56, v84, v85
	v_fmac_f32_e32 v86, 0.5, v62
	v_fmac_f32_e32 v87, 0.5, v63
	v_cvt_pk_bf16_f32 v57, v86, v87
	v_fmac_f32_e32 v88, 0.5, v58
	v_fmac_f32_e32 v78, 0.5, v59
	v_cvt_pk_bf16_f32 v58, v88, v78
	v_fmac_f32_e32 v89, 0.5, v76
	v_fmac_f32_e32 v79, 0.5, v77
	v_cvt_pk_bf16_f32 v59, v89, v79
	global_store_dwordx4 v[74:75], v[56:59], off
	v_lshlrev_b32_e32 v60, 16, v56
	v_lshlrev_b32_e32 v61, 16, v57
	v_and_b32_e32 v56, 0xffff0000, v56
	v_mul_f32_e32 v76, v56, v56
	v_fmac_f32_e32 v76, v60, v60
	v_and_b32_e32 v57, 0xffff0000, v57
	v_fmac_f32_e32 v76, v61, v61
	v_lshlrev_b32_e32 v62, 16, v58
	v_fmac_f32_e32 v76, v57, v57
	v_and_b32_e32 v58, 0xffff0000, v58
	v_fmac_f32_e32 v76, v62, v62
	v_lshlrev_b32_e32 v63, 16, v59
	v_fmac_f32_e32 v76, v58, v58
	v_and_b32_e32 v59, 0xffff0000, v59
	v_fmac_f32_e32 v76, v63, v63
	v_fmac_f32_e32 v76, v59, v59
	s_waitcnt vmcnt(3)
	v_lshlrev_b32_e32 v58, 16, v80
	v_and_b32_e32 v59, 0xffff0000, v80
	v_lshlrev_b32_e32 v60, 16, v81
	v_and_b32_e32 v61, 0xffff0000, v81
	v_lshlrev_b32_e32 v62, 16, v82
	v_and_b32_e32 v63, 0xffff0000, v82
	v_lshlrev_b32_e32 v77, 16, v83
	v_and_b32_e32 v78, 0xffff0000, v83
	v_pk_add_f32 v[56:57], v[50:51], 0 op_sel_hi:[1,0]
	v_pk_add_f32 v[50:51], v[48:49], 0 op_sel_hi:[1,0]
	v_fmac_f32_e32 v58, 0.5, v52
	v_fmac_f32_e32 v59, 0.5, v53
	v_cvt_pk_bf16_f32 v48, v58, v59
	v_fmac_f32_e32 v60, 0.5, v54
	v_lshlrev_b32_e32 v52, 16, v48
	v_fmac_f32_e32 v61, 0.5, v55
	v_cvt_pk_bf16_f32 v49, v60, v61
	v_fmac_f32_e32 v62, 0.5, v50
	v_fmac_f32_e32 v63, 0.5, v51
	v_cvt_pk_bf16_f32 v50, v62, v63
	v_fmac_f32_e32 v77, 0.5, v56
	v_fmac_f32_e32 v78, 0.5, v57
	v_cvt_pk_bf16_f32 v51, v77, v78
	global_store_dwordx4 v[74:75], v[48:51], off offset:256
	v_fmac_f32_e32 v76, v52, v52
	v_lshlrev_b32_e32 v53, 16, v49
	v_and_b32_e32 v48, 0xffff0000, v48
	v_fmac_f32_e32 v76, v48, v48
	v_and_b32_e32 v49, 0xffff0000, v49
	v_fmac_f32_e32 v76, v53, v53
	v_lshlrev_b32_e32 v54, 16, v50
	v_fmac_f32_e32 v76, v49, v49
	v_and_b32_e32 v50, 0xffff0000, v50
	v_fmac_f32_e32 v76, v54, v54
	v_lshlrev_b32_e32 v55, 16, v51
	v_fmac_f32_e32 v76, v50, v50
	v_and_b32_e32 v51, 0xffff0000, v51
	v_fmac_f32_e32 v76, v55, v55
	v_fmac_f32_e32 v76, v51, v51
	v_mov_b32_e32 v48, v76
	s_nop 1
	v_permlane16_swap_b32_e32 v48, v76
	s_waitcnt lgkmcnt(0)
	v_add_f32_e32 v48, v76, v48
	v_mov_b32_e32 v49, v48
	s_nop 1
	v_permlane32_swap_b32_e32 v49, v48
	s_and_saveexec_b64 s[16:17], s[4:5]
	s_cbranch_execz .LBB0_1467
	s_waitcnt lgkmcnt(0)
	v_add_f32_e32 v50, v48, v49
	v_lshl_add_u64 v[48:49], v[138:139], 2, s[14:15]
	global_atomic_add_f32 v[48:49], v50, off offset:512
.LBB0_1467:
	s_or_b64 exec, exec, s[16:17]
	s_waitcnt vmcnt(3)
	v_lshlrev_b32_e32 v50, 16, v68
	v_and_b32_e32 v51, 0xffff0000, v68
	v_lshlrev_b32_e32 v52, 16, v69
	v_pk_add_f32 v[46:47], v[46:47], 0 op_sel_hi:[1,0]
	v_pk_add_f32 v[44:45], v[44:45], 0 op_sel_hi:[1,0]
	v_and_b32_e32 v53, 0xffff0000, v69
	s_waitcnt lgkmcnt(0)
	v_pk_add_f32 v[48:49], v[42:43], 0 op_sel_hi:[1,0]
	v_pk_add_f32 v[42:43], v[40:41], 0 op_sel_hi:[1,0]
	v_fmac_f32_e32 v50, 0.5, v44
	v_fmac_f32_e32 v51, 0.5, v45
	v_cvt_pk_bf16_f32 v40, v50, v51
	v_fmac_f32_e32 v52, 0.5, v46
	v_and_b32_e32 v45, 0xffff0000, v40
	v_fmac_f32_e32 v53, 0.5, v47
	v_cvt_pk_bf16_f32 v41, v52, v53
	v_lshlrev_b32_e32 v44, 16, v40
	v_mul_f32_e32 v52, v45, v45
	v_lshlrev_b32_e32 v46, 16, v41
	v_fmac_f32_e32 v52, v44, v44
	v_lshlrev_b32_e32 v54, 16, v70
	v_and_b32_e32 v55, 0xffff0000, v70
	v_lshlrev_b32_e32 v56, 16, v71
	v_and_b32_e32 v47, 0xffff0000, v41
	v_fmac_f32_e32 v52, v46, v46
	v_and_b32_e32 v57, 0xffff0000, v71
	v_fmac_f32_e32 v54, 0.5, v42
	v_fmac_f32_e32 v55, 0.5, v43
	v_cvt_pk_bf16_f32 v42, v54, v55
	v_fmac_f32_e32 v56, 0.5, v48
	v_lshlrev_b32_e32 v48, 16, v42
	v_fmac_f32_e32 v52, v47, v47
	v_fmac_f32_e32 v57, 0.5, v49
	v_and_b32_e32 v49, 0xffff0000, v42
	v_fmac_f32_e32 v52, v48, v48
	v_cvt_pk_bf16_f32 v43, v56, v57
	v_fmac_f32_e32 v52, v49, v49
	v_lshlrev_b32_e32 v50, 16, v43
	v_and_b32_e32 v51, 0xffff0000, v43
	v_fmac_f32_e32 v52, v50, v50
	s_waitcnt vmcnt(2)
;     __device__ __forceinline__ void operator()(const f32x4 (&acc)[2][2][4][2], const Unit& u, int wr, int wc, int fr, int fq) const {
;     ...
;                 u32x4 xin[2][2];
; #pragma unroll
;                 for (int mm = 0; mm < 2; ++mm)
; #pragma unroll
;                     for (int bj = 0; bj < 2; ++bj) xin[mm][bj] = *(const u32x4*)(X + (size_t)(row0 + ai * HALF + (mp * 2 + mm) * 16) * DM + col0 + bj * HALF);
;                 f32x4 pv[2][2][2];
; #pragma unroll
;                 for (int mm = 0; mm < 2; ++mm)
; #pragma unroll
;                     for (int bj = 0; bj < 2; ++bj)
; #pragma unroll
;                         for (int n = 0; n < 2; ++n) pv[mm][bj][n] = (f32x4){0.f, 0.f, 0.f, 0.f};
;                 if (src) {
;                     u32x4 pc[2][2];
;     ...
;                     asm volatile("global_load_dwordx4 %0, %4, off sc1\n\tglobal_load_dwordx4 %1, %5, off sc1\n\tglobal_load_dwordx4 %2, %6, off sc1\n\tglobal_load_dwordx4 %3, %7, off sc1\n\ts_waitcnt vmcnt(0)"
;                                  : "=&v"(pc[0][0]), "=&v"(pc[0][1]), "=&v"(pc[1][0]), "=&v"(pc[1][1])
;                                  : "v"(src + CI(0, 0)), "v"(src + CI(0, 1)), "v"(src + CI(1, 0)), "v"(src + CI(1, 1))
;                                  : "memory");
;     ...
; #pragma unroll
;                     for (int mm = 0; mm < 2; ++mm)
; #pragma unroll
;                         for (int bj = 0; bj < 2; ++bj) { float f[8]; unpack8(pc[mm][bj], f); pv[mm][bj][0] = (f32x4){f[0], f[1], f[2], f[3]}; pv[mm][bj][1] = (f32x4){f[4], f[5], f[6], f[7]}; }
;                 }
; #pragma unroll
;                 for (int mm = 0; mm < 2; ++mm) {
;                     const int m = mp * 2 + mm;
;                     const int row = row0 + ai * HALF + m * 16;
;                     float s = 0.f;
; #pragma unroll
;                     for (int bj = 0; bj < 2; ++bj) {
;                         u32x4* px = (u32x4*)(X + (size_t)row * DM + col0 + bj * HALF);
;                         float xo[8]; unpack8(xin[mm][bj], xo);
;                         const f32x4 a0 = acc[ai][bj][m][0] + pv[mm][bj][0], a1 = acc[ai][bj][m][1] + pv[mm][bj][1];
;                         u32x4 w;
;                         w.x = cvt_pk(xo[0] + scale * a0[0], xo[1] + scale * a0[1]); w.y = cvt_pk(xo[2] + scale * a0[2], xo[3] + scale * a0[3]);
	v_lshlrev_b32_e32 v46, 16, v64
	v_and_b32_e32 v47, 0xffff0000, v64
	v_lshlrev_b32_e32 v50, 16, v66
	v_pk_add_f32 v[36:37], v[36:37], 0 op_sel_hi:[1,0]
	v_pk_add_f32 v[32:33], v[32:33], 0 op_sel_hi:[1,0]
	v_fmac_f32_e32 v52, v51, v51
	v_and_b32_e32 v51, 0xffff0000, v66
	v_pk_add_f32 v[44:45], v[34:35], 0 op_sel_hi:[1,0]
	v_fmac_f32_e32 v46, 0.5, v36
	v_fmac_f32_e32 v47, 0.5, v37
	v_cvt_pk_bf16_f32 v34, v46, v47
	v_fmac_f32_e32 v50, 0.5, v32
	v_lshlrev_b32_e32 v32, 16, v34
	v_lshlrev_b32_e32 v48, 16, v65
	v_and_b32_e32 v49, 0xffff0000, v65
	v_pk_add_f32 v[38:39], v[38:39], 0 op_sel_hi:[1,0]
	v_fmac_f32_e32 v51, 0.5, v33
	v_and_b32_e32 v33, 0xffff0000, v34
	v_fmac_f32_e32 v52, v32, v32
	v_fmac_f32_e32 v48, 0.5, v38
	v_fmac_f32_e32 v49, 0.5, v39
	v_cvt_pk_bf16_f32 v35, v48, v49
	v_fmac_f32_e32 v52, v33, v33
	v_lshlrev_b32_e32 v38, 16, v35
	v_lshlrev_b32_e32 v53, 16, v67
	v_and_b32_e32 v39, 0xffff0000, v35
	v_fmac_f32_e32 v52, v38, v38
	v_and_b32_e32 v54, 0xffff0000, v67
	v_cvt_pk_bf16_f32 v36, v50, v51
	v_fmac_f32_e32 v53, 0.5, v44
	v_lshlrev_b32_e32 v44, 16, v36
	v_fmac_f32_e32 v52, v39, v39
	v_fmac_f32_e32 v54, 0.5, v45
	v_and_b32_e32 v45, 0xffff0000, v36
	v_fmac_f32_e32 v52, v44, v44
	v_cvt_pk_bf16_f32 v37, v53, v54
	v_fmac_f32_e32 v52, v45, v45
	v_lshlrev_b32_e32 v46, 16, v37
	v_and_b32_e32 v47, 0xffff0000, v37
	v_fmac_f32_e32 v52, v46, v46
	v_fmac_f32_e32 v52, v47, v47
	v_mov_b32_e32 v32, v52
	s_nop 1
	v_permlane16_swap_b32_e32 v32, v52
	v_lshl_add_u64 v[38:39], s[28:29], 0, v[72:73]
	v_lshl_add_u64 v[38:39], v[140:141], 1, v[38:39]
	global_store_dwordx4 v[38:39], v[40:43], off
	global_store_dwordx4 v[38:39], v[34:37], off offset:256
	s_waitcnt lgkmcnt(0)
	v_add_f32_e32 v32, v52, v32
	v_mov_b32_e32 v33, v32
	s_nop 1
	v_permlane32_swap_b32_e32 v33, v32
	s_and_saveexec_b64 s[16:17], s[4:5]
	s_cbranch_execz .LBB0_1469
	s_waitcnt lgkmcnt(0)
	v_add_f32_e32 v34, v32, v33
	v_lshl_add_u64 v[32:33], v[138:139], 2, s[14:15]
	global_atomic_add_f32 v[32:33], v34, off offset:576
.LBB0_1469:
	s_or_b64 exec, exec, s[16:17]
	s_mov_b64 s[16:17], 0x50000
	v_lshl_add_u64 v[42:43], v[154:155], 0, s[16:17]
	s_waitcnt lgkmcnt(0)
	v_lshl_add_u64 v[32:33], v[142:143], 0, v[42:43]
	global_load_dwordx4 v[44:47], v[32:33], off
	global_load_dwordx4 v[48:51], v[32:33], off offset:256
	s_mov_b64 s[16:17], 0x58000
	v_lshl_add_u64 v[40:41], v[154:155], 0, s[16:17]
	v_lshl_add_u64 v[32:33], v[142:143], 0, v[40:41]
	global_load_dwordx4 v[36:39], v[32:33], off
	s_nop 0
	global_load_dwordx4 v[32:35], v[32:33], off offset:256
	v_lshl_add_u64 v[42:43], s[28:29], 0, v[42:43]
	v_pk_add_f32 v[28:29], v[28:29], 0 op_sel_hi:[1,0]
	v_lshl_add_u64 v[42:43], v[140:141], 1, v[42:43]
	v_pk_add_f32 v[30:31], v[30:31], 0 op_sel_hi:[1,0]
	v_pk_add_f32 v[20:21], v[20:21], 0 op_sel_hi:[1,0]
	v_pk_add_f32 v[22:23], v[22:23], 0 op_sel_hi:[1,0]
	s_waitcnt vmcnt(3)
	v_lshlrev_b32_e32 v52, 16, v44
	v_and_b32_e32 v53, 0xffff0000, v44
	v_lshlrev_b32_e32 v54, 16, v45
	v_and_b32_e32 v55, 0xffff0000, v45
	v_lshlrev_b32_e32 v56, 16, v46
	v_and_b32_e32 v46, 0xffff0000, v46
	v_lshlrev_b32_e32 v57, 16, v47
	v_and_b32_e32 v47, 0xffff0000, v47
	v_pk_add_f32 v[44:45], v[26:27], 0 op_sel_hi:[1,0]
	v_pk_add_f32 v[26:27], v[24:25], 0 op_sel_hi:[1,0]
	v_fmac_f32_e32 v52, 0.5, v28
	v_fmac_f32_e32 v53, 0.5, v29
	v_cvt_pk_bf16_f32 v24, v52, v53
	v_fmac_f32_e32 v54, 0.5, v30
	v_fmac_f32_e32 v55, 0.5, v31
	v_cvt_pk_bf16_f32 v25, v54, v55
	v_fmac_f32_e32 v56, 0.5, v26
	v_fmac_f32_e32 v46, 0.5, v27
	v_cvt_pk_bf16_f32 v26, v56, v46
	v_fmac_f32_e32 v57, 0.5, v44
	v_fmac_f32_e32 v47, 0.5, v45
	v_cvt_pk_bf16_f32 v27, v57, v47
	global_store_dwordx4 v[42:43], v[24:27], off
	v_lshlrev_b32_e32 v28, 16, v24
	v_lshlrev_b32_e32 v29, 16, v25
	v_and_b32_e32 v24, 0xffff0000, v24
	v_mul_f32_e32 v44, v24, v24
	v_fmac_f32_e32 v44, v28, v28
	v_and_b32_e32 v25, 0xffff0000, v25
	v_fmac_f32_e32 v44, v29, v29
	v_lshlrev_b32_e32 v30, 16, v26
	v_fmac_f32_e32 v44, v25, v25
	v_and_b32_e32 v26, 0xffff0000, v26
	v_fmac_f32_e32 v44, v30, v30
	v_lshlrev_b32_e32 v31, 16, v27
	v_fmac_f32_e32 v44, v26, v26
	v_and_b32_e32 v27, 0xffff0000, v27
	v_fmac_f32_e32 v44, v31, v31
	v_fmac_f32_e32 v44, v27, v27
	s_waitcnt vmcnt(3)
	v_lshlrev_b32_e32 v26, 16, v48
	v_and_b32_e32 v27, 0xffff0000, v48
	v_lshlrev_b32_e32 v28, 16, v49
	v_and_b32_e32 v29, 0xffff0000, v49
	v_lshlrev_b32_e32 v30, 16, v50
	v_and_b32_e32 v31, 0xffff0000, v50
	v_lshlrev_b32_e32 v45, 16, v51
	v_and_b32_e32 v46, 0xffff0000, v51
	v_pk_add_f32 v[24:25], v[18:19], 0 op_sel_hi:[1,0]
	v_pk_add_f32 v[18:19], v[16:17], 0 op_sel_hi:[1,0]
	v_fmac_f32_e32 v26, 0.5, v20
	v_fmac_f32_e32 v27, 0.5, v21
	v_cvt_pk_bf16_f32 v16, v26, v27
	v_fmac_f32_e32 v28, 0.5, v22
	v_lshlrev_b32_e32 v20, 16, v16
	v_fmac_f32_e32 v29, 0.5, v23
	v_cvt_pk_bf16_f32 v17, v28, v29
	v_fmac_f32_e32 v30, 0.5, v18
	v_fmac_f32_e32 v31, 0.5, v19
	v_cvt_pk_bf16_f32 v18, v30, v31
	v_fmac_f32_e32 v45, 0.5, v24
	v_fmac_f32_e32 v46, 0.5, v25
	v_cvt_pk_bf16_f32 v19, v45, v46
	global_store_dwordx4 v[42:43], v[16:19], off offset:256
	v_fmac_f32_e32 v44, v20, v20
	v_lshlrev_b32_e32 v21, 16, v17
	v_and_b32_e32 v16, 0xffff0000, v16
	v_fmac_f32_e32 v44, v16, v16
	v_and_b32_e32 v17, 0xffff0000, v17
	v_fmac_f32_e32 v44, v21, v21
	v_lshlrev_b32_e32 v22, 16, v18
	v_fmac_f32_e32 v44, v17, v17
	v_and_b32_e32 v18, 0xffff0000, v18
	v_fmac_f32_e32 v44, v22, v22
	v_lshlrev_b32_e32 v23, 16, v19
	v_fmac_f32_e32 v44, v18, v18
	v_and_b32_e32 v19, 0xffff0000, v19
	v_fmac_f32_e32 v44, v23, v23
	v_fmac_f32_e32 v44, v19, v19
	v_mov_b32_e32 v16, v44
	s_nop 1
	v_permlane16_swap_b32_e32 v16, v44
	s_waitcnt lgkmcnt(0)
	v_add_f32_e32 v16, v44, v16
	v_mov_b32_e32 v17, v16
	s_nop 1
	v_permlane32_swap_b32_e32 v17, v16
	s_and_saveexec_b64 s[16:17], s[4:5]
	s_cbranch_execz .LBB0_1471
	s_waitcnt lgkmcnt(0)
	v_add_f32_e32 v18, v16, v17
	v_lshl_add_u64 v[16:17], v[138:139], 2, s[14:15]
	global_atomic_add_f32 v[16:17], v18, off offset:640
; DI unsigned cvt_pk(float lo, float hi) { unsigned r; asm("v_cvt_pk_bf16_f32 %0, %1, %2" : "=v"(r) : "v"(lo), "v"(hi)); return r; }
;     __device__ __forceinline__ void operator()(const f32x4 (&acc)[2][2][4][2], const Unit& u, int wr, int wc, int fr, int fq) const {
;     ...
; #pragma unroll
;                 for (int mm = 0; mm < 2; ++mm) {
;                     const int m = mp * 2 + mm;
;                     const int row = row0 + ai * HALF + m * 16;
;                     float s = 0.f;
; #pragma unroll
;                     for (int bj = 0; bj < 2; ++bj) {
;                         u32x4* px = (u32x4*)(X + (size_t)row * DM + col0 + bj * HALF);
;                         float xo[8]; unpack8(xin[mm][bj], xo);
;                         const f32x4 a0 = acc[ai][bj][m][0] + pv[mm][bj][0], a1 = acc[ai][bj][m][1] + pv[mm][bj][1];
;                         u32x4 w;
;                         w.x = cvt_pk(xo[0] + scale * a0[0], xo[1] + scale * a0[1]); w.y = cvt_pk(xo[2] + scale * a0[2], xo[3] + scale * a0[3]);
;                         w.z = cvt_pk(xo[4] + scale * a1[0], xo[5] + scale * a1[1]); w.w = cvt_pk(xo[6] + scale * a1[2], xo[7] + scale * a1[3]);
;                         *px = w;
;                         float xn[8]; unpack8(w, xn);
; #pragma unroll
;                         for (int j = 0; j < 8; ++j) s += xn[j] * xn[j];
;                     }
;                     s += __shfl_xor(s, 16); s += __shfl_xor(s, 32);
;                     if (fq == 0) unsafeAtomicAdd(ssn + row, s);
;                 }
.LBB0_1471:
	s_or_b64 exec, exec, s[16:17]
	s_waitcnt vmcnt(3)
	v_lshlrev_b32_e32 v18, 16, v36
	v_and_b32_e32 v19, 0xffff0000, v36
	v_lshlrev_b32_e32 v20, 16, v37
	v_pk_add_f32 v[14:15], v[14:15], 0 op_sel_hi:[1,0]
	v_pk_add_f32 v[12:13], v[12:13], 0 op_sel_hi:[1,0]
	v_and_b32_e32 v21, 0xffff0000, v37
	s_waitcnt lgkmcnt(0)
	v_pk_add_f32 v[16:17], v[10:11], 0 op_sel_hi:[1,0]
	v_pk_add_f32 v[10:11], v[8:9], 0 op_sel_hi:[1,0]
	v_fmac_f32_e32 v18, 0.5, v12
	v_fmac_f32_e32 v19, 0.5, v13
	v_cvt_pk_bf16_f32 v8, v18, v19
	v_fmac_f32_e32 v20, 0.5, v14
	v_and_b32_e32 v13, 0xffff0000, v8
	v_fmac_f32_e32 v21, 0.5, v15
	v_cvt_pk_bf16_f32 v9, v20, v21
	v_lshlrev_b32_e32 v12, 16, v8
	v_mul_f32_e32 v20, v13, v13
	v_lshlrev_b32_e32 v14, 16, v9
	v_fmac_f32_e32 v20, v12, v12
	v_lshlrev_b32_e32 v22, 16, v38
	v_and_b32_e32 v23, 0xffff0000, v38
	v_lshlrev_b32_e32 v24, 16, v39
	v_and_b32_e32 v15, 0xffff0000, v9
	v_fmac_f32_e32 v20, v14, v14
	v_and_b32_e32 v25, 0xffff0000, v39
	v_fmac_f32_e32 v22, 0.5, v10
	v_fmac_f32_e32 v23, 0.5, v11
	v_cvt_pk_bf16_f32 v10, v22, v23
	v_fmac_f32_e32 v24, 0.5, v16
	v_lshlrev_b32_e32 v16, 16, v10
	v_fmac_f32_e32 v20, v15, v15
	v_fmac_f32_e32 v25, 0.5, v17
	v_and_b32_e32 v17, 0xffff0000, v10
	v_fmac_f32_e32 v20, v16, v16
	v_cvt_pk_bf16_f32 v11, v24, v25
	v_fmac_f32_e32 v20, v17, v17
	v_lshlrev_b32_e32 v18, 16, v11
	v_and_b32_e32 v19, 0xffff0000, v11
	v_fmac_f32_e32 v20, v18, v18
	s_waitcnt vmcnt(2)
	v_lshlrev_b32_e32 v14, 16, v32
	v_and_b32_e32 v15, 0xffff0000, v32
	v_lshlrev_b32_e32 v18, 16, v34
	v_pk_add_f32 v[4:5], v[4:5], 0 op_sel_hi:[1,0]
	v_pk_add_f32 v[0:1], v[0:1], 0 op_sel_hi:[1,0]
	v_fmac_f32_e32 v20, v19, v19
	v_and_b32_e32 v19, 0xffff0000, v34
	v_pk_add_f32 v[12:13], v[2:3], 0 op_sel_hi:[1,0]
	v_fmac_f32_e32 v14, 0.5, v4
	v_fmac_f32_e32 v15, 0.5, v5
	v_cvt_pk_bf16_f32 v2, v14, v15
	v_fmac_f32_e32 v18, 0.5, v0
	v_lshlrev_b32_e32 v0, 16, v2
	v_lshlrev_b32_e32 v16, 16, v33
	v_and_b32_e32 v17, 0xffff0000, v33
	v_pk_add_f32 v[6:7], v[6:7], 0 op_sel_hi:[1,0]
	v_fmac_f32_e32 v19, 0.5, v1
	v_and_b32_e32 v1, 0xffff0000, v2
	v_fmac_f32_e32 v20, v0, v0
	v_fmac_f32_e32 v16, 0.5, v6
	v_fmac_f32_e32 v17, 0.5, v7
	v_cvt_pk_bf16_f32 v3, v16, v17
	v_fmac_f32_e32 v20, v1, v1
	v_lshlrev_b32_e32 v6, 16, v3
	v_lshlrev_b32_e32 v21, 16, v35
	v_and_b32_e32 v7, 0xffff0000, v3
	v_fmac_f32_e32 v20, v6, v6
	v_and_b32_e32 v22, 0xffff0000, v35
	v_cvt_pk_bf16_f32 v4, v18, v19
	v_fmac_f32_e32 v21, 0.5, v12
	v_lshlrev_b32_e32 v12, 16, v4
	v_fmac_f32_e32 v20, v7, v7
	v_fmac_f32_e32 v22, 0.5, v13
	v_and_b32_e32 v13, 0xffff0000, v4
	v_fmac_f32_e32 v20, v12, v12
	v_cvt_pk_bf16_f32 v5, v21, v22
	v_fmac_f32_e32 v20, v13, v13
	v_lshlrev_b32_e32 v14, 16, v5
	v_and_b32_e32 v15, 0xffff0000, v5
	v_fmac_f32_e32 v20, v14, v14
	v_fmac_f32_e32 v20, v15, v15
	v_mov_b32_e32 v0, v20
	s_nop 1
	v_permlane16_swap_b32_e32 v0, v20
	v_lshl_add_u64 v[6:7], s[28:29], 0, v[40:41]
	v_lshl_add_u64 v[6:7], v[140:141], 1, v[6:7]
	global_store_dwordx4 v[6:7], v[8:11], off
	global_store_dwordx4 v[6:7], v[2:5], off offset:256
	s_waitcnt lgkmcnt(0)
	v_add_f32_e32 v0, v20, v0
	v_mov_b32_e32 v1, v0
	s_nop 1
	v_permlane32_swap_b32_e32 v1, v0
	s_and_saveexec_b64 s[16:17], s[4:5]
	s_cbranch_execz .LBB0_1473
	s_waitcnt lgkmcnt(0)
	v_add_f32_e32 v2, v0, v1
	v_lshl_add_u64 v[0:1], v[138:139], 2, s[14:15]
	global_atomic_add_f32 v[0:1], v2, off offset:704
